# grid barrier instances 1-13 replaced by lean hand-written version: constant generation, last leader releases all XCD generation words directly, early L1 invalidate
# speedup vs baseline: 1.0088x; 1.0088x over previous
.LBB0_233:
	s_cmp_gt_i32 s59, 2
	s_cselect_b64 s[6:7], -1, 0
	s_and_b64 s[0:1], s[0:1], s[6:7]
	s_andn2_b64 vcc, exec, s[0:1]
	s_cbranch_vccnz .LBB0_287
	s_waitcnt vmcnt(0) lgkmcnt(0)
	s_barrier
	s_mov_b64 s[0:1], exec
	v_readlane_b32 s2, v249, 5
	v_readlane_b32 s3, v249, 6
	v_readlane_b32 s8, v249, 4
	s_and_b64 s[2:3], s[0:1], s[2:3]
	s_mov_b64 exec, s[2:3]
	s_cbranch_execz .Lgb_1_done
	v_mov_b32_e32 v1, 0x27e00
	ds_read2_b32 v[2:3], v1 offset1:1
	s_lshl_b32 s8, s8, 8
	s_add_u32 s4, s56, s8
	s_addc_u32 s5, s57, 0
	v_mov_b32_e32 v4, 0x1000
	v_mov_b32_e32 v5, 1
	global_atomic_add v6, v4, v5, s[4:5] offset:1024 sc0
	buffer_inv sc1
	s_waitcnt lgkmcnt(0)
	v_mul_lo_u32 v7, v2, 2
	s_waitcnt vmcnt(1)
	v_add_u32_e32 v6, 1, v6
	v_cmp_eq_u32_e32 vcc, v6, v7
	s_cbranch_vccz .Lgb_1_wait
	buffer_wbl2 sc1
	s_waitcnt vmcnt(0)
	v_mov_b32_e32 v4, 0x3000
	global_atomic_add v8, v4, v5, s[56:57] offset:1024 sc0
	v_mul_lo_u32 v7, v3, 2
	s_waitcnt vmcnt(0)
	v_add_u32_e32 v8, 1, v8
	v_cmp_eq_u32_e32 vcc, v8, v7
	s_cbranch_vccz .Lgb_1_wait
	v_mov_b32_e32 v9, 0x2400
	global_atomic_add v9, v5, s[56:57] offset:0
	global_atomic_add v9, v5, s[56:57] offset:256
	global_atomic_add v9, v5, s[56:57] offset:512
	global_atomic_add v9, v5, s[56:57] offset:768
	global_atomic_add v9, v5, s[56:57] offset:1024
	global_atomic_add v9, v5, s[56:57] offset:1280
	global_atomic_add v9, v5, s[56:57] offset:1536
	global_atomic_add v9, v5, s[56:57] offset:1792
	global_atomic_add v9, v5, s[56:57] offset:2048
	global_atomic_add v9, v5, s[56:57] offset:2304
	global_atomic_add v9, v5, s[56:57] offset:2560
	global_atomic_add v9, v5, s[56:57] offset:2816
	global_atomic_add v9, v5, s[56:57] offset:3072
	global_atomic_add v9, v5, s[56:57] offset:3328
	global_atomic_add v9, v5, s[56:57] offset:3584
	global_atomic_add v9, v5, s[56:57] offset:3840
	s_waitcnt vmcnt(0)
	s_branch .Lgb_1_done
.Lgb_1_wait:
	s_mov_b32 s8, 0
	v_mov_b32_e32 v9, 0x2000
.Lgb_1_spin:
	global_load_dword v8, v9, s[4:5] offset:1024 sc1
	s_waitcnt vmcnt(0)
	v_cmp_ne_u32_e32 vcc, 1, v8
	s_cbranch_vccnz .Lgb_1_done
	s_sleep 1
	s_add_u32 s8, s8, 1
	s_cmp_lt_u32 s8, 0x40000
	s_cbranch_scc1 .Lgb_1_spin
.Lgb_1_done:
	s_mov_b64 exec, s[0:1]
	s_waitcnt vmcnt(0) lgkmcnt(0)
	s_barrier

.LBB0_297:
	s_add_u32 s47, s38, s46
	s_addc_u32 s66, s39, 0
	s_add_u32 s64, s47, 0x100
	s_addc_u32 s65, s66, 0
	s_and_b64 s[48:49], s[44:45], exec
	s_cselect_b32 s49, s70, s65
	s_cselect_b32 s48, s71, s64
	s_add_u32 s46, s36, s46
	s_addc_u32 s64, s37, 0
	s_add_u32 s46, s46, 0x100
	s_addc_u32 s64, s64, 0
	s_and_b64 s[44:45], s[44:45], exec
	s_cselect_b32 s65, s72, s64
	s_cselect_b32 s64, s73, s46
	s_add_u32 s68, s47, 0x10080
	ds_read_b128 v[150:153], v146
	ds_read_b128 v[154:157], v146 offset:1024
	ds_read_b128 v[158:161], v146 offset:2048
	ds_read_b128 v[162:165], v146 offset:3072
	ds_read_b128 v[166:169], v147
	ds_read_b128 v[170:173], v147 offset:1024
	ds_read_b128 v[174:177], v147 offset:2048
	ds_read_b128 v[178:181], v147 offset:3072
	s_addc_u32 s69, s66, 0
	s_add_i32 s83, s30, s2
	s_add_i32 m0, s16, 0xc000
	s_add_i32 s84, s16, 0xe000
	s_add_i32 s80, s83, 0x2000
	s_add_u32 s66, s64, 0x40000
	s_addc_u32 s67, s65, 0
	s_add_i32 s82, s31, s2
	s_add_i32 s81, s82, 0x2000
	s_add_i32 s79, 0, 0x18000
	s_add_i32 s78, 0, 0x1c000
	s_add_u32 s46, s48, 0x10000
	s_addc_u32 s47, s49, 0
	s_add_i32 s77, s79, s2
	s_add_i32 s75, s77, 0x2000
	s_add_u32 s44, s64, 0x40080
	s_addc_u32 s45, s65, 0
	s_add_i32 s76, s78, s2
	s_add_i32 s74, s76, 0x2000
	v_lshl_add_u64 v[202:203], s[68:69], 0, v[130:131]
	ds_read_b128 v[182:185], v148
	ds_read_b128 v[186:189], v148 offset:1024
	ds_read_b128 v[190:193], v148 offset:2048
	ds_read_b128 v[194:197], v148 offset:3072
	ds_read_b128 v[198:201], v148 offset:4096
	ds_read_b128 v[206:209], v148 offset:5120
	ds_read_b128 v[210:213], v148 offset:6144
	ds_read_b128 v[214:217], v148 offset:7168
	global_load_lds_dwordx4 v[202:203], off
	v_lshl_add_u64 v[202:203], s[68:69], 0, v[132:133]
	s_mov_b32 m0, s84
	s_nop 0
	global_load_lds_dwordx4 v[202:203], off
	s_waitcnt vmcnt(8)
	s_waitcnt lgkmcnt(0)
	s_barrier
	s_setprio 1
	s_waitcnt lgkmcnt(0)
	v_mfma_f32_16x16x32_bf16 v[126:129], v[150:153], v[182:185], v[126:129]
	v_mfma_f32_16x16x32_bf16 v[122:125], v[158:161], v[182:185], v[122:125]
	v_mfma_f32_16x16x32_bf16 v[118:121], v[150:153], v[190:193], v[118:121]
	v_mfma_f32_16x16x32_bf16 v[114:117], v[158:161], v[190:193], v[114:117]
	v_mfma_f32_16x16x32_bf16 v[102:105], v[150:153], v[198:201], v[102:105]
	v_mfma_f32_16x16x32_bf16 v[98:101], v[158:161], v[198:201], v[98:101]
	v_mfma_f32_16x16x32_bf16 v[86:89], v[150:153], v[210:213], v[86:89]
	v_mfma_f32_16x16x32_bf16 v[82:85], v[158:161], v[210:213], v[82:85]
	v_mfma_f32_16x16x32_bf16 v[126:129], v[154:157], v[186:189], v[126:129]
	v_mfma_f32_16x16x32_bf16 v[122:125], v[162:165], v[186:189], v[122:125]
	v_mfma_f32_16x16x32_bf16 v[118:121], v[154:157], v[194:197], v[118:121]
	v_mfma_f32_16x16x32_bf16 v[114:117], v[162:165], v[194:197], v[114:117]
	v_mfma_f32_16x16x32_bf16 v[102:105], v[154:157], v[206:209], v[102:105]
	v_mfma_f32_16x16x32_bf16 v[98:101], v[162:165], v[206:209], v[98:101]
	v_mfma_f32_16x16x32_bf16 v[86:89], v[154:157], v[214:217], v[86:89]
	v_mfma_f32_16x16x32_bf16 v[82:85], v[162:165], v[214:217], v[82:85]
	s_setprio 0
	s_setprio 1
	v_mfma_f32_16x16x32_bf16 v[110:113], v[166:169], v[182:185], v[110:113]
	v_mfma_f32_16x16x32_bf16 v[106:109], v[174:177], v[182:185], v[106:109]
	v_mfma_f32_16x16x32_bf16 v[94:97], v[166:169], v[190:193], v[94:97]
	v_mfma_f32_16x16x32_bf16 v[90:93], v[174:177], v[190:193], v[90:93]
	v_mfma_f32_16x16x32_bf16 v[78:81], v[166:169], v[198:201], v[78:81]
	v_mfma_f32_16x16x32_bf16 v[74:77], v[174:177], v[198:201], v[74:77]
	v_mfma_f32_16x16x32_bf16 v[70:73], v[166:169], v[210:213], v[70:73]
	v_mfma_f32_16x16x32_bf16 v[66:69], v[174:177], v[210:213], v[66:69]
	v_mfma_f32_16x16x32_bf16 v[110:113], v[170:173], v[186:189], v[110:113]
	v_mfma_f32_16x16x32_bf16 v[106:109], v[178:181], v[186:189], v[106:109]
	v_mfma_f32_16x16x32_bf16 v[94:97], v[170:173], v[194:197], v[94:97]
	v_mfma_f32_16x16x32_bf16 v[90:93], v[178:181], v[194:197], v[90:93]
	v_mfma_f32_16x16x32_bf16 v[78:81], v[170:173], v[206:209], v[78:81]
	v_mfma_f32_16x16x32_bf16 v[74:77], v[178:181], v[206:209], v[74:77]
	v_mfma_f32_16x16x32_bf16 v[70:73], v[170:173], v[214:217], v[70:73]
	v_mfma_f32_16x16x32_bf16 v[66:69], v[178:181], v[214:217], v[66:69]
	s_setprio 0
	s_barrier
	s_mov_b32 m0, s83
	v_lshl_add_u64 v[202:203], s[64:65], 0, v[136:137]
	ds_read_b128 v[182:185], v148 offset:16384
	ds_read_b128 v[186:189], v148 offset:17408
	ds_read_b128 v[190:193], v148 offset:18432
	ds_read_b128 v[194:197], v148 offset:19456
	ds_read_b128 v[198:201], v148 offset:20480
	ds_read_b128 v[206:209], v148 offset:21504
	ds_read_b128 v[210:213], v148 offset:22528
	ds_read_b128 v[214:217], v148 offset:23552
	global_load_lds_dwordx4 v[202:203], off
	v_lshl_add_u64 v[218:219], s[64:65], 0, v[134:135]
	s_mov_b32 m0, s80
	v_lshl_add_u64 v[220:221], s[66:67], 0, v[136:137]
	global_load_lds_dwordx4 v[218:219], off
	s_mov_b32 m0, s82
	v_lshl_add_u64 v[222:223], s[48:49], 0, v[132:133]
	global_load_lds_dwordx4 v[220:221], off
	v_lshl_add_u64 v[220:221], s[66:67], 0, v[134:135]
	s_mov_b32 m0, s81
	s_nop 0
	global_load_lds_dwordx4 v[220:221], off
	v_lshl_add_u64 v[220:221], s[48:49], 0, v[130:131]
	s_mov_b32 m0, s16
	s_nop 0
	global_load_lds_dwordx4 v[220:221], off
	s_mov_b32 m0, s17
	s_nop 0
	global_load_lds_dwordx4 v[222:223], off
	s_waitcnt vmcnt(8)
	s_waitcnt lgkmcnt(0)
	s_barrier
	s_setprio 1
	s_waitcnt lgkmcnt(0)
	v_mfma_f32_16x16x32_bf16 v[62:65], v[150:153], v[182:185], v[62:65]
	v_mfma_f32_16x16x32_bf16 v[58:61], v[158:161], v[182:185], v[58:61]
	v_mfma_f32_16x16x32_bf16 v[54:57], v[150:153], v[190:193], v[54:57]
	v_mfma_f32_16x16x32_bf16 v[50:53], v[158:161], v[190:193], v[50:53]
	v_mfma_f32_16x16x32_bf16 v[38:41], v[150:153], v[198:201], v[38:41]
	v_mfma_f32_16x16x32_bf16 v[34:37], v[158:161], v[198:201], v[34:37]
	v_mfma_f32_16x16x32_bf16 v[22:25], v[150:153], v[210:213], v[22:25]
	v_mfma_f32_16x16x32_bf16 v[18:21], v[158:161], v[210:213], v[18:21]
	v_mfma_f32_16x16x32_bf16 v[62:65], v[154:157], v[186:189], v[62:65]
	v_mfma_f32_16x16x32_bf16 v[58:61], v[162:165], v[186:189], v[58:61]
	v_mfma_f32_16x16x32_bf16 v[54:57], v[154:157], v[194:197], v[54:57]
	v_mfma_f32_16x16x32_bf16 v[50:53], v[162:165], v[194:197], v[50:53]
	v_mfma_f32_16x16x32_bf16 v[38:41], v[154:157], v[206:209], v[38:41]
	v_mfma_f32_16x16x32_bf16 v[34:37], v[162:165], v[206:209], v[34:37]
	v_mfma_f32_16x16x32_bf16 v[22:25], v[154:157], v[214:217], v[22:25]
	v_mfma_f32_16x16x32_bf16 v[18:21], v[162:165], v[214:217], v[18:21]
	s_setprio 0
	s_setprio 1
	v_mfma_f32_16x16x32_bf16 v[46:49], v[166:169], v[182:185], v[46:49]
	v_mfma_f32_16x16x32_bf16 v[42:45], v[174:177], v[182:185], v[42:45]
	v_mfma_f32_16x16x32_bf16 v[30:33], v[166:169], v[190:193], v[30:33]
	v_mfma_f32_16x16x32_bf16 v[26:29], v[174:177], v[190:193], v[26:29]
	v_mfma_f32_16x16x32_bf16 v[14:17], v[166:169], v[198:201], v[14:17]
	v_mfma_f32_16x16x32_bf16 v[10:13], v[174:177], v[198:201], v[10:13]
	v_mfma_f32_16x16x32_bf16 v[6:9], v[166:169], v[210:213], v[6:9]
	v_mfma_f32_16x16x32_bf16 v[2:5], v[174:177], v[210:213], v[2:5]
	v_mfma_f32_16x16x32_bf16 v[46:49], v[170:173], v[186:189], v[46:49]
	v_mfma_f32_16x16x32_bf16 v[42:45], v[178:181], v[186:189], v[42:45]
	v_mfma_f32_16x16x32_bf16 v[30:33], v[170:173], v[194:197], v[30:33]
	v_mfma_f32_16x16x32_bf16 v[26:29], v[178:181], v[194:197], v[26:29]
	v_mfma_f32_16x16x32_bf16 v[14:17], v[170:173], v[206:209], v[14:17]
	v_mfma_f32_16x16x32_bf16 v[10:13], v[178:181], v[206:209], v[10:13]
	v_mfma_f32_16x16x32_bf16 v[6:9], v[170:173], v[214:217], v[6:9]
	v_mfma_f32_16x16x32_bf16 v[2:5], v[178:181], v[214:217], v[2:5]
	s_setprio 0
	s_barrier
	v_add_u32_e32 v149, s79, v145
	ds_read_b128 v[150:153], v149
	ds_read_b128 v[154:157], v149 offset:1024
	ds_read_b128 v[158:161], v149 offset:2048
	ds_read_b128 v[162:165], v149 offset:3072
	v_add_u32_e32 v149, s78, v145
	ds_read_b128 v[166:169], v149
	ds_read_b128 v[170:173], v149 offset:1024
	ds_read_b128 v[174:177], v149 offset:2048
	ds_read_b128 v[178:181], v149 offset:3072
	s_mov_b32 m0, s18
	v_lshl_add_u64 v[224:225], s[46:47], 0, v[130:131]
	ds_read_b128 v[182:185], v148 offset:32768
	ds_read_b128 v[186:189], v148 offset:33792
	ds_read_b128 v[190:193], v148 offset:34816
	ds_read_b128 v[194:197], v148 offset:35840
	ds_read_b128 v[198:201], v148 offset:36864
	ds_read_b128 v[206:209], v148 offset:37888
	ds_read_b128 v[210:213], v148 offset:38912
	ds_read_b128 v[214:217], v148 offset:39936
	global_load_lds_dwordx4 v[224:225], off
	v_lshl_add_u64 v[224:225], s[46:47], 0, v[132:133]
	s_mov_b32 m0, s19
	s_nop 0
	global_load_lds_dwordx4 v[224:225], off
	s_waitcnt vmcnt(8)
	s_waitcnt lgkmcnt(0)
	s_barrier
	s_setprio 1
	s_waitcnt lgkmcnt(0)
	v_mfma_f32_16x16x32_bf16 v[126:129], v[150:153], v[182:185], v[126:129]
	v_mfma_f32_16x16x32_bf16 v[122:125], v[158:161], v[182:185], v[122:125]
	v_mfma_f32_16x16x32_bf16 v[118:121], v[150:153], v[190:193], v[118:121]
	v_mfma_f32_16x16x32_bf16 v[114:117], v[158:161], v[190:193], v[114:117]
	v_mfma_f32_16x16x32_bf16 v[102:105], v[150:153], v[198:201], v[102:105]
	v_mfma_f32_16x16x32_bf16 v[98:101], v[158:161], v[198:201], v[98:101]
	v_mfma_f32_16x16x32_bf16 v[86:89], v[150:153], v[210:213], v[86:89]
	v_mfma_f32_16x16x32_bf16 v[82:85], v[158:161], v[210:213], v[82:85]
	v_mfma_f32_16x16x32_bf16 v[126:129], v[154:157], v[186:189], v[126:129]
	v_mfma_f32_16x16x32_bf16 v[122:125], v[162:165], v[186:189], v[122:125]
	v_mfma_f32_16x16x32_bf16 v[118:121], v[154:157], v[194:197], v[118:121]
	v_mfma_f32_16x16x32_bf16 v[114:117], v[162:165], v[194:197], v[114:117]
	v_mfma_f32_16x16x32_bf16 v[102:105], v[154:157], v[206:209], v[102:105]
	v_mfma_f32_16x16x32_bf16 v[98:101], v[162:165], v[206:209], v[98:101]
	v_mfma_f32_16x16x32_bf16 v[86:89], v[154:157], v[214:217], v[86:89]
	v_mfma_f32_16x16x32_bf16 v[82:85], v[162:165], v[214:217], v[82:85]
	s_setprio 0
	s_setprio 1
	v_mfma_f32_16x16x32_bf16 v[110:113], v[166:169], v[182:185], v[110:113]
	v_mfma_f32_16x16x32_bf16 v[106:109], v[174:177], v[182:185], v[106:109]
	v_mfma_f32_16x16x32_bf16 v[94:97], v[166:169], v[190:193], v[94:97]
	v_mfma_f32_16x16x32_bf16 v[90:93], v[174:177], v[190:193], v[90:93]
	v_mfma_f32_16x16x32_bf16 v[78:81], v[166:169], v[198:201], v[78:81]
	v_mfma_f32_16x16x32_bf16 v[74:77], v[174:177], v[198:201], v[74:77]
	v_mfma_f32_16x16x32_bf16 v[70:73], v[166:169], v[210:213], v[70:73]
	v_mfma_f32_16x16x32_bf16 v[66:69], v[174:177], v[210:213], v[66:69]
	v_mfma_f32_16x16x32_bf16 v[110:113], v[170:173], v[186:189], v[110:113]
	v_mfma_f32_16x16x32_bf16 v[106:109], v[178:181], v[186:189], v[106:109]
	v_mfma_f32_16x16x32_bf16 v[94:97], v[170:173], v[194:197], v[94:97]
	v_mfma_f32_16x16x32_bf16 v[90:93], v[178:181], v[194:197], v[90:93]
	v_mfma_f32_16x16x32_bf16 v[78:81], v[170:173], v[206:209], v[78:81]
	v_mfma_f32_16x16x32_bf16 v[74:77], v[178:181], v[206:209], v[74:77]
	v_mfma_f32_16x16x32_bf16 v[70:73], v[170:173], v[214:217], v[70:73]
	v_mfma_f32_16x16x32_bf16 v[66:69], v[178:181], v[214:217], v[66:69]
	s_setprio 0
	s_barrier
	s_mov_b32 m0, s77
	v_lshl_add_u64 v[202:203], v[202:203], 0, s[8:9]
	ds_read_b128 v[182:185], v148 offset:49152
	ds_read_b128 v[186:189], v148 offset:50176
	ds_read_b128 v[190:193], v148 offset:51200
	ds_read_b128 v[194:197], v148 offset:52224
	ds_read_b128 v[198:201], v148 offset:53248
	ds_read_b128 v[206:209], v148 offset:54272
	ds_read_b128 v[210:213], v148 offset:55296
	ds_read_b128 v[214:217], v148 offset:56320
	global_load_lds_dwordx4 v[202:203], off
	v_lshl_add_u64 v[202:203], v[218:219], 0, s[8:9]
	s_mov_b32 m0, s75
	s_nop 0
	global_load_lds_dwordx4 v[202:203], off
	v_lshl_add_u64 v[202:203], s[44:45], 0, v[136:137]
	s_mov_b32 m0, s76
	s_nop 0
	global_load_lds_dwordx4 v[202:203], off
	v_lshl_add_u64 v[202:203], s[44:45], 0, v[134:135]
	s_mov_b32 m0, s74
	s_nop 0
	global_load_lds_dwordx4 v[202:203], off
	v_lshl_add_u64 v[202:203], v[220:221], 0, s[8:9]
	s_mov_b32 m0, s28
	s_nop 0
	global_load_lds_dwordx4 v[202:203], off
	v_lshl_add_u64 v[202:203], v[222:223], 0, s[8:9]
	s_mov_b32 m0, s29
	s_nop 0
	global_load_lds_dwordx4 v[202:203], off
	s_waitcnt vmcnt(8)
	s_waitcnt lgkmcnt(0)
	s_barrier
	s_setprio 1
	s_waitcnt lgkmcnt(0)
	v_mfma_f32_16x16x32_bf16 v[62:65], v[150:153], v[182:185], v[62:65]
	v_mfma_f32_16x16x32_bf16 v[58:61], v[158:161], v[182:185], v[58:61]
	v_mfma_f32_16x16x32_bf16 v[54:57], v[150:153], v[190:193], v[54:57]
	v_mfma_f32_16x16x32_bf16 v[50:53], v[158:161], v[190:193], v[50:53]
	v_mfma_f32_16x16x32_bf16 v[38:41], v[150:153], v[198:201], v[38:41]
	v_mfma_f32_16x16x32_bf16 v[34:37], v[158:161], v[198:201], v[34:37]
	v_mfma_f32_16x16x32_bf16 v[22:25], v[150:153], v[210:213], v[22:25]
	v_mfma_f32_16x16x32_bf16 v[18:21], v[158:161], v[210:213], v[18:21]
	v_mfma_f32_16x16x32_bf16 v[62:65], v[154:157], v[186:189], v[62:65]
	v_mfma_f32_16x16x32_bf16 v[58:61], v[162:165], v[186:189], v[58:61]
	v_mfma_f32_16x16x32_bf16 v[54:57], v[154:157], v[194:197], v[54:57]
	v_mfma_f32_16x16x32_bf16 v[50:53], v[162:165], v[194:197], v[50:53]
	v_mfma_f32_16x16x32_bf16 v[38:41], v[154:157], v[206:209], v[38:41]
	v_mfma_f32_16x16x32_bf16 v[34:37], v[162:165], v[206:209], v[34:37]
	v_mfma_f32_16x16x32_bf16 v[22:25], v[154:157], v[214:217], v[22:25]
	v_mfma_f32_16x16x32_bf16 v[18:21], v[162:165], v[214:217], v[18:21]
	s_setprio 0
	s_setprio 1
	v_mfma_f32_16x16x32_bf16 v[46:49], v[166:169], v[182:185], v[46:49]
	v_mfma_f32_16x16x32_bf16 v[42:45], v[174:177], v[182:185], v[42:45]
	v_mfma_f32_16x16x32_bf16 v[30:33], v[166:169], v[190:193], v[30:33]
	v_mfma_f32_16x16x32_bf16 v[26:29], v[174:177], v[190:193], v[26:29]
	v_mfma_f32_16x16x32_bf16 v[14:17], v[166:169], v[198:201], v[14:17]
	v_mfma_f32_16x16x32_bf16 v[10:13], v[174:177], v[198:201], v[10:13]
	v_mfma_f32_16x16x32_bf16 v[6:9], v[166:169], v[210:213], v[6:9]
	v_mfma_f32_16x16x32_bf16 v[2:5], v[174:177], v[210:213], v[2:5]
	v_mfma_f32_16x16x32_bf16 v[46:49], v[170:173], v[186:189], v[46:49]
	v_mfma_f32_16x16x32_bf16 v[42:45], v[178:181], v[186:189], v[42:45]
	v_mfma_f32_16x16x32_bf16 v[30:33], v[170:173], v[194:197], v[30:33]
	v_mfma_f32_16x16x32_bf16 v[26:29], v[178:181], v[194:197], v[26:29]
	v_mfma_f32_16x16x32_bf16 v[14:17], v[170:173], v[206:209], v[14:17]
	v_mfma_f32_16x16x32_bf16 v[10:13], v[178:181], v[206:209], v[10:13]
	v_mfma_f32_16x16x32_bf16 v[6:9], v[170:173], v[214:217], v[6:9]
	v_mfma_f32_16x16x32_bf16 v[2:5], v[178:181], v[214:217], v[2:5]
	s_setprio 0
	s_barrier
	s_movk_i32 s46, 0x100
	s_andn2_b64 vcc, exec, s[42:43]
	s_mov_b64 s[44:45], -1
	s_mov_b64 s[42:43], 0
	s_cbranch_vccz .LBB0_297
	s_and_b64 vcc, exec, s[10:11]
	s_cbranch_vccz .LBB0_300
	s_barrier

.LBB0_313:
	s_add_u32 s49, s38, s48
	s_addc_u32 s68, s39, 0
	s_add_u32 s66, s49, 0x100
	s_addc_u32 s67, s68, 0
	s_and_b64 s[64:65], s[46:47], exec
	s_cselect_b32 s65, s43, s67
	s_cselect_b32 s64, s75, s66
	s_add_u32 s48, s36, s48
	s_addc_u32 s66, s37, 0
	s_add_u32 s48, s48, 0x100
	s_addc_u32 s66, s66, 0
	s_and_b64 s[46:47], s[46:47], exec
	s_cselect_b32 s67, s76, s66
	s_cselect_b32 s66, s77, s48
	s_add_u32 s70, s49, 0x10080
	ds_read_b128 v[144:147], v140
	ds_read_b128 v[148:151], v140 offset:1024
	ds_read_b128 v[152:155], v140 offset:2048
	ds_read_b128 v[156:159], v140 offset:3072
	ds_read_b128 v[160:163], v141
	ds_read_b128 v[164:167], v141 offset:1024
	ds_read_b128 v[168:171], v141 offset:2048
	ds_read_b128 v[172:175], v141 offset:3072
	s_addc_u32 s71, s68, 0
	s_add_i32 s87, s33, s2
	s_add_i32 m0, s16, 0xc000
	s_add_i32 s88, s16, 0xe000
	s_add_i32 s84, s87, 0x2000
	s_add_u32 s68, s66, 0x1000
	s_addc_u32 s69, s67, 0
	s_add_i32 s86, s34, s2
	s_add_i32 s85, s86, 0x2000
	s_add_i32 s83, 0, 0x18000
	s_add_i32 s82, 0, 0x1c000
	s_add_u32 s48, s64, 0x10000
	s_addc_u32 s49, s65, 0
	s_add_i32 s81, s83, s2
	s_add_i32 s79, s81, 0x2000
	s_add_u32 s46, s66, 0x1080
	s_addc_u32 s47, s67, 0
	s_add_i32 s80, s82, s2
	s_add_i32 s78, s80, 0x2000
	v_lshl_add_u64 v[210:211], s[70:71], 0, v[130:131]
	ds_read_b128 v[176:179], v142
	ds_read_b128 v[180:183], v142 offset:1024
	ds_read_b128 v[184:187], v142 offset:2048
	ds_read_b128 v[188:191], v142 offset:3072
	ds_read_b128 v[192:195], v142 offset:4096
	ds_read_b128 v[196:199], v142 offset:5120
	ds_read_b128 v[200:203], v142 offset:6144
	ds_read_b128 v[206:209], v142 offset:7168
	global_load_lds_dwordx4 v[210:211], off
	v_lshl_add_u64 v[210:211], s[70:71], 0, v[132:133]
	s_mov_b32 m0, s88
	s_nop 0
	global_load_lds_dwordx4 v[210:211], off
	s_waitcnt vmcnt(8)
	s_waitcnt lgkmcnt(0)
	s_barrier
	s_setprio 1
	s_waitcnt lgkmcnt(0)
	v_mfma_f32_16x16x32_bf16 v[126:129], v[144:147], v[176:179], v[126:129]
	v_mfma_f32_16x16x32_bf16 v[122:125], v[152:155], v[176:179], v[122:125]
	v_mfma_f32_16x16x32_bf16 v[118:121], v[144:147], v[184:187], v[118:121]
	v_mfma_f32_16x16x32_bf16 v[114:117], v[152:155], v[184:187], v[114:117]
	v_mfma_f32_16x16x32_bf16 v[102:105], v[144:147], v[192:195], v[102:105]
	v_mfma_f32_16x16x32_bf16 v[98:101], v[152:155], v[192:195], v[98:101]
	v_mfma_f32_16x16x32_bf16 v[86:89], v[144:147], v[200:203], v[86:89]
	v_mfma_f32_16x16x32_bf16 v[82:85], v[152:155], v[200:203], v[82:85]
	v_mfma_f32_16x16x32_bf16 v[126:129], v[148:151], v[180:183], v[126:129]
	v_mfma_f32_16x16x32_bf16 v[122:125], v[156:159], v[180:183], v[122:125]
	v_mfma_f32_16x16x32_bf16 v[118:121], v[148:151], v[188:191], v[118:121]
	v_mfma_f32_16x16x32_bf16 v[114:117], v[156:159], v[188:191], v[114:117]
	v_mfma_f32_16x16x32_bf16 v[102:105], v[148:151], v[196:199], v[102:105]
	v_mfma_f32_16x16x32_bf16 v[98:101], v[156:159], v[196:199], v[98:101]
	v_mfma_f32_16x16x32_bf16 v[86:89], v[148:151], v[206:209], v[86:89]
	v_mfma_f32_16x16x32_bf16 v[82:85], v[156:159], v[206:209], v[82:85]
	s_setprio 0
	s_setprio 1
	v_mfma_f32_16x16x32_bf16 v[110:113], v[160:163], v[176:179], v[110:113]
	v_mfma_f32_16x16x32_bf16 v[106:109], v[168:171], v[176:179], v[106:109]
	v_mfma_f32_16x16x32_bf16 v[94:97], v[160:163], v[184:187], v[94:97]
	v_mfma_f32_16x16x32_bf16 v[90:93], v[168:171], v[184:187], v[90:93]
	v_mfma_f32_16x16x32_bf16 v[78:81], v[160:163], v[192:195], v[78:81]
	v_mfma_f32_16x16x32_bf16 v[74:77], v[168:171], v[192:195], v[74:77]
	v_mfma_f32_16x16x32_bf16 v[70:73], v[160:163], v[200:203], v[70:73]
	v_mfma_f32_16x16x32_bf16 v[66:69], v[168:171], v[200:203], v[66:69]
	v_mfma_f32_16x16x32_bf16 v[110:113], v[164:167], v[180:183], v[110:113]
	v_mfma_f32_16x16x32_bf16 v[106:109], v[172:175], v[180:183], v[106:109]
	v_mfma_f32_16x16x32_bf16 v[94:97], v[164:167], v[188:191], v[94:97]
	v_mfma_f32_16x16x32_bf16 v[90:93], v[172:175], v[188:191], v[90:93]
	v_mfma_f32_16x16x32_bf16 v[78:81], v[164:167], v[196:199], v[78:81]
	v_mfma_f32_16x16x32_bf16 v[74:77], v[172:175], v[196:199], v[74:77]
	v_mfma_f32_16x16x32_bf16 v[70:73], v[164:167], v[206:209], v[70:73]
	v_mfma_f32_16x16x32_bf16 v[66:69], v[172:175], v[206:209], v[66:69]
	s_setprio 0
	s_barrier
	s_mov_b32 m0, s87
	v_lshl_add_u64 v[210:211], s[66:67], 0, v[136:137]
	ds_read_b128 v[176:179], v142 offset:16384
	ds_read_b128 v[180:183], v142 offset:17408
	ds_read_b128 v[184:187], v142 offset:18432
	ds_read_b128 v[188:191], v142 offset:19456
	ds_read_b128 v[192:195], v142 offset:20480
	ds_read_b128 v[196:199], v142 offset:21504
	ds_read_b128 v[200:203], v142 offset:22528
	ds_read_b128 v[206:209], v142 offset:23552
	global_load_lds_dwordx4 v[210:211], off
	v_lshl_add_u64 v[212:213], s[66:67], 0, v[134:135]
	s_mov_b32 m0, s84
	v_lshl_add_u64 v[214:215], s[68:69], 0, v[136:137]
	global_load_lds_dwordx4 v[212:213], off
	s_mov_b32 m0, s86
	v_lshl_add_u64 v[216:217], s[64:65], 0, v[132:133]
	global_load_lds_dwordx4 v[214:215], off
	v_lshl_add_u64 v[214:215], s[68:69], 0, v[134:135]
	s_mov_b32 m0, s85
	s_nop 0
	global_load_lds_dwordx4 v[214:215], off
	v_lshl_add_u64 v[214:215], s[64:65], 0, v[130:131]
	s_mov_b32 m0, s16
	s_nop 0
	global_load_lds_dwordx4 v[214:215], off
	s_mov_b32 m0, s17
	s_nop 0
	global_load_lds_dwordx4 v[216:217], off
	s_waitcnt vmcnt(8)
	s_waitcnt lgkmcnt(0)
	s_barrier
	s_setprio 1
	s_waitcnt lgkmcnt(0)
	v_mfma_f32_16x16x32_bf16 v[62:65], v[144:147], v[176:179], v[62:65]
	v_mfma_f32_16x16x32_bf16 v[58:61], v[152:155], v[176:179], v[58:61]
	v_mfma_f32_16x16x32_bf16 v[54:57], v[144:147], v[184:187], v[54:57]
	v_mfma_f32_16x16x32_bf16 v[50:53], v[152:155], v[184:187], v[50:53]
	v_mfma_f32_16x16x32_bf16 v[38:41], v[144:147], v[192:195], v[38:41]
	v_mfma_f32_16x16x32_bf16 v[34:37], v[152:155], v[192:195], v[34:37]
	v_mfma_f32_16x16x32_bf16 v[22:25], v[144:147], v[200:203], v[22:25]
	v_mfma_f32_16x16x32_bf16 v[18:21], v[152:155], v[200:203], v[18:21]
	v_mfma_f32_16x16x32_bf16 v[62:65], v[148:151], v[180:183], v[62:65]
	v_mfma_f32_16x16x32_bf16 v[58:61], v[156:159], v[180:183], v[58:61]
	v_mfma_f32_16x16x32_bf16 v[54:57], v[148:151], v[188:191], v[54:57]
	v_mfma_f32_16x16x32_bf16 v[50:53], v[156:159], v[188:191], v[50:53]
	v_mfma_f32_16x16x32_bf16 v[38:41], v[148:151], v[196:199], v[38:41]
	v_mfma_f32_16x16x32_bf16 v[34:37], v[156:159], v[196:199], v[34:37]
	v_mfma_f32_16x16x32_bf16 v[22:25], v[148:151], v[206:209], v[22:25]
	v_mfma_f32_16x16x32_bf16 v[18:21], v[156:159], v[206:209], v[18:21]
	s_setprio 0
	s_setprio 1
	v_mfma_f32_16x16x32_bf16 v[46:49], v[160:163], v[176:179], v[46:49]
	v_mfma_f32_16x16x32_bf16 v[42:45], v[168:171], v[176:179], v[42:45]
	v_mfma_f32_16x16x32_bf16 v[30:33], v[160:163], v[184:187], v[30:33]
	v_mfma_f32_16x16x32_bf16 v[26:29], v[168:171], v[184:187], v[26:29]
	v_mfma_f32_16x16x32_bf16 v[14:17], v[160:163], v[192:195], v[14:17]
	v_mfma_f32_16x16x32_bf16 v[10:13], v[168:171], v[192:195], v[10:13]
	v_mfma_f32_16x16x32_bf16 v[6:9], v[160:163], v[200:203], v[6:9]
	v_mfma_f32_16x16x32_bf16 v[2:5], v[168:171], v[200:203], v[2:5]
	v_mfma_f32_16x16x32_bf16 v[46:49], v[164:167], v[180:183], v[46:49]
	v_mfma_f32_16x16x32_bf16 v[42:45], v[172:175], v[180:183], v[42:45]
	v_mfma_f32_16x16x32_bf16 v[30:33], v[164:167], v[188:191], v[30:33]
	v_mfma_f32_16x16x32_bf16 v[26:29], v[172:175], v[188:191], v[26:29]
	v_mfma_f32_16x16x32_bf16 v[14:17], v[164:167], v[196:199], v[14:17]
	v_mfma_f32_16x16x32_bf16 v[10:13], v[172:175], v[196:199], v[10:13]
	v_mfma_f32_16x16x32_bf16 v[6:9], v[164:167], v[206:209], v[6:9]
	v_mfma_f32_16x16x32_bf16 v[2:5], v[172:175], v[206:209], v[2:5]
	s_setprio 0
	s_barrier
	v_add_u32_e32 v143, s83, v139
	ds_read_b128 v[144:147], v143
	ds_read_b128 v[148:151], v143 offset:1024
	ds_read_b128 v[152:155], v143 offset:2048
	ds_read_b128 v[156:159], v143 offset:3072
	v_add_u32_e32 v143, s82, v139
	ds_read_b128 v[160:163], v143
	ds_read_b128 v[164:167], v143 offset:1024
	ds_read_b128 v[168:171], v143 offset:2048
	ds_read_b128 v[172:175], v143 offset:3072
	s_mov_b32 m0, s18
	v_lshl_add_u64 v[218:219], s[48:49], 0, v[130:131]
	ds_read_b128 v[176:179], v142 offset:32768
	ds_read_b128 v[180:183], v142 offset:33792
	ds_read_b128 v[184:187], v142 offset:34816
	ds_read_b128 v[188:191], v142 offset:35840
	ds_read_b128 v[192:195], v142 offset:36864
	ds_read_b128 v[196:199], v142 offset:37888
	ds_read_b128 v[200:203], v142 offset:38912
	ds_read_b128 v[206:209], v142 offset:39936
	global_load_lds_dwordx4 v[218:219], off
	v_lshl_add_u64 v[218:219], s[48:49], 0, v[132:133]
	s_mov_b32 m0, s19
	s_nop 0
	global_load_lds_dwordx4 v[218:219], off
	s_waitcnt vmcnt(8)
	s_waitcnt lgkmcnt(0)
	s_barrier
	s_setprio 1
	s_waitcnt lgkmcnt(0)
	v_mfma_f32_16x16x32_bf16 v[126:129], v[144:147], v[176:179], v[126:129]
	v_mfma_f32_16x16x32_bf16 v[122:125], v[152:155], v[176:179], v[122:125]
	v_mfma_f32_16x16x32_bf16 v[118:121], v[144:147], v[184:187], v[118:121]
	v_mfma_f32_16x16x32_bf16 v[114:117], v[152:155], v[184:187], v[114:117]
	v_mfma_f32_16x16x32_bf16 v[102:105], v[144:147], v[192:195], v[102:105]
	v_mfma_f32_16x16x32_bf16 v[98:101], v[152:155], v[192:195], v[98:101]
	v_mfma_f32_16x16x32_bf16 v[86:89], v[144:147], v[200:203], v[86:89]
	v_mfma_f32_16x16x32_bf16 v[82:85], v[152:155], v[200:203], v[82:85]
	v_mfma_f32_16x16x32_bf16 v[126:129], v[148:151], v[180:183], v[126:129]
	v_mfma_f32_16x16x32_bf16 v[122:125], v[156:159], v[180:183], v[122:125]
	v_mfma_f32_16x16x32_bf16 v[118:121], v[148:151], v[188:191], v[118:121]
	v_mfma_f32_16x16x32_bf16 v[114:117], v[156:159], v[188:191], v[114:117]
	v_mfma_f32_16x16x32_bf16 v[102:105], v[148:151], v[196:199], v[102:105]
	v_mfma_f32_16x16x32_bf16 v[98:101], v[156:159], v[196:199], v[98:101]
	v_mfma_f32_16x16x32_bf16 v[86:89], v[148:151], v[206:209], v[86:89]
	v_mfma_f32_16x16x32_bf16 v[82:85], v[156:159], v[206:209], v[82:85]
	s_setprio 0
	s_setprio 1
	v_mfma_f32_16x16x32_bf16 v[110:113], v[160:163], v[176:179], v[110:113]
	v_mfma_f32_16x16x32_bf16 v[106:109], v[168:171], v[176:179], v[106:109]
	v_mfma_f32_16x16x32_bf16 v[94:97], v[160:163], v[184:187], v[94:97]
	v_mfma_f32_16x16x32_bf16 v[90:93], v[168:171], v[184:187], v[90:93]
	v_mfma_f32_16x16x32_bf16 v[78:81], v[160:163], v[192:195], v[78:81]
	v_mfma_f32_16x16x32_bf16 v[74:77], v[168:171], v[192:195], v[74:77]
	v_mfma_f32_16x16x32_bf16 v[70:73], v[160:163], v[200:203], v[70:73]
	v_mfma_f32_16x16x32_bf16 v[66:69], v[168:171], v[200:203], v[66:69]
	v_mfma_f32_16x16x32_bf16 v[110:113], v[164:167], v[180:183], v[110:113]
	v_mfma_f32_16x16x32_bf16 v[106:109], v[172:175], v[180:183], v[106:109]
	v_mfma_f32_16x16x32_bf16 v[94:97], v[164:167], v[188:191], v[94:97]
	v_mfma_f32_16x16x32_bf16 v[90:93], v[172:175], v[188:191], v[90:93]
	v_mfma_f32_16x16x32_bf16 v[78:81], v[164:167], v[196:199], v[78:81]
	v_mfma_f32_16x16x32_bf16 v[74:77], v[172:175], v[196:199], v[74:77]
	v_mfma_f32_16x16x32_bf16 v[70:73], v[164:167], v[206:209], v[70:73]
	v_mfma_f32_16x16x32_bf16 v[66:69], v[172:175], v[206:209], v[66:69]
	s_setprio 0
	s_barrier
	s_mov_b32 m0, s81
	v_lshl_add_u64 v[210:211], v[210:211], 0, s[8:9]
	ds_read_b128 v[176:179], v142 offset:49152
	ds_read_b128 v[180:183], v142 offset:50176
	ds_read_b128 v[184:187], v142 offset:51200
	ds_read_b128 v[188:191], v142 offset:52224
	ds_read_b128 v[192:195], v142 offset:53248
	ds_read_b128 v[196:199], v142 offset:54272
	ds_read_b128 v[200:203], v142 offset:55296
	ds_read_b128 v[206:209], v142 offset:56320
	global_load_lds_dwordx4 v[210:211], off
	v_lshl_add_u64 v[210:211], v[212:213], 0, s[8:9]
	s_mov_b32 m0, s79
	s_nop 0
	global_load_lds_dwordx4 v[210:211], off
	v_lshl_add_u64 v[210:211], s[46:47], 0, v[136:137]
	s_mov_b32 m0, s80
	s_nop 0
	global_load_lds_dwordx4 v[210:211], off
	v_lshl_add_u64 v[210:211], s[46:47], 0, v[134:135]
	s_mov_b32 m0, s78
	s_nop 0
	global_load_lds_dwordx4 v[210:211], off
	v_lshl_add_u64 v[210:211], v[214:215], 0, s[8:9]
	s_mov_b32 m0, s30
	s_nop 0
	global_load_lds_dwordx4 v[210:211], off
	v_lshl_add_u64 v[210:211], v[216:217], 0, s[8:9]
	s_mov_b32 m0, s31
	s_nop 0
	global_load_lds_dwordx4 v[210:211], off
	s_waitcnt vmcnt(8)
	s_waitcnt lgkmcnt(0)
	s_barrier
	s_setprio 1
	s_waitcnt lgkmcnt(0)
	v_mfma_f32_16x16x32_bf16 v[62:65], v[144:147], v[176:179], v[62:65]
	v_mfma_f32_16x16x32_bf16 v[58:61], v[152:155], v[176:179], v[58:61]
	v_mfma_f32_16x16x32_bf16 v[54:57], v[144:147], v[184:187], v[54:57]
	v_mfma_f32_16x16x32_bf16 v[50:53], v[152:155], v[184:187], v[50:53]
	v_mfma_f32_16x16x32_bf16 v[38:41], v[144:147], v[192:195], v[38:41]
	v_mfma_f32_16x16x32_bf16 v[34:37], v[152:155], v[192:195], v[34:37]
	v_mfma_f32_16x16x32_bf16 v[22:25], v[144:147], v[200:203], v[22:25]
	v_mfma_f32_16x16x32_bf16 v[18:21], v[152:155], v[200:203], v[18:21]
	v_mfma_f32_16x16x32_bf16 v[62:65], v[148:151], v[180:183], v[62:65]
	v_mfma_f32_16x16x32_bf16 v[58:61], v[156:159], v[180:183], v[58:61]
	v_mfma_f32_16x16x32_bf16 v[54:57], v[148:151], v[188:191], v[54:57]
	v_mfma_f32_16x16x32_bf16 v[50:53], v[156:159], v[188:191], v[50:53]
	v_mfma_f32_16x16x32_bf16 v[38:41], v[148:151], v[196:199], v[38:41]
	v_mfma_f32_16x16x32_bf16 v[34:37], v[156:159], v[196:199], v[34:37]
	v_mfma_f32_16x16x32_bf16 v[22:25], v[148:151], v[206:209], v[22:25]
	v_mfma_f32_16x16x32_bf16 v[18:21], v[156:159], v[206:209], v[18:21]
	s_setprio 0
	s_setprio 1
	v_mfma_f32_16x16x32_bf16 v[46:49], v[160:163], v[176:179], v[46:49]
	v_mfma_f32_16x16x32_bf16 v[42:45], v[168:171], v[176:179], v[42:45]
	v_mfma_f32_16x16x32_bf16 v[30:33], v[160:163], v[184:187], v[30:33]
	v_mfma_f32_16x16x32_bf16 v[26:29], v[168:171], v[184:187], v[26:29]
	v_mfma_f32_16x16x32_bf16 v[14:17], v[160:163], v[192:195], v[14:17]
	v_mfma_f32_16x16x32_bf16 v[10:13], v[168:171], v[192:195], v[10:13]
	v_mfma_f32_16x16x32_bf16 v[6:9], v[160:163], v[200:203], v[6:9]
	v_mfma_f32_16x16x32_bf16 v[2:5], v[168:171], v[200:203], v[2:5]
	v_mfma_f32_16x16x32_bf16 v[46:49], v[164:167], v[180:183], v[46:49]
	v_mfma_f32_16x16x32_bf16 v[42:45], v[172:175], v[180:183], v[42:45]
	v_mfma_f32_16x16x32_bf16 v[30:33], v[164:167], v[188:191], v[30:33]
	v_mfma_f32_16x16x32_bf16 v[26:29], v[172:175], v[188:191], v[26:29]
	v_mfma_f32_16x16x32_bf16 v[14:17], v[164:167], v[196:199], v[14:17]
	v_mfma_f32_16x16x32_bf16 v[10:13], v[172:175], v[196:199], v[10:13]
	v_mfma_f32_16x16x32_bf16 v[6:9], v[164:167], v[206:209], v[6:9]
	v_mfma_f32_16x16x32_bf16 v[2:5], v[172:175], v[206:209], v[2:5]
	s_setprio 0
	s_barrier
	s_movk_i32 s48, 0x100
	s_andn2_b64 vcc, exec, s[44:45]
	s_mov_b64 s[46:47], -1
	s_mov_b64 s[44:45], 0
	s_cbranch_vccz .LBB0_313
	s_and_b64 vcc, exec, s[10:11]
	s_cbranch_vccz .LBB0_316
	s_barrier

.LBB0_320:
	s_cmp_gt_i32 s59, 3
	s_cselect_b64 s[6:7], -1, 0
	s_and_b64 s[2:3], s[4:5], s[6:7]
	s_andn2_b64 vcc, exec, s[2:3]
	s_cbranch_vccnz .LBB0_374
	s_waitcnt vmcnt(0) lgkmcnt(0)
	s_barrier
	s_mov_b64 s[2:3], exec
	v_readlane_b32 s4, v249, 5
	v_readlane_b32 s5, v249, 6
	v_readlane_b32 s10, v249, 4
	s_and_b64 s[4:5], s[2:3], s[4:5]
	s_mov_b64 exec, s[4:5]
	s_cbranch_execz .Lgb_2_done
	v_mov_b32_e32 v1, 0x27e00
	ds_read2_b32 v[2:3], v1 offset1:1
	s_lshl_b32 s10, s10, 8
	s_add_u32 s8, s56, s10
	s_addc_u32 s9, s57, 0
	v_mov_b32_e32 v4, 0x1000
	v_mov_b32_e32 v5, 1
	global_atomic_add v6, v4, v5, s[8:9] offset:1024 sc0
	buffer_inv sc1
	s_waitcnt lgkmcnt(0)
	v_mul_lo_u32 v7, v2, 3
	s_waitcnt vmcnt(1)
	v_add_u32_e32 v6, 1, v6
	v_cmp_eq_u32_e32 vcc, v6, v7
	s_cbranch_vccz .Lgb_2_wait
	buffer_wbl2 sc1
	s_waitcnt vmcnt(0)
	v_mov_b32_e32 v4, 0x3000
	global_atomic_add v8, v4, v5, s[56:57] offset:1024 sc0
	v_mul_lo_u32 v7, v3, 3
	s_waitcnt vmcnt(0)
	v_add_u32_e32 v8, 1, v8
	v_cmp_eq_u32_e32 vcc, v8, v7
	s_cbranch_vccz .Lgb_2_wait
	v_mov_b32_e32 v9, 0x2400
	global_atomic_add v9, v5, s[56:57] offset:0
	global_atomic_add v9, v5, s[56:57] offset:256
	global_atomic_add v9, v5, s[56:57] offset:512
	global_atomic_add v9, v5, s[56:57] offset:768
	global_atomic_add v9, v5, s[56:57] offset:1024
	global_atomic_add v9, v5, s[56:57] offset:1280
	global_atomic_add v9, v5, s[56:57] offset:1536
	global_atomic_add v9, v5, s[56:57] offset:1792
	global_atomic_add v9, v5, s[56:57] offset:2048
	global_atomic_add v9, v5, s[56:57] offset:2304
	global_atomic_add v9, v5, s[56:57] offset:2560
	global_atomic_add v9, v5, s[56:57] offset:2816
	global_atomic_add v9, v5, s[56:57] offset:3072
	global_atomic_add v9, v5, s[56:57] offset:3328
	global_atomic_add v9, v5, s[56:57] offset:3584
	global_atomic_add v9, v5, s[56:57] offset:3840
	s_waitcnt vmcnt(0)
	s_branch .Lgb_2_done
.Lgb_2_wait:
	s_mov_b32 s10, 0
	v_mov_b32_e32 v9, 0x2000
.Lgb_2_spin:
	global_load_dword v8, v9, s[8:9] offset:1024 sc1
	s_waitcnt vmcnt(0)
	v_cmp_ne_u32_e32 vcc, 2, v8
	s_cbranch_vccnz .Lgb_2_done
	s_sleep 1
	s_add_u32 s10, s10, 1
	s_cmp_lt_u32 s10, 0x40000
	s_cbranch_scc1 .Lgb_2_spin
.Lgb_2_done:
	s_mov_b64 exec, s[2:3]
	s_waitcnt vmcnt(0) lgkmcnt(0)
	s_barrier

.LBB0_384:
	ds_read_b128 v[152:155], v146
	ds_read_b128 v[156:159], v146 offset:1024
	ds_read_b128 v[160:163], v146 offset:2048
	ds_read_b128 v[164:167], v146 offset:3072
	ds_read_b128 v[168:171], v147
	ds_read_b128 v[172:175], v147 offset:1024
	ds_read_b128 v[176:179], v147 offset:2048
	ds_read_b128 v[180:183], v147 offset:3072
	s_add_u32 s44, s42, 0x100
	s_addc_u32 s45, s43, 0
	s_add_u32 s46, s66, s42
	s_addc_u32 s47, s67, s43
	s_cmp_eq_u32 s68, 4
	s_cselect_b32 s48, 0, s44
	s_cselect_b32 s49, 0, s45
	s_cselect_b32 s46, s39, s46
	s_cselect_b32 s47, s15, s47
	s_add_u32 s48, s6, s48
	s_addc_u32 s49, s7, s49
	s_mov_b32 m0, s29
	v_lshl_add_u64 v[218:219], v[138:139], 0, s[42:43]
	ds_read_b128 v[184:187], v148
	ds_read_b128 v[188:191], v148 offset:1024
	ds_read_b128 v[192:195], v148 offset:2048
	ds_read_b128 v[196:199], v148 offset:3072
	ds_read_b128 v[200:203], v148 offset:4096
	ds_read_b128 v[206:209], v148 offset:5120
	ds_read_b128 v[210:213], v148 offset:6144
	ds_read_b128 v[214:217], v148 offset:7168
	global_load_lds_dwordx4 v[218:219], off
	v_lshl_add_u64 v[218:219], v[140:141], 0, s[42:43]
	s_mov_b32 m0, s30
	s_nop 0
	global_load_lds_dwordx4 v[218:219], off
	s_waitcnt vmcnt(8)
	s_waitcnt lgkmcnt(0)
	s_barrier
	s_setprio 1
	s_waitcnt lgkmcnt(0)
	v_mfma_f32_16x16x32_bf16 v[126:129], v[152:155], v[184:187], v[126:129]
	v_mfma_f32_16x16x32_bf16 v[122:125], v[160:163], v[184:187], v[122:125]
	v_mfma_f32_16x16x32_bf16 v[118:121], v[152:155], v[192:195], v[118:121]
	v_mfma_f32_16x16x32_bf16 v[114:117], v[160:163], v[192:195], v[114:117]
	v_mfma_f32_16x16x32_bf16 v[102:105], v[152:155], v[200:203], v[102:105]
	v_mfma_f32_16x16x32_bf16 v[98:101], v[160:163], v[200:203], v[98:101]
	v_mfma_f32_16x16x32_bf16 v[86:89], v[152:155], v[210:213], v[86:89]
	v_mfma_f32_16x16x32_bf16 v[82:85], v[160:163], v[210:213], v[82:85]
	v_mfma_f32_16x16x32_bf16 v[126:129], v[156:159], v[188:191], v[126:129]
	v_mfma_f32_16x16x32_bf16 v[122:125], v[164:167], v[188:191], v[122:125]
	v_mfma_f32_16x16x32_bf16 v[118:121], v[156:159], v[196:199], v[118:121]
	v_mfma_f32_16x16x32_bf16 v[114:117], v[164:167], v[196:199], v[114:117]
	v_mfma_f32_16x16x32_bf16 v[102:105], v[156:159], v[206:209], v[102:105]
	v_mfma_f32_16x16x32_bf16 v[98:101], v[164:167], v[206:209], v[98:101]
	v_mfma_f32_16x16x32_bf16 v[86:89], v[156:159], v[214:217], v[86:89]
	v_mfma_f32_16x16x32_bf16 v[82:85], v[164:167], v[214:217], v[82:85]
	s_setprio 0
	s_setprio 1
	v_mfma_f32_16x16x32_bf16 v[110:113], v[168:171], v[184:187], v[110:113]
	v_mfma_f32_16x16x32_bf16 v[106:109], v[176:179], v[184:187], v[106:109]
	v_mfma_f32_16x16x32_bf16 v[94:97], v[168:171], v[192:195], v[94:97]
	v_mfma_f32_16x16x32_bf16 v[90:93], v[176:179], v[192:195], v[90:93]
	v_mfma_f32_16x16x32_bf16 v[78:81], v[168:171], v[200:203], v[78:81]
	v_mfma_f32_16x16x32_bf16 v[74:77], v[176:179], v[200:203], v[74:77]
	v_mfma_f32_16x16x32_bf16 v[70:73], v[168:171], v[210:213], v[70:73]
	v_mfma_f32_16x16x32_bf16 v[66:69], v[176:179], v[210:213], v[66:69]
	v_mfma_f32_16x16x32_bf16 v[110:113], v[172:175], v[188:191], v[110:113]
	v_mfma_f32_16x16x32_bf16 v[106:109], v[180:183], v[188:191], v[106:109]
	v_mfma_f32_16x16x32_bf16 v[94:97], v[172:175], v[196:199], v[94:97]
	v_mfma_f32_16x16x32_bf16 v[90:93], v[180:183], v[196:199], v[90:93]
	v_mfma_f32_16x16x32_bf16 v[78:81], v[172:175], v[206:209], v[78:81]
	v_mfma_f32_16x16x32_bf16 v[74:77], v[180:183], v[206:209], v[74:77]
	v_mfma_f32_16x16x32_bf16 v[70:73], v[172:175], v[214:217], v[70:73]
	v_mfma_f32_16x16x32_bf16 v[66:69], v[180:183], v[214:217], v[66:69]
	s_setprio 0
	s_barrier
	s_mov_b32 m0, s31
	v_lshl_add_u64 v[218:219], s[46:47], 0, v[134:135]
	s_add_u32 s42, s46, 0x20000
	ds_read_b128 v[184:187], v148 offset:16384
	ds_read_b128 v[188:191], v148 offset:17408
	ds_read_b128 v[192:195], v148 offset:18432
	ds_read_b128 v[196:199], v148 offset:19456
	ds_read_b128 v[200:203], v148 offset:20480
	ds_read_b128 v[206:209], v148 offset:21504
	ds_read_b128 v[210:213], v148 offset:22528
	ds_read_b128 v[214:217], v148 offset:23552
	global_load_lds_dwordx4 v[218:219], off
	v_lshl_add_u64 v[220:221], s[46:47], 0, v[130:131]
	s_mov_b32 m0, s33
	s_addc_u32 s43, s47, 0
	global_load_lds_dwordx4 v[220:221], off
	v_lshl_add_u64 v[222:223], s[42:43], 0, v[134:135]
	s_mov_b32 m0, s34
	v_lshl_add_u64 v[224:225], s[48:49], 0, v[132:133]
	global_load_lds_dwordx4 v[222:223], off
	v_lshl_add_u64 v[222:223], s[42:43], 0, v[130:131]
	s_mov_b32 m0, s35
	s_nop 0
	global_load_lds_dwordx4 v[222:223], off
	v_lshl_add_u64 v[222:223], s[48:49], 0, v[136:137]
	s_mov_b32 m0, s2
	s_nop 0
	global_load_lds_dwordx4 v[222:223], off
	s_mov_b32 m0, s3
	s_nop 0
	global_load_lds_dwordx4 v[224:225], off
	s_waitcnt vmcnt(8)
	s_waitcnt lgkmcnt(0)
	s_barrier
	s_setprio 1
	s_waitcnt lgkmcnt(0)
	v_mfma_f32_16x16x32_bf16 v[62:65], v[152:155], v[184:187], v[62:65]
	v_mfma_f32_16x16x32_bf16 v[58:61], v[160:163], v[184:187], v[58:61]
	v_mfma_f32_16x16x32_bf16 v[54:57], v[152:155], v[192:195], v[54:57]
	v_mfma_f32_16x16x32_bf16 v[50:53], v[160:163], v[192:195], v[50:53]
	v_mfma_f32_16x16x32_bf16 v[38:41], v[152:155], v[200:203], v[38:41]
	v_mfma_f32_16x16x32_bf16 v[34:37], v[160:163], v[200:203], v[34:37]
	v_mfma_f32_16x16x32_bf16 v[22:25], v[152:155], v[210:213], v[22:25]
	v_mfma_f32_16x16x32_bf16 v[18:21], v[160:163], v[210:213], v[18:21]
	v_mfma_f32_16x16x32_bf16 v[62:65], v[156:159], v[188:191], v[62:65]
	v_mfma_f32_16x16x32_bf16 v[58:61], v[164:167], v[188:191], v[58:61]
	v_mfma_f32_16x16x32_bf16 v[54:57], v[156:159], v[196:199], v[54:57]
	v_mfma_f32_16x16x32_bf16 v[50:53], v[164:167], v[196:199], v[50:53]
	v_mfma_f32_16x16x32_bf16 v[38:41], v[156:159], v[206:209], v[38:41]
	v_mfma_f32_16x16x32_bf16 v[34:37], v[164:167], v[206:209], v[34:37]
	v_mfma_f32_16x16x32_bf16 v[22:25], v[156:159], v[214:217], v[22:25]
	v_mfma_f32_16x16x32_bf16 v[18:21], v[164:167], v[214:217], v[18:21]
	s_setprio 0
	s_setprio 1
	v_mfma_f32_16x16x32_bf16 v[46:49], v[168:171], v[184:187], v[46:49]
	v_mfma_f32_16x16x32_bf16 v[42:45], v[176:179], v[184:187], v[42:45]
	v_mfma_f32_16x16x32_bf16 v[30:33], v[168:171], v[192:195], v[30:33]
	v_mfma_f32_16x16x32_bf16 v[26:29], v[176:179], v[192:195], v[26:29]
	v_mfma_f32_16x16x32_bf16 v[14:17], v[168:171], v[200:203], v[14:17]
	v_mfma_f32_16x16x32_bf16 v[10:13], v[176:179], v[200:203], v[10:13]
	v_mfma_f32_16x16x32_bf16 v[6:9], v[168:171], v[210:213], v[6:9]
	v_mfma_f32_16x16x32_bf16 v[2:5], v[176:179], v[210:213], v[2:5]
	v_mfma_f32_16x16x32_bf16 v[46:49], v[172:175], v[188:191], v[46:49]
	v_mfma_f32_16x16x32_bf16 v[42:45], v[180:183], v[188:191], v[42:45]
	v_mfma_f32_16x16x32_bf16 v[30:33], v[172:175], v[196:199], v[30:33]
	v_mfma_f32_16x16x32_bf16 v[26:29], v[180:183], v[196:199], v[26:29]
	v_mfma_f32_16x16x32_bf16 v[14:17], v[172:175], v[206:209], v[14:17]
	v_mfma_f32_16x16x32_bf16 v[10:13], v[180:183], v[206:209], v[10:13]
	v_mfma_f32_16x16x32_bf16 v[6:9], v[172:175], v[214:217], v[6:9]
	v_mfma_f32_16x16x32_bf16 v[2:5], v[180:183], v[214:217], v[2:5]
	s_setprio 0
	s_barrier
	ds_read_b128 v[152:155], v149
	ds_read_b128 v[156:159], v149 offset:1024
	ds_read_b128 v[160:163], v149 offset:2048
	ds_read_b128 v[164:167], v149 offset:3072
	ds_read_b128 v[168:171], v150
	ds_read_b128 v[172:175], v150 offset:1024
	ds_read_b128 v[176:179], v150 offset:2048
	ds_read_b128 v[180:183], v150 offset:3072
	s_add_u32 s42, s48, 0x20000
	s_addc_u32 s43, s49, 0
	s_mov_b32 m0, s16
	v_lshl_add_u64 v[226:227], s[42:43], 0, v[136:137]
	ds_read_b128 v[184:187], v148 offset:32768
	ds_read_b128 v[188:191], v148 offset:33792
	ds_read_b128 v[192:195], v148 offset:34816
	ds_read_b128 v[196:199], v148 offset:35840
	ds_read_b128 v[200:203], v148 offset:36864
	ds_read_b128 v[206:209], v148 offset:37888
	ds_read_b128 v[210:213], v148 offset:38912
	ds_read_b128 v[214:217], v148 offset:39936
	global_load_lds_dwordx4 v[226:227], off
	v_lshl_add_u64 v[226:227], s[42:43], 0, v[132:133]
	s_mov_b32 m0, s17
	s_nop 0
	global_load_lds_dwordx4 v[226:227], off
	s_waitcnt vmcnt(8)
	s_waitcnt lgkmcnt(0)
	s_barrier
	s_setprio 1
	s_waitcnt lgkmcnt(0)
	v_mfma_f32_16x16x32_bf16 v[126:129], v[152:155], v[184:187], v[126:129]
	v_mfma_f32_16x16x32_bf16 v[122:125], v[160:163], v[184:187], v[122:125]
	v_mfma_f32_16x16x32_bf16 v[118:121], v[152:155], v[192:195], v[118:121]
	v_mfma_f32_16x16x32_bf16 v[114:117], v[160:163], v[192:195], v[114:117]
	v_mfma_f32_16x16x32_bf16 v[102:105], v[152:155], v[200:203], v[102:105]
	v_mfma_f32_16x16x32_bf16 v[98:101], v[160:163], v[200:203], v[98:101]
	v_mfma_f32_16x16x32_bf16 v[86:89], v[152:155], v[210:213], v[86:89]
	v_mfma_f32_16x16x32_bf16 v[82:85], v[160:163], v[210:213], v[82:85]
	v_mfma_f32_16x16x32_bf16 v[126:129], v[156:159], v[188:191], v[126:129]
	v_mfma_f32_16x16x32_bf16 v[122:125], v[164:167], v[188:191], v[122:125]
	v_mfma_f32_16x16x32_bf16 v[118:121], v[156:159], v[196:199], v[118:121]
	v_mfma_f32_16x16x32_bf16 v[114:117], v[164:167], v[196:199], v[114:117]
	v_mfma_f32_16x16x32_bf16 v[102:105], v[156:159], v[206:209], v[102:105]
	v_mfma_f32_16x16x32_bf16 v[98:101], v[164:167], v[206:209], v[98:101]
	v_mfma_f32_16x16x32_bf16 v[86:89], v[156:159], v[214:217], v[86:89]
	v_mfma_f32_16x16x32_bf16 v[82:85], v[164:167], v[214:217], v[82:85]
	s_setprio 0
	s_setprio 1
	v_mfma_f32_16x16x32_bf16 v[110:113], v[168:171], v[184:187], v[110:113]
	v_mfma_f32_16x16x32_bf16 v[106:109], v[176:179], v[184:187], v[106:109]
	v_mfma_f32_16x16x32_bf16 v[94:97], v[168:171], v[192:195], v[94:97]
	v_mfma_f32_16x16x32_bf16 v[90:93], v[176:179], v[192:195], v[90:93]
	v_mfma_f32_16x16x32_bf16 v[78:81], v[168:171], v[200:203], v[78:81]
	v_mfma_f32_16x16x32_bf16 v[74:77], v[176:179], v[200:203], v[74:77]
	v_mfma_f32_16x16x32_bf16 v[70:73], v[168:171], v[210:213], v[70:73]
	v_mfma_f32_16x16x32_bf16 v[66:69], v[176:179], v[210:213], v[66:69]
	v_mfma_f32_16x16x32_bf16 v[110:113], v[172:175], v[188:191], v[110:113]
	v_mfma_f32_16x16x32_bf16 v[106:109], v[180:183], v[188:191], v[106:109]
	v_mfma_f32_16x16x32_bf16 v[94:97], v[172:175], v[196:199], v[94:97]
	v_mfma_f32_16x16x32_bf16 v[90:93], v[180:183], v[196:199], v[90:93]
	v_mfma_f32_16x16x32_bf16 v[78:81], v[172:175], v[206:209], v[78:81]
	v_mfma_f32_16x16x32_bf16 v[74:77], v[180:183], v[206:209], v[74:77]
	v_mfma_f32_16x16x32_bf16 v[70:73], v[172:175], v[214:217], v[70:73]
	v_mfma_f32_16x16x32_bf16 v[66:69], v[180:183], v[214:217], v[66:69]
	s_setprio 0
	s_barrier
	s_mov_b32 m0, s62
	v_lshl_add_u64 v[218:219], v[218:219], 0, s[10:11]
	s_add_u32 s42, s46, 0x20080
	ds_read_b128 v[184:187], v148 offset:49152
	ds_read_b128 v[188:191], v148 offset:50176
	ds_read_b128 v[192:195], v148 offset:51200
	ds_read_b128 v[196:199], v148 offset:52224
	ds_read_b128 v[200:203], v148 offset:53248
	ds_read_b128 v[206:209], v148 offset:54272
	ds_read_b128 v[210:213], v148 offset:55296
	ds_read_b128 v[214:217], v148 offset:56320
	global_load_lds_dwordx4 v[218:219], off
	v_lshl_add_u64 v[218:219], v[220:221], 0, s[10:11]
	s_mov_b32 m0, s63
	s_addc_u32 s43, s47, 0
	global_load_lds_dwordx4 v[218:219], off
	v_lshl_add_u64 v[218:219], s[42:43], 0, v[134:135]
	s_mov_b32 m0, s64
	s_nop 0
	global_load_lds_dwordx4 v[218:219], off
	v_lshl_add_u64 v[218:219], s[42:43], 0, v[130:131]
	s_mov_b32 m0, s65
	s_nop 0
	global_load_lds_dwordx4 v[218:219], off
	v_lshl_add_u64 v[218:219], v[222:223], 0, s[10:11]
	s_mov_b32 m0, s25
	s_nop 0
	global_load_lds_dwordx4 v[218:219], off
	v_lshl_add_u64 v[218:219], v[224:225], 0, s[10:11]
	s_mov_b32 m0, s28
	s_nop 0
	global_load_lds_dwordx4 v[218:219], off
	s_waitcnt vmcnt(8)
	s_waitcnt lgkmcnt(0)
	s_barrier
	s_setprio 1
	s_waitcnt lgkmcnt(0)
	v_mfma_f32_16x16x32_bf16 v[62:65], v[152:155], v[184:187], v[62:65]
	v_mfma_f32_16x16x32_bf16 v[58:61], v[160:163], v[184:187], v[58:61]
	v_mfma_f32_16x16x32_bf16 v[54:57], v[152:155], v[192:195], v[54:57]
	v_mfma_f32_16x16x32_bf16 v[50:53], v[160:163], v[192:195], v[50:53]
	v_mfma_f32_16x16x32_bf16 v[38:41], v[152:155], v[200:203], v[38:41]
	v_mfma_f32_16x16x32_bf16 v[34:37], v[160:163], v[200:203], v[34:37]
	v_mfma_f32_16x16x32_bf16 v[22:25], v[152:155], v[210:213], v[22:25]
	v_mfma_f32_16x16x32_bf16 v[18:21], v[160:163], v[210:213], v[18:21]
	v_mfma_f32_16x16x32_bf16 v[62:65], v[156:159], v[188:191], v[62:65]
	v_mfma_f32_16x16x32_bf16 v[58:61], v[164:167], v[188:191], v[58:61]
	v_mfma_f32_16x16x32_bf16 v[54:57], v[156:159], v[196:199], v[54:57]
	v_mfma_f32_16x16x32_bf16 v[50:53], v[164:167], v[196:199], v[50:53]
	v_mfma_f32_16x16x32_bf16 v[38:41], v[156:159], v[206:209], v[38:41]
	v_mfma_f32_16x16x32_bf16 v[34:37], v[164:167], v[206:209], v[34:37]
	v_mfma_f32_16x16x32_bf16 v[22:25], v[156:159], v[214:217], v[22:25]
	v_mfma_f32_16x16x32_bf16 v[18:21], v[164:167], v[214:217], v[18:21]
	s_setprio 0
	s_setprio 1
	v_mfma_f32_16x16x32_bf16 v[46:49], v[168:171], v[184:187], v[46:49]
	v_mfma_f32_16x16x32_bf16 v[42:45], v[176:179], v[184:187], v[42:45]
	v_mfma_f32_16x16x32_bf16 v[30:33], v[168:171], v[192:195], v[30:33]
	v_mfma_f32_16x16x32_bf16 v[26:29], v[176:179], v[192:195], v[26:29]
	v_mfma_f32_16x16x32_bf16 v[14:17], v[168:171], v[200:203], v[14:17]
	v_mfma_f32_16x16x32_bf16 v[10:13], v[176:179], v[200:203], v[10:13]
	v_mfma_f32_16x16x32_bf16 v[6:9], v[168:171], v[210:213], v[6:9]
	v_mfma_f32_16x16x32_bf16 v[2:5], v[176:179], v[210:213], v[2:5]
	v_mfma_f32_16x16x32_bf16 v[46:49], v[172:175], v[188:191], v[46:49]
	v_mfma_f32_16x16x32_bf16 v[42:45], v[180:183], v[188:191], v[42:45]
	v_mfma_f32_16x16x32_bf16 v[30:33], v[172:175], v[196:199], v[30:33]
	v_mfma_f32_16x16x32_bf16 v[26:29], v[180:183], v[196:199], v[26:29]
	v_mfma_f32_16x16x32_bf16 v[14:17], v[172:175], v[206:209], v[14:17]
	v_mfma_f32_16x16x32_bf16 v[10:13], v[180:183], v[206:209], v[10:13]
	v_mfma_f32_16x16x32_bf16 v[6:9], v[172:175], v[214:217], v[6:9]
	v_mfma_f32_16x16x32_bf16 v[2:5], v[180:183], v[214:217], v[2:5]
	s_setprio 0
	s_barrier
	s_add_i32 s68, s68, 2
	s_cmp_gt_u32 s68, 5
	s_mov_b64 s[42:43], s[44:45]
	s_cbranch_scc0 .LBB0_384
	s_and_b64 vcc, exec, s[12:13]
	s_cbranch_vccz .LBB0_387
	s_barrier

.LBB0_406:
	s_lshl_b32 s74, s12, 7
	s_add_i32 s12, s12, 2
	v_cndmask_b32_e64 v138, 0, 1, s[66:67]
	s_lshl_b64 s[66:67], s[12:13], 7
	s_and_b64 s[68:69], s[64:65], exec
	s_cselect_b32 s66, 0, s66
	s_cselect_b32 s67, 0, s67
	s_add_u32 s70, s8, s66
	s_addc_u32 s71, s9, s67
	s_lshl_b64 s[66:67], s[12:13], 12
	s_add_u32 s12, s48, s66
	s_addc_u32 s66, s49, s67
	s_and_b64 s[64:65], s[64:65], exec
	s_cselect_b32 s73, s14, s66
	s_cselect_b32 s72, s15, s12
	s_add_u32 s76, s10, s74
	s_addc_u32 s77, s11, 0
	s_add_i32 s91, s62, s16
	s_add_i32 m0, s17, 0xc000
	s_add_i32 s92, s17, 0xe000
	s_add_i32 s88, s91, 0x2000
	s_add_u32 s74, s72, 0x10000
	ds_read_b128 v[146:149], v141
	ds_read_b128 v[150:153], v141 offset:1024
	ds_read_b128 v[154:157], v141 offset:2048
	ds_read_b128 v[158:161], v141 offset:3072
	ds_read_b128 v[162:165], v143
	ds_read_b128 v[166:169], v143 offset:1024
	ds_read_b128 v[170:173], v143 offset:2048
	ds_read_b128 v[174:177], v143 offset:3072
	s_addc_u32 s75, s73, 0
	s_add_i32 s90, s63, s16
	s_add_i32 s89, s90, 0x2000
	s_add_i32 s87, 0, 0x18000
	s_add_i32 s86, 0, 0x1c000
	s_add_u32 s68, s70, 0x10000
	s_addc_u32 s69, s71, 0
	s_add_u32 s64, s72, 0x1000
	s_addc_u32 s65, s73, 0
	s_add_i32 s85, s87, s16
	s_add_i32 s83, s85, 0x2000
	s_add_u32 s66, s72, 0x11000
	s_addc_u32 s67, s73, 0
	s_add_i32 s84, s86, s16
	s_add_i32 s12, s84, 0x2000
	v_cmp_ne_u32_e32 vcc, 1, v138
	v_lshl_add_u64 v[202:203], s[76:77], 0, v[136:137]
	v_lshl_add_u64 v[202:203], v[202:203], 0, s[36:37]
	ds_read_b128 v[178:181], v144
	ds_read_b128 v[182:185], v144 offset:1024
	ds_read_b128 v[186:189], v144 offset:2048
	ds_read_b128 v[190:193], v144 offset:3072
	ds_read_b128 v[194:197], v144 offset:4096
	ds_read_b128 v[198:201], v144 offset:5120
	ds_read_b128 v[206:209], v144 offset:6144
	ds_read_b128 v[210:213], v144 offset:7168
	global_load_lds_dwordx4 v[202:203], off
	v_lshl_add_u64 v[202:203], s[76:77], 0, v[132:133]
	v_lshl_add_u64 v[202:203], v[202:203], 0, s[36:37]
	s_mov_b32 m0, s92
	s_nop 0
	global_load_lds_dwordx4 v[202:203], off
	s_waitcnt vmcnt(8)
	s_waitcnt lgkmcnt(0)
	s_barrier
	s_setprio 1
	s_waitcnt lgkmcnt(0)
	v_mfma_f32_16x16x32_bf16 v[126:129], v[146:149], v[178:181], v[126:129]
	v_mfma_f32_16x16x32_bf16 v[122:125], v[154:157], v[178:181], v[122:125]
	v_mfma_f32_16x16x32_bf16 v[118:121], v[146:149], v[186:189], v[118:121]
	v_mfma_f32_16x16x32_bf16 v[110:113], v[154:157], v[186:189], v[110:113]
	v_mfma_f32_16x16x32_bf16 v[102:105], v[146:149], v[194:197], v[102:105]
	v_mfma_f32_16x16x32_bf16 v[98:101], v[154:157], v[194:197], v[98:101]
	v_mfma_f32_16x16x32_bf16 v[86:89], v[146:149], v[206:209], v[86:89]
	v_mfma_f32_16x16x32_bf16 v[82:85], v[154:157], v[206:209], v[82:85]
	v_mfma_f32_16x16x32_bf16 v[126:129], v[150:153], v[182:185], v[126:129]
	v_mfma_f32_16x16x32_bf16 v[122:125], v[158:161], v[182:185], v[122:125]
	v_mfma_f32_16x16x32_bf16 v[118:121], v[150:153], v[190:193], v[118:121]
	v_mfma_f32_16x16x32_bf16 v[110:113], v[158:161], v[190:193], v[110:113]
	v_mfma_f32_16x16x32_bf16 v[102:105], v[150:153], v[198:201], v[102:105]
	v_mfma_f32_16x16x32_bf16 v[98:101], v[158:161], v[198:201], v[98:101]
	v_mfma_f32_16x16x32_bf16 v[86:89], v[150:153], v[210:213], v[86:89]
	v_mfma_f32_16x16x32_bf16 v[82:85], v[158:161], v[210:213], v[82:85]
	s_setprio 0
	s_setprio 1
	v_mfma_f32_16x16x32_bf16 v[114:117], v[162:165], v[178:181], v[114:117]
	v_mfma_f32_16x16x32_bf16 v[106:109], v[170:173], v[178:181], v[106:109]
	v_mfma_f32_16x16x32_bf16 v[94:97], v[162:165], v[186:189], v[94:97]
	v_mfma_f32_16x16x32_bf16 v[90:93], v[170:173], v[186:189], v[90:93]
	v_mfma_f32_16x16x32_bf16 v[78:81], v[162:165], v[194:197], v[78:81]
	v_mfma_f32_16x16x32_bf16 v[74:77], v[170:173], v[194:197], v[74:77]
	v_mfma_f32_16x16x32_bf16 v[70:73], v[162:165], v[206:209], v[70:73]
	v_mfma_f32_16x16x32_bf16 v[66:69], v[170:173], v[206:209], v[66:69]
	v_mfma_f32_16x16x32_bf16 v[114:117], v[166:169], v[182:185], v[114:117]
	v_mfma_f32_16x16x32_bf16 v[106:109], v[174:177], v[182:185], v[106:109]
	v_mfma_f32_16x16x32_bf16 v[94:97], v[166:169], v[190:193], v[94:97]
	v_mfma_f32_16x16x32_bf16 v[90:93], v[174:177], v[190:193], v[90:93]
	v_mfma_f32_16x16x32_bf16 v[78:81], v[166:169], v[198:201], v[78:81]
	v_mfma_f32_16x16x32_bf16 v[74:77], v[174:177], v[198:201], v[74:77]
	v_mfma_f32_16x16x32_bf16 v[70:73], v[166:169], v[210:213], v[70:73]
	v_mfma_f32_16x16x32_bf16 v[66:69], v[174:177], v[210:213], v[66:69]
	s_setprio 0
	s_barrier
	s_mov_b32 m0, s91
	v_lshl_add_u64 v[202:203], s[72:73], 0, v[134:135]
	ds_read_b128 v[178:181], v144 offset:16384
	ds_read_b128 v[182:185], v144 offset:17408
	ds_read_b128 v[186:189], v144 offset:18432
	ds_read_b128 v[190:193], v144 offset:19456
	ds_read_b128 v[194:197], v144 offset:20480
	ds_read_b128 v[198:201], v144 offset:21504
	ds_read_b128 v[206:209], v144 offset:22528
	ds_read_b128 v[210:213], v144 offset:23552
	global_load_lds_dwordx4 v[202:203], off
	v_lshl_add_u64 v[202:203], s[72:73], 0, v[130:131]
	s_mov_b32 m0, s88
	v_lshl_add_u64 v[214:215], s[70:71], 0, v[132:133]
	global_load_lds_dwordx4 v[202:203], off
	v_lshl_add_u64 v[202:203], s[74:75], 0, v[134:135]
	s_mov_b32 m0, s90
	s_nop 0
	global_load_lds_dwordx4 v[202:203], off
	v_lshl_add_u64 v[202:203], s[74:75], 0, v[130:131]
	s_mov_b32 m0, s89
	s_nop 0
	global_load_lds_dwordx4 v[202:203], off
	v_lshl_add_u64 v[202:203], s[70:71], 0, v[136:137]
	s_mov_b32 m0, s17
	s_nop 0
	global_load_lds_dwordx4 v[202:203], off
	s_mov_b32 m0, s18
	s_nop 0
	global_load_lds_dwordx4 v[214:215], off
	s_waitcnt vmcnt(8)
	s_waitcnt lgkmcnt(0)
	s_barrier
	s_setprio 1
	s_waitcnt lgkmcnt(0)
	v_mfma_f32_16x16x32_bf16 v[62:65], v[146:149], v[178:181], v[62:65]
	v_mfma_f32_16x16x32_bf16 v[58:61], v[154:157], v[178:181], v[58:61]
	v_mfma_f32_16x16x32_bf16 v[54:57], v[146:149], v[186:189], v[54:57]
	v_mfma_f32_16x16x32_bf16 v[50:53], v[154:157], v[186:189], v[50:53]
	v_mfma_f32_16x16x32_bf16 v[38:41], v[146:149], v[194:197], v[38:41]
	v_mfma_f32_16x16x32_bf16 v[34:37], v[154:157], v[194:197], v[34:37]
	v_mfma_f32_16x16x32_bf16 v[22:25], v[146:149], v[206:209], v[22:25]
	v_mfma_f32_16x16x32_bf16 v[18:21], v[154:157], v[206:209], v[18:21]
	v_mfma_f32_16x16x32_bf16 v[62:65], v[150:153], v[182:185], v[62:65]
	v_mfma_f32_16x16x32_bf16 v[58:61], v[158:161], v[182:185], v[58:61]
	v_mfma_f32_16x16x32_bf16 v[54:57], v[150:153], v[190:193], v[54:57]
	v_mfma_f32_16x16x32_bf16 v[50:53], v[158:161], v[190:193], v[50:53]
	v_mfma_f32_16x16x32_bf16 v[38:41], v[150:153], v[198:201], v[38:41]
	v_mfma_f32_16x16x32_bf16 v[34:37], v[158:161], v[198:201], v[34:37]
	v_mfma_f32_16x16x32_bf16 v[22:25], v[150:153], v[210:213], v[22:25]
	v_mfma_f32_16x16x32_bf16 v[18:21], v[158:161], v[210:213], v[18:21]
	s_setprio 0
	s_setprio 1
	v_mfma_f32_16x16x32_bf16 v[46:49], v[162:165], v[178:181], v[46:49]
	v_mfma_f32_16x16x32_bf16 v[42:45], v[170:173], v[178:181], v[42:45]
	v_mfma_f32_16x16x32_bf16 v[30:33], v[162:165], v[186:189], v[30:33]
	v_mfma_f32_16x16x32_bf16 v[26:29], v[170:173], v[186:189], v[26:29]
	v_mfma_f32_16x16x32_bf16 v[14:17], v[162:165], v[194:197], v[14:17]
	v_mfma_f32_16x16x32_bf16 v[10:13], v[170:173], v[194:197], v[10:13]
	v_mfma_f32_16x16x32_bf16 v[6:9], v[162:165], v[206:209], v[6:9]
	v_mfma_f32_16x16x32_bf16 v[2:5], v[170:173], v[206:209], v[2:5]
	v_mfma_f32_16x16x32_bf16 v[46:49], v[166:169], v[182:185], v[46:49]
	v_mfma_f32_16x16x32_bf16 v[42:45], v[174:177], v[182:185], v[42:45]
	v_mfma_f32_16x16x32_bf16 v[30:33], v[166:169], v[190:193], v[30:33]
	v_mfma_f32_16x16x32_bf16 v[26:29], v[174:177], v[190:193], v[26:29]
	v_mfma_f32_16x16x32_bf16 v[14:17], v[166:169], v[198:201], v[14:17]
	v_mfma_f32_16x16x32_bf16 v[10:13], v[174:177], v[198:201], v[10:13]
	v_mfma_f32_16x16x32_bf16 v[6:9], v[166:169], v[210:213], v[6:9]
	v_mfma_f32_16x16x32_bf16 v[2:5], v[174:177], v[210:213], v[2:5]
	s_setprio 0
	s_barrier
	v_add_u32_e32 v138, s87, v140
	ds_read_b128 v[146:149], v138
	ds_read_b128 v[150:153], v138 offset:1024
	ds_read_b128 v[154:157], v138 offset:2048
	ds_read_b128 v[158:161], v138 offset:3072
	v_add_u32_e32 v138, s86, v140
	ds_read_b128 v[162:165], v138
	ds_read_b128 v[166:169], v138 offset:1024
	ds_read_b128 v[170:173], v138 offset:2048
	ds_read_b128 v[174:177], v138 offset:3072
	s_mov_b32 m0, s19
	v_lshl_add_u64 v[216:217], s[68:69], 0, v[136:137]
	ds_read_b128 v[178:181], v144 offset:32768
	ds_read_b128 v[182:185], v144 offset:33792
	ds_read_b128 v[186:189], v144 offset:34816
	ds_read_b128 v[190:193], v144 offset:35840
	ds_read_b128 v[194:197], v144 offset:36864
	ds_read_b128 v[198:201], v144 offset:37888
	ds_read_b128 v[206:209], v144 offset:38912
	ds_read_b128 v[210:213], v144 offset:39936
	global_load_lds_dwordx4 v[216:217], off
	v_lshl_add_u64 v[216:217], s[68:69], 0, v[132:133]
	s_mov_b32 m0, s24
	s_nop 0
	global_load_lds_dwordx4 v[216:217], off
	s_waitcnt vmcnt(8)
	s_waitcnt lgkmcnt(0)
	s_barrier
	s_setprio 1
	s_waitcnt lgkmcnt(0)
	v_mfma_f32_16x16x32_bf16 v[126:129], v[146:149], v[178:181], v[126:129]
	v_mfma_f32_16x16x32_bf16 v[122:125], v[154:157], v[178:181], v[122:125]
	v_mfma_f32_16x16x32_bf16 v[118:121], v[146:149], v[186:189], v[118:121]
	v_mfma_f32_16x16x32_bf16 v[110:113], v[154:157], v[186:189], v[110:113]
	v_mfma_f32_16x16x32_bf16 v[102:105], v[146:149], v[194:197], v[102:105]
	v_mfma_f32_16x16x32_bf16 v[98:101], v[154:157], v[194:197], v[98:101]
	v_mfma_f32_16x16x32_bf16 v[86:89], v[146:149], v[206:209], v[86:89]
	v_mfma_f32_16x16x32_bf16 v[82:85], v[154:157], v[206:209], v[82:85]
	v_mfma_f32_16x16x32_bf16 v[126:129], v[150:153], v[182:185], v[126:129]
	v_mfma_f32_16x16x32_bf16 v[122:125], v[158:161], v[182:185], v[122:125]
	v_mfma_f32_16x16x32_bf16 v[118:121], v[150:153], v[190:193], v[118:121]
	v_mfma_f32_16x16x32_bf16 v[110:113], v[158:161], v[190:193], v[110:113]
	v_mfma_f32_16x16x32_bf16 v[102:105], v[150:153], v[198:201], v[102:105]
	v_mfma_f32_16x16x32_bf16 v[98:101], v[158:161], v[198:201], v[98:101]
	v_mfma_f32_16x16x32_bf16 v[86:89], v[150:153], v[210:213], v[86:89]
	v_mfma_f32_16x16x32_bf16 v[82:85], v[158:161], v[210:213], v[82:85]
	s_setprio 0
	s_setprio 1
	v_mfma_f32_16x16x32_bf16 v[114:117], v[162:165], v[178:181], v[114:117]
	v_mfma_f32_16x16x32_bf16 v[106:109], v[170:173], v[178:181], v[106:109]
	v_mfma_f32_16x16x32_bf16 v[94:97], v[162:165], v[186:189], v[94:97]
	v_mfma_f32_16x16x32_bf16 v[90:93], v[170:173], v[186:189], v[90:93]
	v_mfma_f32_16x16x32_bf16 v[78:81], v[162:165], v[194:197], v[78:81]
	v_mfma_f32_16x16x32_bf16 v[74:77], v[170:173], v[194:197], v[74:77]
	v_mfma_f32_16x16x32_bf16 v[70:73], v[162:165], v[206:209], v[70:73]
	v_mfma_f32_16x16x32_bf16 v[66:69], v[170:173], v[206:209], v[66:69]
	v_mfma_f32_16x16x32_bf16 v[114:117], v[166:169], v[182:185], v[114:117]
	v_mfma_f32_16x16x32_bf16 v[106:109], v[174:177], v[182:185], v[106:109]
	v_mfma_f32_16x16x32_bf16 v[94:97], v[166:169], v[190:193], v[94:97]
	v_mfma_f32_16x16x32_bf16 v[90:93], v[174:177], v[190:193], v[90:93]
	v_mfma_f32_16x16x32_bf16 v[78:81], v[166:169], v[198:201], v[78:81]
	v_mfma_f32_16x16x32_bf16 v[74:77], v[174:177], v[198:201], v[74:77]
	v_mfma_f32_16x16x32_bf16 v[70:73], v[166:169], v[210:213], v[70:73]
	v_mfma_f32_16x16x32_bf16 v[66:69], v[174:177], v[210:213], v[66:69]
	s_setprio 0
	s_barrier
	s_mov_b32 m0, s85
	v_lshl_add_u64 v[216:217], s[64:65], 0, v[134:135]
	ds_read_b128 v[178:181], v144 offset:49152
	ds_read_b128 v[182:185], v144 offset:50176
	ds_read_b128 v[186:189], v144 offset:51200
	ds_read_b128 v[190:193], v144 offset:52224
	ds_read_b128 v[194:197], v144 offset:53248
	ds_read_b128 v[198:201], v144 offset:54272
	ds_read_b128 v[206:209], v144 offset:55296
	ds_read_b128 v[210:213], v144 offset:56320
	global_load_lds_dwordx4 v[216:217], off
	v_lshl_add_u64 v[216:217], s[64:65], 0, v[130:131]
	s_mov_b32 m0, s83
	v_lshl_add_u64 v[202:203], v[202:203], 0, s[36:37]
	global_load_lds_dwordx4 v[216:217], off
	v_lshl_add_u64 v[216:217], s[66:67], 0, v[134:135]
	s_mov_b32 m0, s84
	s_nop 0
	global_load_lds_dwordx4 v[216:217], off
	v_lshl_add_u64 v[216:217], s[66:67], 0, v[130:131]
	s_mov_b32 m0, s12
	s_nop 0
	global_load_lds_dwordx4 v[216:217], off
	s_mov_b32 m0, s31
	s_nop 0
	global_load_lds_dwordx4 v[202:203], off
	v_lshl_add_u64 v[202:203], v[214:215], 0, s[36:37]
	s_mov_b32 m0, s33
	s_nop 0
	global_load_lds_dwordx4 v[202:203], off
	s_waitcnt vmcnt(8)
	s_waitcnt lgkmcnt(0)
	s_barrier
	s_setprio 1
	s_waitcnt lgkmcnt(0)
	v_mfma_f32_16x16x32_bf16 v[62:65], v[146:149], v[178:181], v[62:65]
	v_mfma_f32_16x16x32_bf16 v[58:61], v[154:157], v[178:181], v[58:61]
	v_mfma_f32_16x16x32_bf16 v[54:57], v[146:149], v[186:189], v[54:57]
	v_mfma_f32_16x16x32_bf16 v[50:53], v[154:157], v[186:189], v[50:53]
	v_mfma_f32_16x16x32_bf16 v[38:41], v[146:149], v[194:197], v[38:41]
	v_mfma_f32_16x16x32_bf16 v[34:37], v[154:157], v[194:197], v[34:37]
	v_mfma_f32_16x16x32_bf16 v[22:25], v[146:149], v[206:209], v[22:25]
	v_mfma_f32_16x16x32_bf16 v[18:21], v[154:157], v[206:209], v[18:21]
	v_mfma_f32_16x16x32_bf16 v[62:65], v[150:153], v[182:185], v[62:65]
	v_mfma_f32_16x16x32_bf16 v[58:61], v[158:161], v[182:185], v[58:61]
	v_mfma_f32_16x16x32_bf16 v[54:57], v[150:153], v[190:193], v[54:57]
	v_mfma_f32_16x16x32_bf16 v[50:53], v[158:161], v[190:193], v[50:53]
	v_mfma_f32_16x16x32_bf16 v[38:41], v[150:153], v[198:201], v[38:41]
	v_mfma_f32_16x16x32_bf16 v[34:37], v[158:161], v[198:201], v[34:37]
	v_mfma_f32_16x16x32_bf16 v[22:25], v[150:153], v[210:213], v[22:25]
	v_mfma_f32_16x16x32_bf16 v[18:21], v[158:161], v[210:213], v[18:21]
	s_setprio 0
	s_setprio 1
	v_mfma_f32_16x16x32_bf16 v[46:49], v[162:165], v[178:181], v[46:49]
	v_mfma_f32_16x16x32_bf16 v[42:45], v[170:173], v[178:181], v[42:45]
	v_mfma_f32_16x16x32_bf16 v[30:33], v[162:165], v[186:189], v[30:33]
	v_mfma_f32_16x16x32_bf16 v[26:29], v[170:173], v[186:189], v[26:29]
	v_mfma_f32_16x16x32_bf16 v[14:17], v[162:165], v[194:197], v[14:17]
	v_mfma_f32_16x16x32_bf16 v[10:13], v[170:173], v[194:197], v[10:13]
	v_mfma_f32_16x16x32_bf16 v[6:9], v[162:165], v[206:209], v[6:9]
	v_mfma_f32_16x16x32_bf16 v[2:5], v[170:173], v[206:209], v[2:5]
	v_mfma_f32_16x16x32_bf16 v[46:49], v[166:169], v[182:185], v[46:49]
	v_mfma_f32_16x16x32_bf16 v[42:45], v[174:177], v[182:185], v[42:45]
	v_mfma_f32_16x16x32_bf16 v[30:33], v[166:169], v[190:193], v[30:33]
	v_mfma_f32_16x16x32_bf16 v[26:29], v[174:177], v[190:193], v[26:29]
	v_mfma_f32_16x16x32_bf16 v[14:17], v[166:169], v[198:201], v[14:17]
	v_mfma_f32_16x16x32_bf16 v[10:13], v[174:177], v[198:201], v[10:13]
	v_mfma_f32_16x16x32_bf16 v[6:9], v[166:169], v[210:213], v[6:9]
	v_mfma_f32_16x16x32_bf16 v[2:5], v[174:177], v[210:213], v[2:5]
	s_setprio 0
	s_barrier
	s_mov_b64 s[66:67], 0
	s_mov_b64 s[64:65], -1
	s_mov_b32 s12, 2
	s_cbranch_vccz .LBB0_406
	s_and_b64 vcc, exec, s[22:23]
	s_cbranch_vccz .LBB0_409
	s_barrier

.LBB0_413:
	s_cmp_gt_i32 s59, 4
	s_cselect_b64 s[6:7], -1, 0
	s_and_b64 s[2:3], s[4:5], s[6:7]
	s_andn2_b64 vcc, exec, s[2:3]
	s_cbranch_vccnz .LBB0_467
	s_waitcnt vmcnt(0) lgkmcnt(0)
	s_barrier
	s_mov_b64 s[2:3], exec
	v_readlane_b32 s4, v249, 5
	v_readlane_b32 s5, v249, 6
	v_readlane_b32 s10, v249, 4
	s_and_b64 s[4:5], s[2:3], s[4:5]
	s_mov_b64 exec, s[4:5]
	s_cbranch_execz .Lgb_3_done
	v_mov_b32_e32 v1, 0x27e00
	ds_read2_b32 v[2:3], v1 offset1:1
	s_lshl_b32 s10, s10, 8
	s_add_u32 s8, s56, s10
	s_addc_u32 s9, s57, 0
	v_mov_b32_e32 v4, 0x1000
	v_mov_b32_e32 v5, 1
	global_atomic_add v6, v4, v5, s[8:9] offset:1024 sc0
	buffer_inv sc1
	s_waitcnt lgkmcnt(0)
	v_mul_lo_u32 v7, v2, 4
	s_waitcnt vmcnt(1)
	v_add_u32_e32 v6, 1, v6
	v_cmp_eq_u32_e32 vcc, v6, v7
	s_cbranch_vccz .Lgb_3_wait
	buffer_wbl2 sc1
	s_waitcnt vmcnt(0)
	v_mov_b32_e32 v4, 0x3000
	global_atomic_add v8, v4, v5, s[56:57] offset:1024 sc0
	v_mul_lo_u32 v7, v3, 4
	s_waitcnt vmcnt(0)
	v_add_u32_e32 v8, 1, v8
	v_cmp_eq_u32_e32 vcc, v8, v7
	s_cbranch_vccz .Lgb_3_wait
	v_mov_b32_e32 v9, 0x2400
	global_atomic_add v9, v5, s[56:57] offset:0
	global_atomic_add v9, v5, s[56:57] offset:256
	global_atomic_add v9, v5, s[56:57] offset:512
	global_atomic_add v9, v5, s[56:57] offset:768
	global_atomic_add v9, v5, s[56:57] offset:1024
	global_atomic_add v9, v5, s[56:57] offset:1280
	global_atomic_add v9, v5, s[56:57] offset:1536
	global_atomic_add v9, v5, s[56:57] offset:1792
	global_atomic_add v9, v5, s[56:57] offset:2048
	global_atomic_add v9, v5, s[56:57] offset:2304
	global_atomic_add v9, v5, s[56:57] offset:2560
	global_atomic_add v9, v5, s[56:57] offset:2816
	global_atomic_add v9, v5, s[56:57] offset:3072
	global_atomic_add v9, v5, s[56:57] offset:3328
	global_atomic_add v9, v5, s[56:57] offset:3584
	global_atomic_add v9, v5, s[56:57] offset:3840
	s_waitcnt vmcnt(0)
	s_branch .Lgb_3_done

.Lgb_3_spin:
	global_load_dword v8, v9, s[8:9] offset:1024 sc1
	s_waitcnt vmcnt(0)
	v_cmp_ne_u32_e32 vcc, 3, v8
	s_cbranch_vccnz .Lgb_3_done
	s_sleep 1
	s_add_u32 s10, s10, 1
	s_cmp_lt_u32 s10, 0x40000
	s_cbranch_scc1 .Lgb_3_spin

.LBB0_477:
	ds_read_b128 v[148:151], v144
	ds_read_b128 v[152:155], v144 offset:1024
	ds_read_b128 v[156:159], v144 offset:2048
	ds_read_b128 v[160:163], v144 offset:3072
	ds_read_b128 v[164:167], v145
	ds_read_b128 v[168:171], v145 offset:1024
	ds_read_b128 v[172:175], v145 offset:2048
	ds_read_b128 v[176:179], v145 offset:3072
	s_add_u32 s38, s36, 0xfffe0080
	s_addc_u32 s39, s37, -1
	s_cmp_eq_u32 s69, 4
	s_cselect_b32 s43, s63, s39
	s_cselect_b32 s42, s64, s38
	s_cselect_b32 s39, s65, s68
	s_cselect_b32 s38, s66, s67
	v_lshl_add_u64 v[214:215], s[36:37], 0, v[138:139]
	s_add_i32 m0, s19, 0xc000
	ds_read_b128 v[180:183], v146
	ds_read_b128 v[184:187], v146 offset:1024
	ds_read_b128 v[188:191], v146 offset:2048
	ds_read_b128 v[192:195], v146 offset:3072
	ds_read_b128 v[196:199], v146 offset:4096
	ds_read_b128 v[200:203], v146 offset:5120
	ds_read_b128 v[206:209], v146 offset:6144
	ds_read_b128 v[210:213], v146 offset:7168
	global_load_lds_dwordx4 v[214:215], off
	v_lshl_add_u64 v[214:215], s[36:37], 0, v[140:141]
	s_add_i32 m0, s19, 0xe000
	s_nop 0
	global_load_lds_dwordx4 v[214:215], off
	s_waitcnt vmcnt(8)
	s_waitcnt lgkmcnt(0)
	s_barrier
	s_setprio 1
	s_waitcnt lgkmcnt(0)
	v_mfma_f32_16x16x32_bf16 v[126:129], v[148:151], v[180:183], v[126:129]
	v_mfma_f32_16x16x32_bf16 v[122:125], v[156:159], v[180:183], v[122:125]
	v_mfma_f32_16x16x32_bf16 v[118:121], v[148:151], v[188:191], v[118:121]
	v_mfma_f32_16x16x32_bf16 v[114:117], v[156:159], v[188:191], v[114:117]
	v_mfma_f32_16x16x32_bf16 v[102:105], v[148:151], v[196:199], v[102:105]
	v_mfma_f32_16x16x32_bf16 v[98:101], v[156:159], v[196:199], v[98:101]
	v_mfma_f32_16x16x32_bf16 v[86:89], v[148:151], v[206:209], v[86:89]
	v_mfma_f32_16x16x32_bf16 v[82:85], v[156:159], v[206:209], v[82:85]
	v_mfma_f32_16x16x32_bf16 v[126:129], v[152:155], v[184:187], v[126:129]
	v_mfma_f32_16x16x32_bf16 v[122:125], v[160:163], v[184:187], v[122:125]
	v_mfma_f32_16x16x32_bf16 v[118:121], v[152:155], v[192:195], v[118:121]
	v_mfma_f32_16x16x32_bf16 v[114:117], v[160:163], v[192:195], v[114:117]
	v_mfma_f32_16x16x32_bf16 v[102:105], v[152:155], v[200:203], v[102:105]
	v_mfma_f32_16x16x32_bf16 v[98:101], v[160:163], v[200:203], v[98:101]
	v_mfma_f32_16x16x32_bf16 v[86:89], v[152:155], v[210:213], v[86:89]
	v_mfma_f32_16x16x32_bf16 v[82:85], v[160:163], v[210:213], v[82:85]
	s_setprio 0
	s_setprio 1
	v_mfma_f32_16x16x32_bf16 v[110:113], v[164:167], v[180:183], v[110:113]
	v_mfma_f32_16x16x32_bf16 v[106:109], v[172:175], v[180:183], v[106:109]
	v_mfma_f32_16x16x32_bf16 v[94:97], v[164:167], v[188:191], v[94:97]
	v_mfma_f32_16x16x32_bf16 v[90:93], v[172:175], v[188:191], v[90:93]
	v_mfma_f32_16x16x32_bf16 v[78:81], v[164:167], v[196:199], v[78:81]
	v_mfma_f32_16x16x32_bf16 v[74:77], v[172:175], v[196:199], v[74:77]
	v_mfma_f32_16x16x32_bf16 v[70:73], v[164:167], v[206:209], v[70:73]
	v_mfma_f32_16x16x32_bf16 v[66:69], v[172:175], v[206:209], v[66:69]
	v_mfma_f32_16x16x32_bf16 v[110:113], v[168:171], v[184:187], v[110:113]
	v_mfma_f32_16x16x32_bf16 v[106:109], v[176:179], v[184:187], v[106:109]
	v_mfma_f32_16x16x32_bf16 v[94:97], v[168:171], v[192:195], v[94:97]
	v_mfma_f32_16x16x32_bf16 v[90:93], v[176:179], v[192:195], v[90:93]
	v_mfma_f32_16x16x32_bf16 v[78:81], v[168:171], v[200:203], v[78:81]
	v_mfma_f32_16x16x32_bf16 v[74:77], v[176:179], v[200:203], v[74:77]
	v_mfma_f32_16x16x32_bf16 v[70:73], v[168:171], v[210:213], v[70:73]
	v_mfma_f32_16x16x32_bf16 v[66:69], v[176:179], v[210:213], v[66:69]
	s_setprio 0
	s_barrier
	s_add_i32 s70, s35, s18
	v_lshl_add_u64 v[214:215], s[38:39], 0, v[134:135]
	s_mov_b32 m0, s70
	ds_read_b128 v[180:183], v146 offset:16384
	ds_read_b128 v[184:187], v146 offset:17408
	ds_read_b128 v[188:191], v146 offset:18432
	ds_read_b128 v[192:195], v146 offset:19456
	ds_read_b128 v[196:199], v146 offset:20480
	ds_read_b128 v[200:203], v146 offset:21504
	ds_read_b128 v[206:209], v146 offset:22528
	ds_read_b128 v[210:213], v146 offset:23552
	global_load_lds_dwordx4 v[214:215], off
	s_add_i32 m0, s70, 0x2000
	s_add_u32 s70, s38, 0x200000
	v_lshl_add_u64 v[216:217], s[38:39], 0, v[130:131]
	s_addc_u32 s71, s39, 0
	s_add_i32 s72, s44, s18
	global_load_lds_dwordx4 v[216:217], off
	v_lshl_add_u64 v[218:219], s[70:71], 0, v[134:135]
	s_mov_b32 m0, s72
	v_lshl_add_u64 v[220:221], s[42:43], 0, v[132:133]
	global_load_lds_dwordx4 v[218:219], off
	v_lshl_add_u64 v[218:219], s[70:71], 0, v[130:131]
	s_add_i32 m0, s72, 0x2000
	s_nop 0
	global_load_lds_dwordx4 v[218:219], off
	v_lshl_add_u64 v[218:219], s[42:43], 0, v[136:137]
	s_mov_b32 m0, s19
	s_nop 0
	global_load_lds_dwordx4 v[218:219], off
	s_mov_b32 m0, s24
	s_nop 0
	global_load_lds_dwordx4 v[220:221], off
	s_waitcnt vmcnt(8)
	s_waitcnt lgkmcnt(0)
	s_barrier
	s_setprio 1
	s_waitcnt lgkmcnt(0)
	v_mfma_f32_16x16x32_bf16 v[62:65], v[148:151], v[180:183], v[62:65]
	v_mfma_f32_16x16x32_bf16 v[58:61], v[156:159], v[180:183], v[58:61]
	v_mfma_f32_16x16x32_bf16 v[54:57], v[148:151], v[188:191], v[54:57]
	v_mfma_f32_16x16x32_bf16 v[50:53], v[156:159], v[188:191], v[50:53]
	v_mfma_f32_16x16x32_bf16 v[38:41], v[148:151], v[196:199], v[38:41]
	v_mfma_f32_16x16x32_bf16 v[34:37], v[156:159], v[196:199], v[34:37]
	v_mfma_f32_16x16x32_bf16 v[22:25], v[148:151], v[206:209], v[22:25]
	v_mfma_f32_16x16x32_bf16 v[18:21], v[156:159], v[206:209], v[18:21]
	v_mfma_f32_16x16x32_bf16 v[62:65], v[152:155], v[184:187], v[62:65]
	v_mfma_f32_16x16x32_bf16 v[58:61], v[160:163], v[184:187], v[58:61]
	v_mfma_f32_16x16x32_bf16 v[54:57], v[152:155], v[192:195], v[54:57]
	v_mfma_f32_16x16x32_bf16 v[50:53], v[160:163], v[192:195], v[50:53]
	v_mfma_f32_16x16x32_bf16 v[38:41], v[152:155], v[200:203], v[38:41]
	v_mfma_f32_16x16x32_bf16 v[34:37], v[160:163], v[200:203], v[34:37]
	v_mfma_f32_16x16x32_bf16 v[22:25], v[152:155], v[210:213], v[22:25]
	v_mfma_f32_16x16x32_bf16 v[18:21], v[160:163], v[210:213], v[18:21]
	s_setprio 0
	s_setprio 1
	v_mfma_f32_16x16x32_bf16 v[46:49], v[164:167], v[180:183], v[46:49]
	v_mfma_f32_16x16x32_bf16 v[42:45], v[172:175], v[180:183], v[42:45]
	v_mfma_f32_16x16x32_bf16 v[30:33], v[164:167], v[188:191], v[30:33]
	v_mfma_f32_16x16x32_bf16 v[26:29], v[172:175], v[188:191], v[26:29]
	v_mfma_f32_16x16x32_bf16 v[14:17], v[164:167], v[196:199], v[14:17]
	v_mfma_f32_16x16x32_bf16 v[10:13], v[172:175], v[196:199], v[10:13]
	v_mfma_f32_16x16x32_bf16 v[6:9], v[164:167], v[206:209], v[6:9]
	v_mfma_f32_16x16x32_bf16 v[2:5], v[172:175], v[206:209], v[2:5]
	v_mfma_f32_16x16x32_bf16 v[46:49], v[168:171], v[184:187], v[46:49]
	v_mfma_f32_16x16x32_bf16 v[42:45], v[176:179], v[184:187], v[42:45]
	v_mfma_f32_16x16x32_bf16 v[30:33], v[168:171], v[192:195], v[30:33]
	v_mfma_f32_16x16x32_bf16 v[26:29], v[176:179], v[192:195], v[26:29]
	v_mfma_f32_16x16x32_bf16 v[14:17], v[168:171], v[200:203], v[14:17]
	v_mfma_f32_16x16x32_bf16 v[10:13], v[176:179], v[200:203], v[10:13]
	v_mfma_f32_16x16x32_bf16 v[6:9], v[168:171], v[210:213], v[6:9]
	v_mfma_f32_16x16x32_bf16 v[2:5], v[176:179], v[210:213], v[2:5]
	s_setprio 0
	s_barrier
	s_add_i32 s70, 0, 0x18000
	v_add_u32_e32 v147, s70, v143
	s_add_i32 s71, 0, 0x1c000
	ds_read_b128 v[148:151], v147
	ds_read_b128 v[152:155], v147 offset:1024
	ds_read_b128 v[156:159], v147 offset:2048
	ds_read_b128 v[160:163], v147 offset:3072
	v_add_u32_e32 v147, s71, v143
	ds_read_b128 v[164:167], v147
	ds_read_b128 v[168:171], v147 offset:1024
	ds_read_b128 v[172:175], v147 offset:2048
	ds_read_b128 v[176:179], v147 offset:3072
	s_add_u32 s42, s42, 0x20000
	s_addc_u32 s43, s43, 0
	s_mov_b32 m0, s25
	v_lshl_add_u64 v[222:223], s[42:43], 0, v[136:137]
	ds_read_b128 v[180:183], v146 offset:32768
	ds_read_b128 v[184:187], v146 offset:33792
	ds_read_b128 v[188:191], v146 offset:34816
	ds_read_b128 v[192:195], v146 offset:35840
	ds_read_b128 v[196:199], v146 offset:36864
	ds_read_b128 v[200:203], v146 offset:37888
	ds_read_b128 v[206:209], v146 offset:38912
	ds_read_b128 v[210:213], v146 offset:39936
	global_load_lds_dwordx4 v[222:223], off
	v_lshl_add_u64 v[222:223], s[42:43], 0, v[132:133]
	s_mov_b32 m0, s28
	s_nop 0
	global_load_lds_dwordx4 v[222:223], off
	s_waitcnt vmcnt(8)
	s_waitcnt lgkmcnt(0)
	s_barrier
	s_setprio 1
	s_waitcnt lgkmcnt(0)
	v_mfma_f32_16x16x32_bf16 v[126:129], v[148:151], v[180:183], v[126:129]
	v_mfma_f32_16x16x32_bf16 v[122:125], v[156:159], v[180:183], v[122:125]
	v_mfma_f32_16x16x32_bf16 v[118:121], v[148:151], v[188:191], v[118:121]
	v_mfma_f32_16x16x32_bf16 v[114:117], v[156:159], v[188:191], v[114:117]
	v_mfma_f32_16x16x32_bf16 v[102:105], v[148:151], v[196:199], v[102:105]
	v_mfma_f32_16x16x32_bf16 v[98:101], v[156:159], v[196:199], v[98:101]
	v_mfma_f32_16x16x32_bf16 v[86:89], v[148:151], v[206:209], v[86:89]
	v_mfma_f32_16x16x32_bf16 v[82:85], v[156:159], v[206:209], v[82:85]
	v_mfma_f32_16x16x32_bf16 v[126:129], v[152:155], v[184:187], v[126:129]
	v_mfma_f32_16x16x32_bf16 v[122:125], v[160:163], v[184:187], v[122:125]
	v_mfma_f32_16x16x32_bf16 v[118:121], v[152:155], v[192:195], v[118:121]
	v_mfma_f32_16x16x32_bf16 v[114:117], v[160:163], v[192:195], v[114:117]
	v_mfma_f32_16x16x32_bf16 v[102:105], v[152:155], v[200:203], v[102:105]
	v_mfma_f32_16x16x32_bf16 v[98:101], v[160:163], v[200:203], v[98:101]
	v_mfma_f32_16x16x32_bf16 v[86:89], v[152:155], v[210:213], v[86:89]
	v_mfma_f32_16x16x32_bf16 v[82:85], v[160:163], v[210:213], v[82:85]
	s_setprio 0
	s_setprio 1
	v_mfma_f32_16x16x32_bf16 v[110:113], v[164:167], v[180:183], v[110:113]
	v_mfma_f32_16x16x32_bf16 v[106:109], v[172:175], v[180:183], v[106:109]
	v_mfma_f32_16x16x32_bf16 v[94:97], v[164:167], v[188:191], v[94:97]
	v_mfma_f32_16x16x32_bf16 v[90:93], v[172:175], v[188:191], v[90:93]
	v_mfma_f32_16x16x32_bf16 v[78:81], v[164:167], v[196:199], v[78:81]
	v_mfma_f32_16x16x32_bf16 v[74:77], v[172:175], v[196:199], v[74:77]
	v_mfma_f32_16x16x32_bf16 v[70:73], v[164:167], v[206:209], v[70:73]
	v_mfma_f32_16x16x32_bf16 v[66:69], v[172:175], v[206:209], v[66:69]
	v_mfma_f32_16x16x32_bf16 v[110:113], v[168:171], v[184:187], v[110:113]
	v_mfma_f32_16x16x32_bf16 v[106:109], v[176:179], v[184:187], v[106:109]
	v_mfma_f32_16x16x32_bf16 v[94:97], v[168:171], v[192:195], v[94:97]
	v_mfma_f32_16x16x32_bf16 v[90:93], v[176:179], v[192:195], v[90:93]
	v_mfma_f32_16x16x32_bf16 v[78:81], v[168:171], v[200:203], v[78:81]
	v_mfma_f32_16x16x32_bf16 v[74:77], v[176:179], v[200:203], v[74:77]
	v_mfma_f32_16x16x32_bf16 v[70:73], v[168:171], v[210:213], v[70:73]
	v_mfma_f32_16x16x32_bf16 v[66:69], v[176:179], v[210:213], v[66:69]
	s_setprio 0
	s_barrier
	s_add_i32 s42, s70, s18
	v_lshl_add_u64 v[214:215], v[214:215], 0, s[8:9]
	s_mov_b32 m0, s42
	ds_read_b128 v[180:183], v146 offset:49152
	ds_read_b128 v[184:187], v146 offset:50176
	ds_read_b128 v[188:191], v146 offset:51200
	ds_read_b128 v[192:195], v146 offset:52224
	ds_read_b128 v[196:199], v146 offset:53248
	ds_read_b128 v[200:203], v146 offset:54272
	ds_read_b128 v[206:209], v146 offset:55296
	ds_read_b128 v[210:213], v146 offset:56320
	global_load_lds_dwordx4 v[214:215], off
	s_add_i32 m0, s42, 0x2000
	s_add_u32 s38, s38, 0x200080
	v_lshl_add_u64 v[214:215], v[216:217], 0, s[8:9]
	s_addc_u32 s39, s39, 0
	s_add_i32 s42, s71, s18
	global_load_lds_dwordx4 v[214:215], off
	v_lshl_add_u64 v[214:215], s[38:39], 0, v[134:135]
	s_mov_b32 m0, s42
	s_nop 0
	global_load_lds_dwordx4 v[214:215], off
	v_lshl_add_u64 v[214:215], s[38:39], 0, v[130:131]
	s_add_i32 m0, s42, 0x2000
	s_nop 0
	global_load_lds_dwordx4 v[214:215], off
	v_lshl_add_u64 v[214:215], v[218:219], 0, s[8:9]
	s_mov_b32 m0, s33
	s_nop 0
	global_load_lds_dwordx4 v[214:215], off
	v_lshl_add_u64 v[214:215], v[220:221], 0, s[8:9]
	s_mov_b32 m0, s34
	s_nop 0
	global_load_lds_dwordx4 v[214:215], off
	s_waitcnt vmcnt(8)
	s_waitcnt lgkmcnt(0)
	s_barrier
	s_setprio 1
	s_waitcnt lgkmcnt(0)
	v_mfma_f32_16x16x32_bf16 v[62:65], v[148:151], v[180:183], v[62:65]
	v_mfma_f32_16x16x32_bf16 v[58:61], v[156:159], v[180:183], v[58:61]
	v_mfma_f32_16x16x32_bf16 v[54:57], v[148:151], v[188:191], v[54:57]
	v_mfma_f32_16x16x32_bf16 v[50:53], v[156:159], v[188:191], v[50:53]
	v_mfma_f32_16x16x32_bf16 v[38:41], v[148:151], v[196:199], v[38:41]
	v_mfma_f32_16x16x32_bf16 v[34:37], v[156:159], v[196:199], v[34:37]
	v_mfma_f32_16x16x32_bf16 v[22:25], v[148:151], v[206:209], v[22:25]
	v_mfma_f32_16x16x32_bf16 v[18:21], v[156:159], v[206:209], v[18:21]
	v_mfma_f32_16x16x32_bf16 v[62:65], v[152:155], v[184:187], v[62:65]
	v_mfma_f32_16x16x32_bf16 v[58:61], v[160:163], v[184:187], v[58:61]
	v_mfma_f32_16x16x32_bf16 v[54:57], v[152:155], v[192:195], v[54:57]
	v_mfma_f32_16x16x32_bf16 v[50:53], v[160:163], v[192:195], v[50:53]
	v_mfma_f32_16x16x32_bf16 v[38:41], v[152:155], v[200:203], v[38:41]
	v_mfma_f32_16x16x32_bf16 v[34:37], v[160:163], v[200:203], v[34:37]
	v_mfma_f32_16x16x32_bf16 v[22:25], v[152:155], v[210:213], v[22:25]
	v_mfma_f32_16x16x32_bf16 v[18:21], v[160:163], v[210:213], v[18:21]
	s_setprio 0
	s_setprio 1
	v_mfma_f32_16x16x32_bf16 v[46:49], v[164:167], v[180:183], v[46:49]
	v_mfma_f32_16x16x32_bf16 v[42:45], v[172:175], v[180:183], v[42:45]
	v_mfma_f32_16x16x32_bf16 v[30:33], v[164:167], v[188:191], v[30:33]
	v_mfma_f32_16x16x32_bf16 v[26:29], v[172:175], v[188:191], v[26:29]
	v_mfma_f32_16x16x32_bf16 v[14:17], v[164:167], v[196:199], v[14:17]
	v_mfma_f32_16x16x32_bf16 v[10:13], v[172:175], v[196:199], v[10:13]
	v_mfma_f32_16x16x32_bf16 v[6:9], v[164:167], v[206:209], v[6:9]
	v_mfma_f32_16x16x32_bf16 v[2:5], v[172:175], v[206:209], v[2:5]
	v_mfma_f32_16x16x32_bf16 v[46:49], v[168:171], v[184:187], v[46:49]
	v_mfma_f32_16x16x32_bf16 v[42:45], v[176:179], v[184:187], v[42:45]
	v_mfma_f32_16x16x32_bf16 v[30:33], v[168:171], v[192:195], v[30:33]
	v_mfma_f32_16x16x32_bf16 v[26:29], v[176:179], v[192:195], v[26:29]
	v_mfma_f32_16x16x32_bf16 v[14:17], v[168:171], v[200:203], v[14:17]
	v_mfma_f32_16x16x32_bf16 v[10:13], v[176:179], v[200:203], v[10:13]
	v_mfma_f32_16x16x32_bf16 v[6:9], v[168:171], v[210:213], v[6:9]
	v_mfma_f32_16x16x32_bf16 v[2:5], v[176:179], v[210:213], v[2:5]
	s_setprio 0
	s_barrier
	s_add_i32 s69, s69, 2
	s_add_u32 s36, s36, 0x100
	s_addc_u32 s37, s37, 0
	s_add_u32 s67, s67, 0x100
	s_addc_u32 s68, s68, 0
	s_cmp_gt_u32 s69, 5
	s_cbranch_scc0 .LBB0_477
	s_and_b64 vcc, exec, s[10:11]
	s_cbranch_vccz .LBB0_480
	s_barrier

.LBB0_484:
	s_cmp_gt_i32 s59, 5
	s_cselect_b64 s[6:7], -1, 0
	s_and_b64 s[2:3], s[4:5], s[6:7]
	s_andn2_b64 vcc, exec, s[2:3]
	s_cbranch_vccnz .LBB0_538
	s_waitcnt vmcnt(0) lgkmcnt(0)
	s_barrier
	s_mov_b64 s[2:3], exec
	v_readlane_b32 s4, v249, 5
	v_readlane_b32 s5, v249, 6
	v_readlane_b32 s10, v249, 4
	s_and_b64 s[4:5], s[2:3], s[4:5]
	s_mov_b64 exec, s[4:5]
	s_cbranch_execz .Lgb_4_done
	v_mov_b32_e32 v1, 0x27e00
	ds_read2_b32 v[2:3], v1 offset1:1
	s_lshl_b32 s10, s10, 8
	s_add_u32 s8, s56, s10
	s_addc_u32 s9, s57, 0
	v_mov_b32_e32 v4, 0x1000
	v_mov_b32_e32 v5, 1
	global_atomic_add v6, v4, v5, s[8:9] offset:1024 sc0
	buffer_inv sc1
	s_waitcnt lgkmcnt(0)
	v_mul_lo_u32 v7, v2, 5
	s_waitcnt vmcnt(1)
	v_add_u32_e32 v6, 1, v6
	v_cmp_eq_u32_e32 vcc, v6, v7
	s_cbranch_vccz .Lgb_4_wait
	buffer_wbl2 sc1
	s_waitcnt vmcnt(0)
	v_mov_b32_e32 v4, 0x3000
	global_atomic_add v8, v4, v5, s[56:57] offset:1024 sc0
	v_mul_lo_u32 v7, v3, 5
	s_waitcnt vmcnt(0)
	v_add_u32_e32 v8, 1, v8
	v_cmp_eq_u32_e32 vcc, v8, v7
	s_cbranch_vccz .Lgb_4_wait
	v_mov_b32_e32 v9, 0x2400
	global_atomic_add v9, v5, s[56:57] offset:0
	global_atomic_add v9, v5, s[56:57] offset:256
	global_atomic_add v9, v5, s[56:57] offset:512
	global_atomic_add v9, v5, s[56:57] offset:768
	global_atomic_add v9, v5, s[56:57] offset:1024
	global_atomic_add v9, v5, s[56:57] offset:1280
	global_atomic_add v9, v5, s[56:57] offset:1536
	global_atomic_add v9, v5, s[56:57] offset:1792
	global_atomic_add v9, v5, s[56:57] offset:2048
	global_atomic_add v9, v5, s[56:57] offset:2304
	global_atomic_add v9, v5, s[56:57] offset:2560
	global_atomic_add v9, v5, s[56:57] offset:2816
	global_atomic_add v9, v5, s[56:57] offset:3072
	global_atomic_add v9, v5, s[56:57] offset:3328
	global_atomic_add v9, v5, s[56:57] offset:3584
	global_atomic_add v9, v5, s[56:57] offset:3840
	s_waitcnt vmcnt(0)
	s_branch .Lgb_4_done

.Lgb_4_spin:
	global_load_dword v8, v9, s[8:9] offset:1024 sc1
	s_waitcnt vmcnt(0)
	v_cmp_ne_u32_e32 vcc, 4, v8
	s_cbranch_vccnz .Lgb_4_done
	s_sleep 1
	s_add_u32 s10, s10, 1
	s_cmp_lt_u32 s10, 0x40000
	s_cbranch_scc1 .Lgb_4_spin

.LBB0_566:
	s_waitcnt vmcnt(0)
	ds_read_b128 v[114:117], v190
	ds_read_b128 v[118:121], v190 offset:1024
	ds_read_b128 v[122:125], v190 offset:2048
	ds_read_b128 v[126:129], v190 offset:3072
	ds_read_b128 v[146:149], v191
	ds_read_b128 v[150:153], v191 offset:1024
	ds_read_b128 v[154:157], v191 offset:2048
	ds_read_b128 v[158:161], v191 offset:3072
	s_add_i32 s82, s63, 2
	s_add_u32 s78, s76, 0xfffc0080
	s_addc_u32 s79, s77, -1
	s_cmp_eq_u32 s45, s63
	s_cselect_b32 s81, s31, s79
	s_cselect_b32 s80, s33, s78
	s_cselect_b32 s79, s34, s62
	s_cselect_b32 s78, s39, s47
	v_lshl_add_u64 v[186:187], s[76:77], 0, v[180:181]
	s_add_i32 m0, s87, 0xc000
	ds_read_b128 v[162:165], v192
	ds_read_b128 v[166:169], v192 offset:1024
	ds_read_b128 v[194:197], v192 offset:2048
	ds_read_b128 v[198:201], v192 offset:3072
	ds_read_b128 v[206:209], v192 offset:4096
	ds_read_b128 v[210:213], v192 offset:5120
	ds_read_b128 v[214:217], v192 offset:6144
	ds_read_b128 v[218:221], v192 offset:7168
	global_load_lds_dwordx4 v[186:187], off
	v_lshl_add_u64 v[186:187], s[76:77], 0, v[182:183]
	s_add_i32 m0, s87, 0xe000
	s_nop 0
	global_load_lds_dwordx4 v[186:187], off
	s_waitcnt vmcnt(8)
	s_waitcnt lgkmcnt(0)
	s_barrier
	s_setprio 1
	s_waitcnt lgkmcnt(0)
	v_mfma_f32_16x16x32_bf16 v[142:145], v[114:117], v[162:165], v[142:145]
	v_mfma_f32_16x16x32_bf16 v[138:141], v[122:125], v[162:165], v[138:141]
	v_mfma_f32_16x16x32_bf16 v[110:113], v[114:117], v[194:197], v[110:113]
	v_mfma_f32_16x16x32_bf16 v[106:109], v[122:125], v[194:197], v[106:109]
	v_mfma_f32_16x16x32_bf16 v[98:101], v[114:117], v[206:209], v[98:101]
	v_mfma_f32_16x16x32_bf16 v[90:93], v[122:125], v[206:209], v[90:93]
	v_mfma_f32_16x16x32_bf16 v[82:85], v[114:117], v[214:217], v[82:85]
	v_mfma_f32_16x16x32_bf16 v[74:77], v[122:125], v[214:217], v[74:77]
	v_mfma_f32_16x16x32_bf16 v[142:145], v[118:121], v[166:169], v[142:145]
	v_mfma_f32_16x16x32_bf16 v[138:141], v[126:129], v[166:169], v[138:141]
	v_mfma_f32_16x16x32_bf16 v[110:113], v[118:121], v[198:201], v[110:113]
	v_mfma_f32_16x16x32_bf16 v[106:109], v[126:129], v[198:201], v[106:109]
	v_mfma_f32_16x16x32_bf16 v[98:101], v[118:121], v[210:213], v[98:101]
	v_mfma_f32_16x16x32_bf16 v[90:93], v[126:129], v[210:213], v[90:93]
	v_mfma_f32_16x16x32_bf16 v[82:85], v[118:121], v[218:221], v[82:85]
	v_mfma_f32_16x16x32_bf16 v[74:77], v[126:129], v[218:221], v[74:77]
	s_setprio 0
	s_setprio 1
	v_mfma_f32_16x16x32_bf16 v[134:137], v[146:149], v[162:165], v[134:137]
	v_mfma_f32_16x16x32_bf16 v[130:133], v[154:157], v[162:165], v[130:133]
	v_mfma_f32_16x16x32_bf16 v[102:105], v[146:149], v[194:197], v[102:105]
	v_mfma_f32_16x16x32_bf16 v[94:97], v[154:157], v[194:197], v[94:97]
	v_mfma_f32_16x16x32_bf16 v[86:89], v[146:149], v[206:209], v[86:89]
	v_mfma_f32_16x16x32_bf16 v[78:81], v[154:157], v[206:209], v[78:81]
	v_mfma_f32_16x16x32_bf16 v[70:73], v[146:149], v[214:217], v[70:73]
	v_mfma_f32_16x16x32_bf16 v[66:69], v[154:157], v[214:217], v[66:69]
	v_mfma_f32_16x16x32_bf16 v[134:137], v[150:153], v[166:169], v[134:137]
	v_mfma_f32_16x16x32_bf16 v[130:133], v[158:161], v[166:169], v[130:133]
	v_mfma_f32_16x16x32_bf16 v[102:105], v[150:153], v[198:201], v[102:105]
	v_mfma_f32_16x16x32_bf16 v[94:97], v[158:161], v[198:201], v[94:97]
	v_mfma_f32_16x16x32_bf16 v[86:89], v[150:153], v[210:213], v[86:89]
	v_mfma_f32_16x16x32_bf16 v[78:81], v[158:161], v[210:213], v[78:81]
	v_mfma_f32_16x16x32_bf16 v[70:73], v[150:153], v[218:221], v[70:73]
	v_mfma_f32_16x16x32_bf16 v[66:69], v[158:161], v[218:221], v[66:69]
	s_setprio 0
	s_barrier
	s_add_i32 s63, s24, s86
	v_lshl_add_u64 v[186:187], s[78:79], 0, v[172:173]
	s_mov_b32 m0, s63
	ds_read_b128 v[162:165], v192 offset:16384
	ds_read_b128 v[166:169], v192 offset:17408
	ds_read_b128 v[194:197], v192 offset:18432
	ds_read_b128 v[198:201], v192 offset:19456
	ds_read_b128 v[206:209], v192 offset:20480
	ds_read_b128 v[210:213], v192 offset:21504
	ds_read_b128 v[214:217], v192 offset:22528
	ds_read_b128 v[218:221], v192 offset:23552
	global_load_lds_dwordx4 v[186:187], off
	s_add_i32 m0, s63, 0x2000
	s_add_u32 vcc_lo, s78, 0x40000
	v_lshl_add_u64 v[202:203], s[78:79], 0, v[176:177]
	s_addc_u32 vcc_hi, s79, 0
	s_add_i32 s63, s25, s86
	global_load_lds_dwordx4 v[202:203], off
	v_lshl_add_u64 v[222:223], vcc, 0, v[172:173]
	s_mov_b32 m0, s63
	v_lshl_add_u64 v[224:225], s[80:81], 0, v[174:175]
	global_load_lds_dwordx4 v[222:223], off
	v_lshl_add_u64 v[222:223], vcc, 0, v[176:177]
	s_add_i32 m0, s63, 0x2000
	s_nop 0
	global_load_lds_dwordx4 v[222:223], off
	v_lshl_add_u64 v[222:223], s[80:81], 0, v[170:171]
	s_mov_b32 m0, s87
	s_nop 0
	global_load_lds_dwordx4 v[222:223], off
	s_mov_b32 m0, s88
	s_nop 0
	global_load_lds_dwordx4 v[224:225], off
	s_waitcnt vmcnt(8)
	s_waitcnt lgkmcnt(0)
	s_barrier
	s_setprio 1
	s_waitcnt lgkmcnt(0)
	v_mfma_f32_16x16x32_bf16 v[62:65], v[114:117], v[162:165], v[62:65]
	v_mfma_f32_16x16x32_bf16 v[58:61], v[122:125], v[162:165], v[58:61]
	v_mfma_f32_16x16x32_bf16 v[50:53], v[114:117], v[194:197], v[50:53]
	v_mfma_f32_16x16x32_bf16 v[42:45], v[122:125], v[194:197], v[42:45]
	v_mfma_f32_16x16x32_bf16 v[34:37], v[114:117], v[206:209], v[34:37]
	v_mfma_f32_16x16x32_bf16 v[26:29], v[122:125], v[206:209], v[26:29]
	v_mfma_f32_16x16x32_bf16 v[18:21], v[114:117], v[214:217], v[18:21]
	v_mfma_f32_16x16x32_bf16 v[10:13], v[122:125], v[214:217], v[10:13]
	v_mfma_f32_16x16x32_bf16 v[62:65], v[118:121], v[166:169], v[62:65]
	v_mfma_f32_16x16x32_bf16 v[58:61], v[126:129], v[166:169], v[58:61]
	v_mfma_f32_16x16x32_bf16 v[50:53], v[118:121], v[198:201], v[50:53]
	v_mfma_f32_16x16x32_bf16 v[42:45], v[126:129], v[198:201], v[42:45]
	v_mfma_f32_16x16x32_bf16 v[34:37], v[118:121], v[210:213], v[34:37]
	v_mfma_f32_16x16x32_bf16 v[26:29], v[126:129], v[210:213], v[26:29]
	v_mfma_f32_16x16x32_bf16 v[18:21], v[118:121], v[218:221], v[18:21]
	v_mfma_f32_16x16x32_bf16 v[10:13], v[126:129], v[218:221], v[10:13]
	s_setprio 0
	s_setprio 1
	v_mfma_f32_16x16x32_bf16 v[54:57], v[146:149], v[162:165], v[54:57]
	v_mfma_f32_16x16x32_bf16 v[46:49], v[154:157], v[162:165], v[46:49]
	v_mfma_f32_16x16x32_bf16 v[38:41], v[146:149], v[194:197], v[38:41]
	v_mfma_f32_16x16x32_bf16 v[30:33], v[154:157], v[194:197], v[30:33]
	v_mfma_f32_16x16x32_bf16 v[22:25], v[146:149], v[206:209], v[22:25]
	v_mfma_f32_16x16x32_bf16 v[14:17], v[154:157], v[206:209], v[14:17]
	v_mfma_f32_16x16x32_bf16 v[6:9], v[146:149], v[214:217], v[6:9]
	v_mfma_f32_16x16x32_bf16 v[2:5], v[154:157], v[214:217], v[2:5]
	v_mfma_f32_16x16x32_bf16 v[54:57], v[150:153], v[166:169], v[54:57]
	v_mfma_f32_16x16x32_bf16 v[46:49], v[158:161], v[166:169], v[46:49]
	v_mfma_f32_16x16x32_bf16 v[38:41], v[150:153], v[198:201], v[38:41]
	v_mfma_f32_16x16x32_bf16 v[30:33], v[158:161], v[198:201], v[30:33]
	v_mfma_f32_16x16x32_bf16 v[22:25], v[150:153], v[210:213], v[22:25]
	v_mfma_f32_16x16x32_bf16 v[14:17], v[158:161], v[210:213], v[14:17]
	v_mfma_f32_16x16x32_bf16 v[6:9], v[150:153], v[218:221], v[6:9]
	v_mfma_f32_16x16x32_bf16 v[2:5], v[158:161], v[218:221], v[2:5]
	s_setprio 0
	s_barrier
	s_add_i32 s63, 0, 0x18000
	s_add_i32 s83, 0, 0x1c000
	v_add_u32_e32 v126, s63, v189
	v_add_u32_e32 v158, s83, v189
	ds_read_b128 v[114:117], v126
	ds_read_b128 v[118:121], v126 offset:1024
	ds_read_b128 v[122:125], v126 offset:2048
	ds_read_b128 v[126:129], v126 offset:3072
	ds_read_b128 v[146:149], v158
	ds_read_b128 v[150:153], v158 offset:1024
	ds_read_b128 v[154:157], v158 offset:2048
	ds_read_b128 v[158:161], v158 offset:3072
	s_add_u32 s80, s80, 0x40000
	s_addc_u32 s81, s81, 0
	s_mov_b32 m0, s89
	v_lshl_add_u64 v[226:227], s[80:81], 0, v[170:171]
	ds_read_b128 v[162:165], v192 offset:32768
	ds_read_b128 v[166:169], v192 offset:33792
	ds_read_b128 v[194:197], v192 offset:34816
	ds_read_b128 v[198:201], v192 offset:35840
	ds_read_b128 v[206:209], v192 offset:36864
	ds_read_b128 v[210:213], v192 offset:37888
	ds_read_b128 v[214:217], v192 offset:38912
	ds_read_b128 v[218:221], v192 offset:39936
	global_load_lds_dwordx4 v[226:227], off
	v_lshl_add_u64 v[226:227], s[80:81], 0, v[174:175]
	s_mov_b32 m0, s90
	s_nop 0
	global_load_lds_dwordx4 v[226:227], off
	s_waitcnt vmcnt(8)
	s_waitcnt lgkmcnt(0)
	s_barrier
	s_setprio 1
	s_waitcnt lgkmcnt(0)
	v_mfma_f32_16x16x32_bf16 v[142:145], v[114:117], v[162:165], v[142:145]
	v_mfma_f32_16x16x32_bf16 v[138:141], v[122:125], v[162:165], v[138:141]
	v_mfma_f32_16x16x32_bf16 v[110:113], v[114:117], v[194:197], v[110:113]
	v_mfma_f32_16x16x32_bf16 v[106:109], v[122:125], v[194:197], v[106:109]
	v_mfma_f32_16x16x32_bf16 v[98:101], v[114:117], v[206:209], v[98:101]
	v_mfma_f32_16x16x32_bf16 v[90:93], v[122:125], v[206:209], v[90:93]
	v_mfma_f32_16x16x32_bf16 v[82:85], v[114:117], v[214:217], v[82:85]
	v_mfma_f32_16x16x32_bf16 v[74:77], v[122:125], v[214:217], v[74:77]
	v_mfma_f32_16x16x32_bf16 v[142:145], v[118:121], v[166:169], v[142:145]
	v_mfma_f32_16x16x32_bf16 v[138:141], v[126:129], v[166:169], v[138:141]
	v_mfma_f32_16x16x32_bf16 v[110:113], v[118:121], v[198:201], v[110:113]
	v_mfma_f32_16x16x32_bf16 v[106:109], v[126:129], v[198:201], v[106:109]
	v_mfma_f32_16x16x32_bf16 v[98:101], v[118:121], v[210:213], v[98:101]
	v_mfma_f32_16x16x32_bf16 v[90:93], v[126:129], v[210:213], v[90:93]
	v_mfma_f32_16x16x32_bf16 v[82:85], v[118:121], v[218:221], v[82:85]
	v_mfma_f32_16x16x32_bf16 v[74:77], v[126:129], v[218:221], v[74:77]
	s_setprio 0
	s_setprio 1
	v_mfma_f32_16x16x32_bf16 v[134:137], v[146:149], v[162:165], v[134:137]
	v_mfma_f32_16x16x32_bf16 v[130:133], v[154:157], v[162:165], v[130:133]
	v_mfma_f32_16x16x32_bf16 v[102:105], v[146:149], v[194:197], v[102:105]
	v_mfma_f32_16x16x32_bf16 v[94:97], v[154:157], v[194:197], v[94:97]
	v_mfma_f32_16x16x32_bf16 v[86:89], v[146:149], v[206:209], v[86:89]
	v_mfma_f32_16x16x32_bf16 v[78:81], v[154:157], v[206:209], v[78:81]
	v_mfma_f32_16x16x32_bf16 v[70:73], v[146:149], v[214:217], v[70:73]
	v_mfma_f32_16x16x32_bf16 v[66:69], v[154:157], v[214:217], v[66:69]
	v_mfma_f32_16x16x32_bf16 v[134:137], v[150:153], v[166:169], v[134:137]
	v_mfma_f32_16x16x32_bf16 v[130:133], v[158:161], v[166:169], v[130:133]
	v_mfma_f32_16x16x32_bf16 v[102:105], v[150:153], v[198:201], v[102:105]
	v_mfma_f32_16x16x32_bf16 v[94:97], v[158:161], v[198:201], v[94:97]
	v_mfma_f32_16x16x32_bf16 v[86:89], v[150:153], v[210:213], v[86:89]
	v_mfma_f32_16x16x32_bf16 v[78:81], v[158:161], v[210:213], v[78:81]
	v_mfma_f32_16x16x32_bf16 v[70:73], v[150:153], v[218:221], v[70:73]
	v_mfma_f32_16x16x32_bf16 v[66:69], v[158:161], v[218:221], v[66:69]
	s_setprio 0
	s_barrier
	s_add_i32 s63, s63, s86
	v_lshl_add_u64 v[186:187], v[186:187], 0, s[22:23]
	s_mov_b32 m0, s63
	ds_read_b128 v[162:165], v192 offset:49152
	ds_read_b128 v[166:169], v192 offset:50176
	ds_read_b128 v[194:197], v192 offset:51200
	ds_read_b128 v[198:201], v192 offset:52224
	ds_read_b128 v[206:209], v192 offset:53248
	ds_read_b128 v[210:213], v192 offset:54272
	ds_read_b128 v[214:217], v192 offset:55296
	ds_read_b128 v[218:221], v192 offset:56320
	global_load_lds_dwordx4 v[186:187], off
	s_add_i32 m0, s63, 0x2000
	s_add_u32 s78, s78, 0x40080
	v_lshl_add_u64 v[186:187], v[202:203], 0, s[22:23]
	s_addc_u32 s79, s79, 0
	s_add_i32 s63, s83, s86
	global_load_lds_dwordx4 v[186:187], off
	v_lshl_add_u64 v[186:187], s[78:79], 0, v[172:173]
	s_mov_b32 m0, s63
	s_nop 0
	global_load_lds_dwordx4 v[186:187], off
	v_lshl_add_u64 v[186:187], s[78:79], 0, v[176:177]
	s_add_i32 m0, s63, 0x2000
	s_nop 0
	global_load_lds_dwordx4 v[186:187], off
	v_lshl_add_u64 v[186:187], v[222:223], 0, s[22:23]
	s_mov_b32 m0, s95
	s_nop 0
	global_load_lds_dwordx4 v[186:187], off
	v_lshl_add_u64 v[186:187], v[224:225], 0, s[22:23]
	s_mov_b32 m0, s96
	s_nop 0
	global_load_lds_dwordx4 v[186:187], off
	s_waitcnt vmcnt(8)
	s_waitcnt lgkmcnt(0)
	s_barrier
	s_setprio 1
	s_waitcnt lgkmcnt(0)
	v_mfma_f32_16x16x32_bf16 v[62:65], v[114:117], v[162:165], v[62:65]
	v_mfma_f32_16x16x32_bf16 v[58:61], v[122:125], v[162:165], v[58:61]
	v_mfma_f32_16x16x32_bf16 v[50:53], v[114:117], v[194:197], v[50:53]
	v_mfma_f32_16x16x32_bf16 v[42:45], v[122:125], v[194:197], v[42:45]
	v_mfma_f32_16x16x32_bf16 v[34:37], v[114:117], v[206:209], v[34:37]
	v_mfma_f32_16x16x32_bf16 v[26:29], v[122:125], v[206:209], v[26:29]
	v_mfma_f32_16x16x32_bf16 v[18:21], v[114:117], v[214:217], v[18:21]
	v_mfma_f32_16x16x32_bf16 v[10:13], v[122:125], v[214:217], v[10:13]
	v_mfma_f32_16x16x32_bf16 v[62:65], v[118:121], v[166:169], v[62:65]
	v_mfma_f32_16x16x32_bf16 v[58:61], v[126:129], v[166:169], v[58:61]
	v_mfma_f32_16x16x32_bf16 v[50:53], v[118:121], v[198:201], v[50:53]
	v_mfma_f32_16x16x32_bf16 v[42:45], v[126:129], v[198:201], v[42:45]
	v_mfma_f32_16x16x32_bf16 v[34:37], v[118:121], v[210:213], v[34:37]
	v_mfma_f32_16x16x32_bf16 v[26:29], v[126:129], v[210:213], v[26:29]
	v_mfma_f32_16x16x32_bf16 v[18:21], v[118:121], v[218:221], v[18:21]
	v_mfma_f32_16x16x32_bf16 v[10:13], v[126:129], v[218:221], v[10:13]
	s_setprio 0
	s_setprio 1
	v_mfma_f32_16x16x32_bf16 v[54:57], v[146:149], v[162:165], v[54:57]
	v_mfma_f32_16x16x32_bf16 v[46:49], v[154:157], v[162:165], v[46:49]
	v_mfma_f32_16x16x32_bf16 v[38:41], v[146:149], v[194:197], v[38:41]
	v_mfma_f32_16x16x32_bf16 v[30:33], v[154:157], v[194:197], v[30:33]
	v_mfma_f32_16x16x32_bf16 v[22:25], v[146:149], v[206:209], v[22:25]
	v_mfma_f32_16x16x32_bf16 v[14:17], v[154:157], v[206:209], v[14:17]
	v_mfma_f32_16x16x32_bf16 v[6:9], v[146:149], v[214:217], v[6:9]
	v_mfma_f32_16x16x32_bf16 v[2:5], v[154:157], v[214:217], v[2:5]
	v_mfma_f32_16x16x32_bf16 v[54:57], v[150:153], v[166:169], v[54:57]
	v_mfma_f32_16x16x32_bf16 v[46:49], v[158:161], v[166:169], v[46:49]
	v_mfma_f32_16x16x32_bf16 v[38:41], v[150:153], v[198:201], v[38:41]
	v_mfma_f32_16x16x32_bf16 v[30:33], v[158:161], v[198:201], v[30:33]
	v_mfma_f32_16x16x32_bf16 v[22:25], v[150:153], v[210:213], v[22:25]
	v_mfma_f32_16x16x32_bf16 v[14:17], v[158:161], v[210:213], v[14:17]
	v_mfma_f32_16x16x32_bf16 v[6:9], v[150:153], v[218:221], v[6:9]
	v_mfma_f32_16x16x32_bf16 v[2:5], v[158:161], v[218:221], v[2:5]
	s_setprio 0
	s_barrier
	s_add_u32 s76, s76, 0x100
	s_addc_u32 s77, s77, 0
	s_add_u32 s47, s47, 0x100
	s_addc_u32 s62, s62, 0
	s_cmp_ge_i32 s82, s7
	s_mov_b32 s63, s82
	s_cbranch_scc0 .LBB0_566
	s_and_b64 vcc, exec, s[26:27]
	s_cbranch_vccz .LBB0_569
	s_barrier

.LBB0_681:
	s_cmp_gt_i32 s59, 7
	s_cselect_b64 s[4:5], -1, 0
	s_and_b64 s[2:3], s[10:11], s[4:5]
	s_andn2_b64 vcc, exec, s[2:3]
	s_cbranch_vccnz .LBB0_735
	s_waitcnt vmcnt(0) lgkmcnt(0)
	s_barrier
	s_mov_b64 s[2:3], exec
	v_readlane_b32 s6, v249, 5
	v_readlane_b32 s7, v249, 6
	v_readlane_b32 s10, v249, 4
	s_and_b64 s[6:7], s[2:3], s[6:7]
	s_mov_b64 exec, s[6:7]
	s_cbranch_execz .Lgb_5_done
	v_mov_b32_e32 v1, 0x27e00
	ds_read2_b32 v[2:3], v1 offset1:1
	s_lshl_b32 s10, s10, 8
	s_add_u32 s8, s56, s10
	s_addc_u32 s9, s57, 0
	v_mov_b32_e32 v4, 0x1000
	v_mov_b32_e32 v5, 1
	global_atomic_add v6, v4, v5, s[8:9] offset:1024 sc0
	buffer_inv sc1
	s_waitcnt lgkmcnt(0)
	v_mul_lo_u32 v7, v2, 6
	s_waitcnt vmcnt(1)
	v_add_u32_e32 v6, 1, v6
	v_cmp_eq_u32_e32 vcc, v6, v7
	s_cbranch_vccz .Lgb_5_wait
	buffer_wbl2 sc1
	s_waitcnt vmcnt(0)
	v_mov_b32_e32 v4, 0x3000
	global_atomic_add v8, v4, v5, s[56:57] offset:1024 sc0
	v_mul_lo_u32 v7, v3, 6
	s_waitcnt vmcnt(0)
	v_add_u32_e32 v8, 1, v8
	v_cmp_eq_u32_e32 vcc, v8, v7
	s_cbranch_vccz .Lgb_5_wait
	v_mov_b32_e32 v9, 0x2400
	global_atomic_add v9, v5, s[56:57] offset:0
	global_atomic_add v9, v5, s[56:57] offset:256
	global_atomic_add v9, v5, s[56:57] offset:512
	global_atomic_add v9, v5, s[56:57] offset:768
	global_atomic_add v9, v5, s[56:57] offset:1024
	global_atomic_add v9, v5, s[56:57] offset:1280
	global_atomic_add v9, v5, s[56:57] offset:1536
	global_atomic_add v9, v5, s[56:57] offset:1792
	global_atomic_add v9, v5, s[56:57] offset:2048
	global_atomic_add v9, v5, s[56:57] offset:2304
	global_atomic_add v9, v5, s[56:57] offset:2560
	global_atomic_add v9, v5, s[56:57] offset:2816
	global_atomic_add v9, v5, s[56:57] offset:3072
	global_atomic_add v9, v5, s[56:57] offset:3328
	global_atomic_add v9, v5, s[56:57] offset:3584
	global_atomic_add v9, v5, s[56:57] offset:3840
	s_waitcnt vmcnt(0)
	s_branch .Lgb_5_done

.Lgb_5_spin:
	global_load_dword v8, v9, s[8:9] offset:1024 sc1
	s_waitcnt vmcnt(0)
	v_cmp_ne_u32_e32 vcc, 5, v8
	s_cbranch_vccnz .Lgb_5_done
	s_sleep 1
	s_add_u32 s10, s10, 1
	s_cmp_lt_u32 s10, 0x40000
	s_cbranch_scc1 .Lgb_5_spin

.LBB0_745:
	ds_read_b128 v[154:157], v150
	ds_read_b128 v[158:161], v150 offset:1024
	ds_read_b128 v[162:165], v150 offset:2048
	ds_read_b128 v[166:169], v150 offset:3072
	ds_read_b128 v[170:173], v151
	ds_read_b128 v[174:177], v151 offset:1024
	ds_read_b128 v[178:181], v151 offset:2048
	ds_read_b128 v[182:185], v151 offset:3072
	s_add_u32 s44, s42, 0xfffc0080
	s_addc_u32 s45, s43, -1
	s_cmp_eq_u32 s68, 12
	s_cselect_b32 s47, s14, s45
	s_cselect_b32 s46, s15, s44
	s_cselect_b32 s45, s21, s67
	s_cselect_b32 s44, s65, s66
	v_lshl_add_u64 v[146:147], s[42:43], 0, v[138:139]
	s_add_i32 m0, s19, 0xc000
	ds_read_b128 v[186:189], v152
	ds_read_b128 v[190:193], v152 offset:1024
	ds_read_b128 v[194:197], v152 offset:2048
	ds_read_b128 v[198:201], v152 offset:3072
	ds_read_b128 v[206:209], v152 offset:4096
	ds_read_b128 v[210:213], v152 offset:5120
	ds_read_b128 v[214:217], v152 offset:6144
	ds_read_b128 v[218:221], v152 offset:7168
	global_load_lds_dwordx4 v[146:147], off
	v_lshl_add_u64 v[146:147], s[42:43], 0, v[140:141]
	s_add_i32 m0, s19, 0xe000
	s_nop 0
	global_load_lds_dwordx4 v[146:147], off
	s_waitcnt vmcnt(8)
	s_waitcnt lgkmcnt(0)
	s_barrier
	s_setprio 1
	s_waitcnt lgkmcnt(0)
	v_mfma_f32_16x16x32_bf16 v[126:129], v[154:157], v[186:189], v[126:129]
	v_mfma_f32_16x16x32_bf16 v[122:125], v[162:165], v[186:189], v[122:125]
	v_mfma_f32_16x16x32_bf16 v[110:113], v[154:157], v[194:197], v[110:113]
	v_mfma_f32_16x16x32_bf16 v[106:109], v[162:165], v[194:197], v[106:109]
	v_mfma_f32_16x16x32_bf16 v[94:97], v[154:157], v[206:209], v[94:97]
	v_mfma_f32_16x16x32_bf16 v[90:93], v[162:165], v[206:209], v[90:93]
	v_mfma_f32_16x16x32_bf16 v[78:81], v[154:157], v[214:217], v[78:81]
	v_mfma_f32_16x16x32_bf16 v[74:77], v[162:165], v[214:217], v[74:77]
	v_mfma_f32_16x16x32_bf16 v[126:129], v[158:161], v[190:193], v[126:129]
	v_mfma_f32_16x16x32_bf16 v[122:125], v[166:169], v[190:193], v[122:125]
	v_mfma_f32_16x16x32_bf16 v[110:113], v[158:161], v[198:201], v[110:113]
	v_mfma_f32_16x16x32_bf16 v[106:109], v[166:169], v[198:201], v[106:109]
	v_mfma_f32_16x16x32_bf16 v[94:97], v[158:161], v[210:213], v[94:97]
	v_mfma_f32_16x16x32_bf16 v[90:93], v[166:169], v[210:213], v[90:93]
	v_mfma_f32_16x16x32_bf16 v[78:81], v[158:161], v[218:221], v[78:81]
	v_mfma_f32_16x16x32_bf16 v[74:77], v[166:169], v[218:221], v[74:77]
	s_setprio 0
	s_setprio 1
	v_mfma_f32_16x16x32_bf16 v[118:121], v[170:173], v[186:189], v[118:121]
	v_mfma_f32_16x16x32_bf16 v[114:117], v[178:181], v[186:189], v[114:117]
	v_mfma_f32_16x16x32_bf16 v[102:105], v[170:173], v[194:197], v[102:105]
	v_mfma_f32_16x16x32_bf16 v[98:101], v[178:181], v[194:197], v[98:101]
	v_mfma_f32_16x16x32_bf16 v[86:89], v[170:173], v[206:209], v[86:89]
	v_mfma_f32_16x16x32_bf16 v[82:85], v[178:181], v[206:209], v[82:85]
	v_mfma_f32_16x16x32_bf16 v[70:73], v[170:173], v[214:217], v[70:73]
	v_mfma_f32_16x16x32_bf16 v[66:69], v[178:181], v[214:217], v[66:69]
	v_mfma_f32_16x16x32_bf16 v[118:121], v[174:177], v[190:193], v[118:121]
	v_mfma_f32_16x16x32_bf16 v[114:117], v[182:185], v[190:193], v[114:117]
	v_mfma_f32_16x16x32_bf16 v[102:105], v[174:177], v[198:201], v[102:105]
	v_mfma_f32_16x16x32_bf16 v[98:101], v[182:185], v[198:201], v[98:101]
	v_mfma_f32_16x16x32_bf16 v[86:89], v[174:177], v[210:213], v[86:89]
	v_mfma_f32_16x16x32_bf16 v[82:85], v[182:185], v[210:213], v[82:85]
	v_mfma_f32_16x16x32_bf16 v[70:73], v[174:177], v[218:221], v[70:73]
	v_mfma_f32_16x16x32_bf16 v[66:69], v[182:185], v[218:221], v[66:69]
	s_setprio 0
	s_barrier
	s_add_i32 s69, s49, s16
	v_lshl_add_u64 v[146:147], s[44:45], 0, v[134:135]
	s_mov_b32 m0, s69
	ds_read_b128 v[186:189], v152 offset:16384
	ds_read_b128 v[190:193], v152 offset:17408
	ds_read_b128 v[194:197], v152 offset:18432
	ds_read_b128 v[198:201], v152 offset:19456
	ds_read_b128 v[206:209], v152 offset:20480
	ds_read_b128 v[210:213], v152 offset:21504
	ds_read_b128 v[214:217], v152 offset:22528
	ds_read_b128 v[218:221], v152 offset:23552
	global_load_lds_dwordx4 v[146:147], off
	s_add_i32 m0, s69, 0x2000
	s_add_u32 s70, s44, 0x40000
	v_lshl_add_u64 v[202:203], s[44:45], 0, v[130:131]
	s_addc_u32 s71, s45, 0
	s_add_i32 s69, s62, s16
	global_load_lds_dwordx4 v[202:203], off
	v_lshl_add_u64 v[222:223], s[70:71], 0, v[134:135]
	s_mov_b32 m0, s69
	v_lshl_add_u64 v[224:225], s[46:47], 0, v[132:133]
	global_load_lds_dwordx4 v[222:223], off
	v_lshl_add_u64 v[222:223], s[70:71], 0, v[130:131]
	s_add_i32 m0, s69, 0x2000
	s_nop 0
	global_load_lds_dwordx4 v[222:223], off
	v_lshl_add_u64 v[222:223], s[46:47], 0, v[136:137]
	s_mov_b32 m0, s19
	s_nop 0
	global_load_lds_dwordx4 v[222:223], off
	s_mov_b32 m0, s24
	s_nop 0
	global_load_lds_dwordx4 v[224:225], off
	s_waitcnt vmcnt(8)
	s_waitcnt lgkmcnt(0)
	s_barrier
	s_setprio 1
	s_waitcnt lgkmcnt(0)
	v_mfma_f32_16x16x32_bf16 v[62:65], v[154:157], v[186:189], v[62:65]
	v_mfma_f32_16x16x32_bf16 v[58:61], v[162:165], v[186:189], v[58:61]
	v_mfma_f32_16x16x32_bf16 v[46:49], v[154:157], v[194:197], v[46:49]
	v_mfma_f32_16x16x32_bf16 v[42:45], v[162:165], v[194:197], v[42:45]
	v_mfma_f32_16x16x32_bf16 v[30:33], v[154:157], v[206:209], v[30:33]
	v_mfma_f32_16x16x32_bf16 v[26:29], v[162:165], v[206:209], v[26:29]
	v_mfma_f32_16x16x32_bf16 v[14:17], v[154:157], v[214:217], v[14:17]
	v_mfma_f32_16x16x32_bf16 v[10:13], v[162:165], v[214:217], v[10:13]
	v_mfma_f32_16x16x32_bf16 v[62:65], v[158:161], v[190:193], v[62:65]
	v_mfma_f32_16x16x32_bf16 v[58:61], v[166:169], v[190:193], v[58:61]
	v_mfma_f32_16x16x32_bf16 v[46:49], v[158:161], v[198:201], v[46:49]
	v_mfma_f32_16x16x32_bf16 v[42:45], v[166:169], v[198:201], v[42:45]
	v_mfma_f32_16x16x32_bf16 v[30:33], v[158:161], v[210:213], v[30:33]
	v_mfma_f32_16x16x32_bf16 v[26:29], v[166:169], v[210:213], v[26:29]
	v_mfma_f32_16x16x32_bf16 v[14:17], v[158:161], v[218:221], v[14:17]
	v_mfma_f32_16x16x32_bf16 v[10:13], v[166:169], v[218:221], v[10:13]
	s_setprio 0
	s_setprio 1
	v_mfma_f32_16x16x32_bf16 v[54:57], v[170:173], v[186:189], v[54:57]
	v_mfma_f32_16x16x32_bf16 v[50:53], v[178:181], v[186:189], v[50:53]
	v_mfma_f32_16x16x32_bf16 v[38:41], v[170:173], v[194:197], v[38:41]
	v_mfma_f32_16x16x32_bf16 v[34:37], v[178:181], v[194:197], v[34:37]
	v_mfma_f32_16x16x32_bf16 v[22:25], v[170:173], v[206:209], v[22:25]
	v_mfma_f32_16x16x32_bf16 v[18:21], v[178:181], v[206:209], v[18:21]
	v_mfma_f32_16x16x32_bf16 v[6:9], v[170:173], v[214:217], v[6:9]
	v_mfma_f32_16x16x32_bf16 v[2:5], v[178:181], v[214:217], v[2:5]
	v_mfma_f32_16x16x32_bf16 v[54:57], v[174:177], v[190:193], v[54:57]
	v_mfma_f32_16x16x32_bf16 v[50:53], v[182:185], v[190:193], v[50:53]
	v_mfma_f32_16x16x32_bf16 v[38:41], v[174:177], v[198:201], v[38:41]
	v_mfma_f32_16x16x32_bf16 v[34:37], v[182:185], v[198:201], v[34:37]
	v_mfma_f32_16x16x32_bf16 v[22:25], v[174:177], v[210:213], v[22:25]
	v_mfma_f32_16x16x32_bf16 v[18:21], v[182:185], v[210:213], v[18:21]
	v_mfma_f32_16x16x32_bf16 v[6:9], v[174:177], v[218:221], v[6:9]
	v_mfma_f32_16x16x32_bf16 v[2:5], v[182:185], v[218:221], v[2:5]
	s_setprio 0
	s_barrier
	s_add_i32 s69, 0, 0x18000
	v_add_u32_e32 v153, s69, v149
	s_add_i32 s70, 0, 0x1c000
	ds_read_b128 v[154:157], v153
	ds_read_b128 v[158:161], v153 offset:1024
	ds_read_b128 v[162:165], v153 offset:2048
	ds_read_b128 v[166:169], v153 offset:3072
	v_add_u32_e32 v153, s70, v149
	ds_read_b128 v[170:173], v153
	ds_read_b128 v[174:177], v153 offset:1024
	ds_read_b128 v[178:181], v153 offset:2048
	ds_read_b128 v[182:185], v153 offset:3072
	s_add_u32 s46, s46, 0x40000
	s_addc_u32 s47, s47, 0
	s_mov_b32 m0, s25
	v_lshl_add_u64 v[226:227], s[46:47], 0, v[136:137]
	ds_read_b128 v[186:189], v152 offset:32768
	ds_read_b128 v[190:193], v152 offset:33792
	ds_read_b128 v[194:197], v152 offset:34816
	ds_read_b128 v[198:201], v152 offset:35840
	ds_read_b128 v[206:209], v152 offset:36864
	ds_read_b128 v[210:213], v152 offset:37888
	ds_read_b128 v[214:217], v152 offset:38912
	ds_read_b128 v[218:221], v152 offset:39936
	global_load_lds_dwordx4 v[226:227], off
	v_lshl_add_u64 v[226:227], s[46:47], 0, v[132:133]
	s_mov_b32 m0, s28
	s_nop 0
	global_load_lds_dwordx4 v[226:227], off
	s_waitcnt vmcnt(8)
	s_waitcnt lgkmcnt(0)
	s_barrier
	s_setprio 1
	s_waitcnt lgkmcnt(0)
	v_mfma_f32_16x16x32_bf16 v[126:129], v[154:157], v[186:189], v[126:129]
	v_mfma_f32_16x16x32_bf16 v[122:125], v[162:165], v[186:189], v[122:125]
	v_mfma_f32_16x16x32_bf16 v[110:113], v[154:157], v[194:197], v[110:113]
	v_mfma_f32_16x16x32_bf16 v[106:109], v[162:165], v[194:197], v[106:109]
	v_mfma_f32_16x16x32_bf16 v[94:97], v[154:157], v[206:209], v[94:97]
	v_mfma_f32_16x16x32_bf16 v[90:93], v[162:165], v[206:209], v[90:93]
	v_mfma_f32_16x16x32_bf16 v[78:81], v[154:157], v[214:217], v[78:81]
	v_mfma_f32_16x16x32_bf16 v[74:77], v[162:165], v[214:217], v[74:77]
	v_mfma_f32_16x16x32_bf16 v[126:129], v[158:161], v[190:193], v[126:129]
	v_mfma_f32_16x16x32_bf16 v[122:125], v[166:169], v[190:193], v[122:125]
	v_mfma_f32_16x16x32_bf16 v[110:113], v[158:161], v[198:201], v[110:113]
	v_mfma_f32_16x16x32_bf16 v[106:109], v[166:169], v[198:201], v[106:109]
	v_mfma_f32_16x16x32_bf16 v[94:97], v[158:161], v[210:213], v[94:97]
	v_mfma_f32_16x16x32_bf16 v[90:93], v[166:169], v[210:213], v[90:93]
	v_mfma_f32_16x16x32_bf16 v[78:81], v[158:161], v[218:221], v[78:81]
	v_mfma_f32_16x16x32_bf16 v[74:77], v[166:169], v[218:221], v[74:77]
	s_setprio 0
	s_setprio 1
	v_mfma_f32_16x16x32_bf16 v[118:121], v[170:173], v[186:189], v[118:121]
	v_mfma_f32_16x16x32_bf16 v[114:117], v[178:181], v[186:189], v[114:117]
	v_mfma_f32_16x16x32_bf16 v[102:105], v[170:173], v[194:197], v[102:105]
	v_mfma_f32_16x16x32_bf16 v[98:101], v[178:181], v[194:197], v[98:101]
	v_mfma_f32_16x16x32_bf16 v[86:89], v[170:173], v[206:209], v[86:89]
	v_mfma_f32_16x16x32_bf16 v[82:85], v[178:181], v[206:209], v[82:85]
	v_mfma_f32_16x16x32_bf16 v[70:73], v[170:173], v[214:217], v[70:73]
	v_mfma_f32_16x16x32_bf16 v[66:69], v[178:181], v[214:217], v[66:69]
	v_mfma_f32_16x16x32_bf16 v[118:121], v[174:177], v[190:193], v[118:121]
	v_mfma_f32_16x16x32_bf16 v[114:117], v[182:185], v[190:193], v[114:117]
	v_mfma_f32_16x16x32_bf16 v[102:105], v[174:177], v[198:201], v[102:105]
	v_mfma_f32_16x16x32_bf16 v[98:101], v[182:185], v[198:201], v[98:101]
	v_mfma_f32_16x16x32_bf16 v[86:89], v[174:177], v[210:213], v[86:89]
	v_mfma_f32_16x16x32_bf16 v[82:85], v[182:185], v[210:213], v[82:85]
	v_mfma_f32_16x16x32_bf16 v[70:73], v[174:177], v[218:221], v[70:73]
	v_mfma_f32_16x16x32_bf16 v[66:69], v[182:185], v[218:221], v[66:69]
	s_setprio 0
	s_barrier
	s_add_i32 s46, s69, s16
	v_lshl_add_u64 v[146:147], v[146:147], 0, s[10:11]
	s_mov_b32 m0, s46
	ds_read_b128 v[186:189], v152 offset:49152
	ds_read_b128 v[190:193], v152 offset:50176
	ds_read_b128 v[194:197], v152 offset:51200
	ds_read_b128 v[198:201], v152 offset:52224
	ds_read_b128 v[206:209], v152 offset:53248
	ds_read_b128 v[210:213], v152 offset:54272
	ds_read_b128 v[214:217], v152 offset:55296
	ds_read_b128 v[218:221], v152 offset:56320
	global_load_lds_dwordx4 v[146:147], off
	s_add_i32 m0, s46, 0x2000
	s_add_u32 s44, s44, 0x40080
	v_lshl_add_u64 v[146:147], v[202:203], 0, s[10:11]
	s_addc_u32 s45, s45, 0
	s_add_i32 s46, s70, s16
	global_load_lds_dwordx4 v[146:147], off
	v_lshl_add_u64 v[146:147], s[44:45], 0, v[134:135]
	s_mov_b32 m0, s46
	s_nop 0
	global_load_lds_dwordx4 v[146:147], off
	v_lshl_add_u64 v[146:147], s[44:45], 0, v[130:131]
	s_add_i32 m0, s46, 0x2000
	s_nop 0
	global_load_lds_dwordx4 v[146:147], off
	v_lshl_add_u64 v[146:147], v[222:223], 0, s[10:11]
	s_mov_b32 m0, s33
	s_nop 0
	global_load_lds_dwordx4 v[146:147], off
	v_lshl_add_u64 v[146:147], v[224:225], 0, s[10:11]
	s_mov_b32 m0, s35
	s_nop 0
	global_load_lds_dwordx4 v[146:147], off
	s_waitcnt vmcnt(8)
	s_waitcnt lgkmcnt(0)
	s_barrier
	s_setprio 1
	s_waitcnt lgkmcnt(0)
	v_mfma_f32_16x16x32_bf16 v[62:65], v[154:157], v[186:189], v[62:65]
	v_mfma_f32_16x16x32_bf16 v[58:61], v[162:165], v[186:189], v[58:61]
	v_mfma_f32_16x16x32_bf16 v[46:49], v[154:157], v[194:197], v[46:49]
	v_mfma_f32_16x16x32_bf16 v[42:45], v[162:165], v[194:197], v[42:45]
	v_mfma_f32_16x16x32_bf16 v[30:33], v[154:157], v[206:209], v[30:33]
	v_mfma_f32_16x16x32_bf16 v[26:29], v[162:165], v[206:209], v[26:29]
	v_mfma_f32_16x16x32_bf16 v[14:17], v[154:157], v[214:217], v[14:17]
	v_mfma_f32_16x16x32_bf16 v[10:13], v[162:165], v[214:217], v[10:13]
	v_mfma_f32_16x16x32_bf16 v[62:65], v[158:161], v[190:193], v[62:65]
	v_mfma_f32_16x16x32_bf16 v[58:61], v[166:169], v[190:193], v[58:61]
	v_mfma_f32_16x16x32_bf16 v[46:49], v[158:161], v[198:201], v[46:49]
	v_mfma_f32_16x16x32_bf16 v[42:45], v[166:169], v[198:201], v[42:45]
	v_mfma_f32_16x16x32_bf16 v[30:33], v[158:161], v[210:213], v[30:33]
	v_mfma_f32_16x16x32_bf16 v[26:29], v[166:169], v[210:213], v[26:29]
	v_mfma_f32_16x16x32_bf16 v[14:17], v[158:161], v[218:221], v[14:17]
	v_mfma_f32_16x16x32_bf16 v[10:13], v[166:169], v[218:221], v[10:13]
	s_setprio 0
	s_setprio 1
	v_mfma_f32_16x16x32_bf16 v[54:57], v[170:173], v[186:189], v[54:57]
	v_mfma_f32_16x16x32_bf16 v[50:53], v[178:181], v[186:189], v[50:53]
	v_mfma_f32_16x16x32_bf16 v[38:41], v[170:173], v[194:197], v[38:41]
	v_mfma_f32_16x16x32_bf16 v[34:37], v[178:181], v[194:197], v[34:37]
	v_mfma_f32_16x16x32_bf16 v[22:25], v[170:173], v[206:209], v[22:25]
	v_mfma_f32_16x16x32_bf16 v[18:21], v[178:181], v[206:209], v[18:21]
	v_mfma_f32_16x16x32_bf16 v[6:9], v[170:173], v[214:217], v[6:9]
	v_mfma_f32_16x16x32_bf16 v[2:5], v[178:181], v[214:217], v[2:5]
	v_mfma_f32_16x16x32_bf16 v[54:57], v[174:177], v[190:193], v[54:57]
	v_mfma_f32_16x16x32_bf16 v[50:53], v[182:185], v[190:193], v[50:53]
	v_mfma_f32_16x16x32_bf16 v[38:41], v[174:177], v[198:201], v[38:41]
	v_mfma_f32_16x16x32_bf16 v[34:37], v[182:185], v[198:201], v[34:37]
	v_mfma_f32_16x16x32_bf16 v[22:25], v[174:177], v[210:213], v[22:25]
	v_mfma_f32_16x16x32_bf16 v[18:21], v[182:185], v[210:213], v[18:21]
	v_mfma_f32_16x16x32_bf16 v[6:9], v[174:177], v[218:221], v[6:9]
	v_mfma_f32_16x16x32_bf16 v[2:5], v[182:185], v[218:221], v[2:5]
	s_setprio 0
	s_barrier
	s_add_i32 s68, s68, 2
	s_add_u32 s42, s42, 0x100
	s_addc_u32 s43, s43, 0
	s_add_u32 s66, s66, 0x100
	s_addc_u32 s67, s67, 0
	s_cmp_gt_u32 s68, 13
	s_cbranch_scc0 .LBB0_745
	s_and_b64 vcc, exec, s[12:13]
	s_cbranch_vccz .LBB0_748
	s_barrier

.LBB0_752:
	s_cmp_gt_i32 s59, 8
	s_cselect_b64 s[4:5], -1, 0
	s_and_b64 s[2:3], s[6:7], s[4:5]
	s_andn2_b64 vcc, exec, s[2:3]
	s_cbranch_vccnz .LBB0_806
	s_waitcnt vmcnt(0) lgkmcnt(0)
	s_barrier
	s_mov_b64 s[2:3], exec
	v_readlane_b32 s6, v249, 5
	v_readlane_b32 s7, v249, 6
	v_readlane_b32 s10, v249, 4
	s_and_b64 s[6:7], s[2:3], s[6:7]
	s_mov_b64 exec, s[6:7]
	s_cbranch_execz .Lgb_6_done
	v_mov_b32_e32 v1, 0x27e00
	ds_read2_b32 v[2:3], v1 offset1:1
	s_lshl_b32 s10, s10, 8
	s_add_u32 s8, s56, s10
	s_addc_u32 s9, s57, 0
	v_mov_b32_e32 v4, 0x1000
	v_mov_b32_e32 v5, 1
	global_atomic_add v6, v4, v5, s[8:9] offset:1024 sc0
	buffer_inv sc1
	s_waitcnt lgkmcnt(0)
	v_mul_lo_u32 v7, v2, 7
	s_waitcnt vmcnt(1)
	v_add_u32_e32 v6, 1, v6
	v_cmp_eq_u32_e32 vcc, v6, v7
	s_cbranch_vccz .Lgb_6_wait
	buffer_wbl2 sc1
	s_waitcnt vmcnt(0)
	v_mov_b32_e32 v4, 0x3000
	global_atomic_add v8, v4, v5, s[56:57] offset:1024 sc0
	v_mul_lo_u32 v7, v3, 7
	s_waitcnt vmcnt(0)
	v_add_u32_e32 v8, 1, v8
	v_cmp_eq_u32_e32 vcc, v8, v7
	s_cbranch_vccz .Lgb_6_wait
	v_mov_b32_e32 v9, 0x2400
	global_atomic_add v9, v5, s[56:57] offset:0
	global_atomic_add v9, v5, s[56:57] offset:256
	global_atomic_add v9, v5, s[56:57] offset:512
	global_atomic_add v9, v5, s[56:57] offset:768
	global_atomic_add v9, v5, s[56:57] offset:1024
	global_atomic_add v9, v5, s[56:57] offset:1280
	global_atomic_add v9, v5, s[56:57] offset:1536
	global_atomic_add v9, v5, s[56:57] offset:1792
	global_atomic_add v9, v5, s[56:57] offset:2048
	global_atomic_add v9, v5, s[56:57] offset:2304
	global_atomic_add v9, v5, s[56:57] offset:2560
	global_atomic_add v9, v5, s[56:57] offset:2816
	global_atomic_add v9, v5, s[56:57] offset:3072
	global_atomic_add v9, v5, s[56:57] offset:3328
	global_atomic_add v9, v5, s[56:57] offset:3584
	global_atomic_add v9, v5, s[56:57] offset:3840
	s_waitcnt vmcnt(0)
	s_branch .Lgb_6_done

.Lgb_6_spin:
	global_load_dword v8, v9, s[8:9] offset:1024 sc1
	s_waitcnt vmcnt(0)
	v_cmp_ne_u32_e32 vcc, 6, v8
	s_cbranch_vccnz .Lgb_6_done
	s_sleep 1
	s_add_u32 s10, s10, 1
	s_cmp_lt_u32 s10, 0x40000
	s_cbranch_scc1 .Lgb_6_spin

.LBB0_834:
	ds_read_b128 v[114:117], v190
	ds_read_b128 v[118:121], v190 offset:1024
	ds_read_b128 v[122:125], v190 offset:2048
	ds_read_b128 v[126:129], v190 offset:3072
	ds_read_b128 v[146:149], v191
	ds_read_b128 v[150:153], v191 offset:1024
	ds_read_b128 v[154:157], v191 offset:2048
	ds_read_b128 v[158:161], v191 offset:3072
	s_add_i32 s82, s63, 2
	s_add_u32 s78, s76, 0xfff00080
	s_addc_u32 s79, s77, -1
	s_cmp_eq_u32 s45, s63
	s_cselect_b32 s81, s15, s79
	s_cselect_b32 s80, s33, s78
	s_cselect_b32 s79, s34, s62
	s_cselect_b32 s78, s39, s47
	v_lshl_add_u64 v[186:187], s[76:77], 0, v[180:181]
	s_add_i32 m0, s87, 0xc000
	ds_read_b128 v[162:165], v192
	ds_read_b128 v[166:169], v192 offset:1024
	ds_read_b128 v[194:197], v192 offset:2048
	ds_read_b128 v[198:201], v192 offset:3072
	ds_read_b128 v[206:209], v192 offset:4096
	ds_read_b128 v[210:213], v192 offset:5120
	ds_read_b128 v[214:217], v192 offset:6144
	ds_read_b128 v[218:221], v192 offset:7168
	global_load_lds_dwordx4 v[186:187], off
	v_lshl_add_u64 v[186:187], s[76:77], 0, v[182:183]
	s_add_i32 m0, s87, 0xe000
	s_nop 0
	global_load_lds_dwordx4 v[186:187], off
	s_waitcnt vmcnt(8)
	s_waitcnt lgkmcnt(0)
	s_barrier
	s_setprio 1
	s_waitcnt lgkmcnt(0)
	v_mfma_f32_16x16x32_bf16 v[142:145], v[114:117], v[162:165], v[142:145]
	v_mfma_f32_16x16x32_bf16 v[138:141], v[122:125], v[162:165], v[138:141]
	v_mfma_f32_16x16x32_bf16 v[110:113], v[114:117], v[194:197], v[110:113]
	v_mfma_f32_16x16x32_bf16 v[106:109], v[122:125], v[194:197], v[106:109]
	v_mfma_f32_16x16x32_bf16 v[98:101], v[114:117], v[206:209], v[98:101]
	v_mfma_f32_16x16x32_bf16 v[90:93], v[122:125], v[206:209], v[90:93]
	v_mfma_f32_16x16x32_bf16 v[82:85], v[114:117], v[214:217], v[82:85]
	v_mfma_f32_16x16x32_bf16 v[74:77], v[122:125], v[214:217], v[74:77]
	v_mfma_f32_16x16x32_bf16 v[142:145], v[118:121], v[166:169], v[142:145]
	v_mfma_f32_16x16x32_bf16 v[138:141], v[126:129], v[166:169], v[138:141]
	v_mfma_f32_16x16x32_bf16 v[110:113], v[118:121], v[198:201], v[110:113]
	v_mfma_f32_16x16x32_bf16 v[106:109], v[126:129], v[198:201], v[106:109]
	v_mfma_f32_16x16x32_bf16 v[98:101], v[118:121], v[210:213], v[98:101]
	v_mfma_f32_16x16x32_bf16 v[90:93], v[126:129], v[210:213], v[90:93]
	v_mfma_f32_16x16x32_bf16 v[82:85], v[118:121], v[218:221], v[82:85]
	v_mfma_f32_16x16x32_bf16 v[74:77], v[126:129], v[218:221], v[74:77]
	s_setprio 0
	s_setprio 1
	v_mfma_f32_16x16x32_bf16 v[134:137], v[146:149], v[162:165], v[134:137]
	v_mfma_f32_16x16x32_bf16 v[130:133], v[154:157], v[162:165], v[130:133]
	v_mfma_f32_16x16x32_bf16 v[102:105], v[146:149], v[194:197], v[102:105]
	v_mfma_f32_16x16x32_bf16 v[94:97], v[154:157], v[194:197], v[94:97]
	v_mfma_f32_16x16x32_bf16 v[86:89], v[146:149], v[206:209], v[86:89]
	v_mfma_f32_16x16x32_bf16 v[78:81], v[154:157], v[206:209], v[78:81]
	v_mfma_f32_16x16x32_bf16 v[70:73], v[146:149], v[214:217], v[70:73]
	v_mfma_f32_16x16x32_bf16 v[66:69], v[154:157], v[214:217], v[66:69]
	v_mfma_f32_16x16x32_bf16 v[134:137], v[150:153], v[166:169], v[134:137]
	v_mfma_f32_16x16x32_bf16 v[130:133], v[158:161], v[166:169], v[130:133]
	v_mfma_f32_16x16x32_bf16 v[102:105], v[150:153], v[198:201], v[102:105]
	v_mfma_f32_16x16x32_bf16 v[94:97], v[158:161], v[198:201], v[94:97]
	v_mfma_f32_16x16x32_bf16 v[86:89], v[150:153], v[210:213], v[86:89]
	v_mfma_f32_16x16x32_bf16 v[78:81], v[158:161], v[210:213], v[78:81]
	v_mfma_f32_16x16x32_bf16 v[70:73], v[150:153], v[218:221], v[70:73]
	v_mfma_f32_16x16x32_bf16 v[66:69], v[158:161], v[218:221], v[66:69]
	s_setprio 0
	s_barrier
	s_add_i32 s63, s24, s86
	v_lshl_add_u64 v[186:187], s[78:79], 0, v[172:173]
	s_mov_b32 m0, s63
	ds_read_b128 v[162:165], v192 offset:16384
	ds_read_b128 v[166:169], v192 offset:17408
	ds_read_b128 v[194:197], v192 offset:18432
	ds_read_b128 v[198:201], v192 offset:19456
	ds_read_b128 v[206:209], v192 offset:20480
	ds_read_b128 v[210:213], v192 offset:21504
	ds_read_b128 v[214:217], v192 offset:22528
	ds_read_b128 v[218:221], v192 offset:23552
	global_load_lds_dwordx4 v[186:187], off
	s_add_i32 m0, s63, 0x2000
	s_add_u32 vcc_lo, s78, 0x100000
	v_lshl_add_u64 v[202:203], s[78:79], 0, v[176:177]
	s_addc_u32 vcc_hi, s79, 0
	s_add_i32 s63, s25, s86
	global_load_lds_dwordx4 v[202:203], off
	v_lshl_add_u64 v[222:223], vcc, 0, v[172:173]
	s_mov_b32 m0, s63
	v_lshl_add_u64 v[224:225], s[80:81], 0, v[174:175]
	global_load_lds_dwordx4 v[222:223], off
	v_lshl_add_u64 v[222:223], vcc, 0, v[176:177]
	s_add_i32 m0, s63, 0x2000
	s_nop 0
	global_load_lds_dwordx4 v[222:223], off
	v_lshl_add_u64 v[222:223], s[80:81], 0, v[170:171]
	s_mov_b32 m0, s87
	s_nop 0
	global_load_lds_dwordx4 v[222:223], off
	s_mov_b32 m0, s88
	s_nop 0
	global_load_lds_dwordx4 v[224:225], off
	s_waitcnt vmcnt(8)
	s_waitcnt lgkmcnt(0)
	s_barrier
	s_setprio 1
	s_waitcnt lgkmcnt(0)
	v_mfma_f32_16x16x32_bf16 v[62:65], v[114:117], v[162:165], v[62:65]
	v_mfma_f32_16x16x32_bf16 v[58:61], v[122:125], v[162:165], v[58:61]
	v_mfma_f32_16x16x32_bf16 v[50:53], v[114:117], v[194:197], v[50:53]
	v_mfma_f32_16x16x32_bf16 v[42:45], v[122:125], v[194:197], v[42:45]
	v_mfma_f32_16x16x32_bf16 v[34:37], v[114:117], v[206:209], v[34:37]
	v_mfma_f32_16x16x32_bf16 v[26:29], v[122:125], v[206:209], v[26:29]
	v_mfma_f32_16x16x32_bf16 v[18:21], v[114:117], v[214:217], v[18:21]
	v_mfma_f32_16x16x32_bf16 v[10:13], v[122:125], v[214:217], v[10:13]
	v_mfma_f32_16x16x32_bf16 v[62:65], v[118:121], v[166:169], v[62:65]
	v_mfma_f32_16x16x32_bf16 v[58:61], v[126:129], v[166:169], v[58:61]
	v_mfma_f32_16x16x32_bf16 v[50:53], v[118:121], v[198:201], v[50:53]
	v_mfma_f32_16x16x32_bf16 v[42:45], v[126:129], v[198:201], v[42:45]
	v_mfma_f32_16x16x32_bf16 v[34:37], v[118:121], v[210:213], v[34:37]
	v_mfma_f32_16x16x32_bf16 v[26:29], v[126:129], v[210:213], v[26:29]
	v_mfma_f32_16x16x32_bf16 v[18:21], v[118:121], v[218:221], v[18:21]
	v_mfma_f32_16x16x32_bf16 v[10:13], v[126:129], v[218:221], v[10:13]
	s_setprio 0
	s_setprio 1
	v_mfma_f32_16x16x32_bf16 v[54:57], v[146:149], v[162:165], v[54:57]
	v_mfma_f32_16x16x32_bf16 v[46:49], v[154:157], v[162:165], v[46:49]
	v_mfma_f32_16x16x32_bf16 v[38:41], v[146:149], v[194:197], v[38:41]
	v_mfma_f32_16x16x32_bf16 v[30:33], v[154:157], v[194:197], v[30:33]
	v_mfma_f32_16x16x32_bf16 v[22:25], v[146:149], v[206:209], v[22:25]
	v_mfma_f32_16x16x32_bf16 v[14:17], v[154:157], v[206:209], v[14:17]
	v_mfma_f32_16x16x32_bf16 v[6:9], v[146:149], v[214:217], v[6:9]
	v_mfma_f32_16x16x32_bf16 v[2:5], v[154:157], v[214:217], v[2:5]
	v_mfma_f32_16x16x32_bf16 v[54:57], v[150:153], v[166:169], v[54:57]
	v_mfma_f32_16x16x32_bf16 v[46:49], v[158:161], v[166:169], v[46:49]
	v_mfma_f32_16x16x32_bf16 v[38:41], v[150:153], v[198:201], v[38:41]
	v_mfma_f32_16x16x32_bf16 v[30:33], v[158:161], v[198:201], v[30:33]
	v_mfma_f32_16x16x32_bf16 v[22:25], v[150:153], v[210:213], v[22:25]
	v_mfma_f32_16x16x32_bf16 v[14:17], v[158:161], v[210:213], v[14:17]
	v_mfma_f32_16x16x32_bf16 v[6:9], v[150:153], v[218:221], v[6:9]
	v_mfma_f32_16x16x32_bf16 v[2:5], v[158:161], v[218:221], v[2:5]
	s_setprio 0
	s_barrier
	s_add_i32 s63, 0, 0x18000
	s_add_i32 s83, 0, 0x1c000
	v_add_u32_e32 v126, s63, v189
	v_add_u32_e32 v158, s83, v189
	ds_read_b128 v[114:117], v126
	ds_read_b128 v[118:121], v126 offset:1024
	ds_read_b128 v[122:125], v126 offset:2048
	ds_read_b128 v[126:129], v126 offset:3072
	ds_read_b128 v[146:149], v158
	ds_read_b128 v[150:153], v158 offset:1024
	ds_read_b128 v[154:157], v158 offset:2048
	ds_read_b128 v[158:161], v158 offset:3072
	s_add_u32 s80, s80, 0x100000
	s_addc_u32 s81, s81, 0
	s_mov_b32 m0, s89
	v_lshl_add_u64 v[226:227], s[80:81], 0, v[170:171]
	ds_read_b128 v[162:165], v192 offset:32768
	ds_read_b128 v[166:169], v192 offset:33792
	ds_read_b128 v[194:197], v192 offset:34816
	ds_read_b128 v[198:201], v192 offset:35840
	ds_read_b128 v[206:209], v192 offset:36864
	ds_read_b128 v[210:213], v192 offset:37888
	ds_read_b128 v[214:217], v192 offset:38912
	ds_read_b128 v[218:221], v192 offset:39936
	global_load_lds_dwordx4 v[226:227], off
	v_lshl_add_u64 v[226:227], s[80:81], 0, v[174:175]
	s_mov_b32 m0, s90
	s_nop 0
	global_load_lds_dwordx4 v[226:227], off
	s_waitcnt vmcnt(8)
	s_waitcnt lgkmcnt(0)
	s_barrier
	s_setprio 1
	s_waitcnt lgkmcnt(0)
	v_mfma_f32_16x16x32_bf16 v[142:145], v[114:117], v[162:165], v[142:145]
	v_mfma_f32_16x16x32_bf16 v[138:141], v[122:125], v[162:165], v[138:141]
	v_mfma_f32_16x16x32_bf16 v[110:113], v[114:117], v[194:197], v[110:113]
	v_mfma_f32_16x16x32_bf16 v[106:109], v[122:125], v[194:197], v[106:109]
	v_mfma_f32_16x16x32_bf16 v[98:101], v[114:117], v[206:209], v[98:101]
	v_mfma_f32_16x16x32_bf16 v[90:93], v[122:125], v[206:209], v[90:93]
	v_mfma_f32_16x16x32_bf16 v[82:85], v[114:117], v[214:217], v[82:85]
	v_mfma_f32_16x16x32_bf16 v[74:77], v[122:125], v[214:217], v[74:77]
	v_mfma_f32_16x16x32_bf16 v[142:145], v[118:121], v[166:169], v[142:145]
	v_mfma_f32_16x16x32_bf16 v[138:141], v[126:129], v[166:169], v[138:141]
	v_mfma_f32_16x16x32_bf16 v[110:113], v[118:121], v[198:201], v[110:113]
	v_mfma_f32_16x16x32_bf16 v[106:109], v[126:129], v[198:201], v[106:109]
	v_mfma_f32_16x16x32_bf16 v[98:101], v[118:121], v[210:213], v[98:101]
	v_mfma_f32_16x16x32_bf16 v[90:93], v[126:129], v[210:213], v[90:93]
	v_mfma_f32_16x16x32_bf16 v[82:85], v[118:121], v[218:221], v[82:85]
	v_mfma_f32_16x16x32_bf16 v[74:77], v[126:129], v[218:221], v[74:77]
	s_setprio 0
	s_setprio 1
	v_mfma_f32_16x16x32_bf16 v[134:137], v[146:149], v[162:165], v[134:137]
	v_mfma_f32_16x16x32_bf16 v[130:133], v[154:157], v[162:165], v[130:133]
	v_mfma_f32_16x16x32_bf16 v[102:105], v[146:149], v[194:197], v[102:105]
	v_mfma_f32_16x16x32_bf16 v[94:97], v[154:157], v[194:197], v[94:97]
	v_mfma_f32_16x16x32_bf16 v[86:89], v[146:149], v[206:209], v[86:89]
	v_mfma_f32_16x16x32_bf16 v[78:81], v[154:157], v[206:209], v[78:81]
	v_mfma_f32_16x16x32_bf16 v[70:73], v[146:149], v[214:217], v[70:73]
	v_mfma_f32_16x16x32_bf16 v[66:69], v[154:157], v[214:217], v[66:69]
	v_mfma_f32_16x16x32_bf16 v[134:137], v[150:153], v[166:169], v[134:137]
	v_mfma_f32_16x16x32_bf16 v[130:133], v[158:161], v[166:169], v[130:133]
	v_mfma_f32_16x16x32_bf16 v[102:105], v[150:153], v[198:201], v[102:105]
	v_mfma_f32_16x16x32_bf16 v[94:97], v[158:161], v[198:201], v[94:97]
	v_mfma_f32_16x16x32_bf16 v[86:89], v[150:153], v[210:213], v[86:89]
	v_mfma_f32_16x16x32_bf16 v[78:81], v[158:161], v[210:213], v[78:81]
	v_mfma_f32_16x16x32_bf16 v[70:73], v[150:153], v[218:221], v[70:73]
	v_mfma_f32_16x16x32_bf16 v[66:69], v[158:161], v[218:221], v[66:69]
	s_setprio 0
	s_barrier
	s_add_i32 s63, s63, s86
	v_lshl_add_u64 v[186:187], v[186:187], 0, s[22:23]
	s_mov_b32 m0, s63
	ds_read_b128 v[162:165], v192 offset:49152
	ds_read_b128 v[166:169], v192 offset:50176
	ds_read_b128 v[194:197], v192 offset:51200
	ds_read_b128 v[198:201], v192 offset:52224
	ds_read_b128 v[206:209], v192 offset:53248
	ds_read_b128 v[210:213], v192 offset:54272
	ds_read_b128 v[214:217], v192 offset:55296
	ds_read_b128 v[218:221], v192 offset:56320
	global_load_lds_dwordx4 v[186:187], off
	s_add_i32 m0, s63, 0x2000
	s_add_u32 s78, s78, 0x100080
	v_lshl_add_u64 v[186:187], v[202:203], 0, s[22:23]
	s_addc_u32 s79, s79, 0
	s_add_i32 s63, s83, s86
	global_load_lds_dwordx4 v[186:187], off
	v_lshl_add_u64 v[186:187], s[78:79], 0, v[172:173]
	s_mov_b32 m0, s63
	s_nop 0
	global_load_lds_dwordx4 v[186:187], off
	v_lshl_add_u64 v[186:187], s[78:79], 0, v[176:177]
	s_add_i32 m0, s63, 0x2000
	s_nop 0
	global_load_lds_dwordx4 v[186:187], off
	v_lshl_add_u64 v[186:187], v[222:223], 0, s[22:23]
	s_mov_b32 m0, s95
	s_nop 0
	global_load_lds_dwordx4 v[186:187], off
	v_lshl_add_u64 v[186:187], v[224:225], 0, s[22:23]
	s_mov_b32 m0, s96
	s_nop 0
	global_load_lds_dwordx4 v[186:187], off
	s_waitcnt vmcnt(8)
	s_waitcnt lgkmcnt(0)
	s_barrier
	s_setprio 1
	s_waitcnt lgkmcnt(0)
	v_mfma_f32_16x16x32_bf16 v[62:65], v[114:117], v[162:165], v[62:65]
	v_mfma_f32_16x16x32_bf16 v[58:61], v[122:125], v[162:165], v[58:61]
	v_mfma_f32_16x16x32_bf16 v[50:53], v[114:117], v[194:197], v[50:53]
	v_mfma_f32_16x16x32_bf16 v[42:45], v[122:125], v[194:197], v[42:45]
	v_mfma_f32_16x16x32_bf16 v[34:37], v[114:117], v[206:209], v[34:37]
	v_mfma_f32_16x16x32_bf16 v[26:29], v[122:125], v[206:209], v[26:29]
	v_mfma_f32_16x16x32_bf16 v[18:21], v[114:117], v[214:217], v[18:21]
	v_mfma_f32_16x16x32_bf16 v[10:13], v[122:125], v[214:217], v[10:13]
	v_mfma_f32_16x16x32_bf16 v[62:65], v[118:121], v[166:169], v[62:65]
	v_mfma_f32_16x16x32_bf16 v[58:61], v[126:129], v[166:169], v[58:61]
	v_mfma_f32_16x16x32_bf16 v[50:53], v[118:121], v[198:201], v[50:53]
	v_mfma_f32_16x16x32_bf16 v[42:45], v[126:129], v[198:201], v[42:45]
	v_mfma_f32_16x16x32_bf16 v[34:37], v[118:121], v[210:213], v[34:37]
	v_mfma_f32_16x16x32_bf16 v[26:29], v[126:129], v[210:213], v[26:29]
	v_mfma_f32_16x16x32_bf16 v[18:21], v[118:121], v[218:221], v[18:21]
	v_mfma_f32_16x16x32_bf16 v[10:13], v[126:129], v[218:221], v[10:13]
	s_setprio 0
	s_setprio 1
	v_mfma_f32_16x16x32_bf16 v[54:57], v[146:149], v[162:165], v[54:57]
	v_mfma_f32_16x16x32_bf16 v[46:49], v[154:157], v[162:165], v[46:49]
	v_mfma_f32_16x16x32_bf16 v[38:41], v[146:149], v[194:197], v[38:41]
	v_mfma_f32_16x16x32_bf16 v[30:33], v[154:157], v[194:197], v[30:33]
	v_mfma_f32_16x16x32_bf16 v[22:25], v[146:149], v[206:209], v[22:25]
	v_mfma_f32_16x16x32_bf16 v[14:17], v[154:157], v[206:209], v[14:17]
	v_mfma_f32_16x16x32_bf16 v[6:9], v[146:149], v[214:217], v[6:9]
	v_mfma_f32_16x16x32_bf16 v[2:5], v[154:157], v[214:217], v[2:5]
	v_mfma_f32_16x16x32_bf16 v[54:57], v[150:153], v[166:169], v[54:57]
	v_mfma_f32_16x16x32_bf16 v[46:49], v[158:161], v[166:169], v[46:49]
	v_mfma_f32_16x16x32_bf16 v[38:41], v[150:153], v[198:201], v[38:41]
	v_mfma_f32_16x16x32_bf16 v[30:33], v[158:161], v[198:201], v[30:33]
	v_mfma_f32_16x16x32_bf16 v[22:25], v[150:153], v[210:213], v[22:25]
	v_mfma_f32_16x16x32_bf16 v[14:17], v[158:161], v[210:213], v[14:17]
	v_mfma_f32_16x16x32_bf16 v[6:9], v[150:153], v[218:221], v[6:9]
	v_mfma_f32_16x16x32_bf16 v[2:5], v[158:161], v[218:221], v[2:5]
	s_setprio 0
	s_barrier
	s_add_u32 s76, s76, 0x100
	s_addc_u32 s77, s77, 0
	s_add_u32 s47, s47, 0x100
	s_addc_u32 s62, s62, 0
	s_cmp_ge_i32 s82, s7
	s_mov_b32 s63, s82
	s_cbranch_scc0 .LBB0_834
	s_and_b64 vcc, exec, s[26:27]
	s_cbranch_vccz .LBB0_837
	s_barrier

.LBB0_949:
	s_cmp_gt_i32 s59, 10
	s_cselect_b64 s[4:5], -1, 0
	s_and_b64 s[0:1], s[10:11], s[4:5]
	s_andn2_b64 vcc, exec, s[0:1]
	s_cbranch_vccnz .LBB0_1003
	s_waitcnt vmcnt(0) lgkmcnt(0)
	s_barrier
	s_mov_b64 s[0:1], exec
	v_readlane_b32 s2, v249, 5
	v_readlane_b32 s3, v249, 6
	v_readlane_b32 s8, v249, 4
	s_and_b64 s[2:3], s[0:1], s[2:3]
	s_mov_b64 exec, s[2:3]
	s_cbranch_execz .Lgb_7_done
	v_mov_b32_e32 v1, 0x27e00
	ds_read2_b32 v[2:3], v1 offset1:1
	s_lshl_b32 s8, s8, 8
	s_add_u32 s6, s56, s8
	s_addc_u32 s7, s57, 0
	v_mov_b32_e32 v4, 0x1000
	v_mov_b32_e32 v5, 1
	global_atomic_add v6, v4, v5, s[6:7] offset:1024 sc0
	buffer_inv sc1
	s_waitcnt lgkmcnt(0)
	v_mul_lo_u32 v7, v2, 8
	s_waitcnt vmcnt(1)
	v_add_u32_e32 v6, 1, v6
	v_cmp_eq_u32_e32 vcc, v6, v7
	s_cbranch_vccz .Lgb_7_wait
	buffer_wbl2 sc1
	s_waitcnt vmcnt(0)
	v_mov_b32_e32 v4, 0x3000
	global_atomic_add v8, v4, v5, s[56:57] offset:1024 sc0
	v_mul_lo_u32 v7, v3, 8
	s_waitcnt vmcnt(0)
	v_add_u32_e32 v8, 1, v8
	v_cmp_eq_u32_e32 vcc, v8, v7
	s_cbranch_vccz .Lgb_7_wait
	v_mov_b32_e32 v9, 0x2400
	global_atomic_add v9, v5, s[56:57] offset:0
	global_atomic_add v9, v5, s[56:57] offset:256
	global_atomic_add v9, v5, s[56:57] offset:512
	global_atomic_add v9, v5, s[56:57] offset:768
	global_atomic_add v9, v5, s[56:57] offset:1024
	global_atomic_add v9, v5, s[56:57] offset:1280
	global_atomic_add v9, v5, s[56:57] offset:1536
	global_atomic_add v9, v5, s[56:57] offset:1792
	global_atomic_add v9, v5, s[56:57] offset:2048
	global_atomic_add v9, v5, s[56:57] offset:2304
	global_atomic_add v9, v5, s[56:57] offset:2560
	global_atomic_add v9, v5, s[56:57] offset:2816
	global_atomic_add v9, v5, s[56:57] offset:3072
	global_atomic_add v9, v5, s[56:57] offset:3328
	global_atomic_add v9, v5, s[56:57] offset:3584
	global_atomic_add v9, v5, s[56:57] offset:3840
	s_waitcnt vmcnt(0)
	s_branch .Lgb_7_done

.Lgb_7_spin:
	global_load_dword v8, v9, s[6:7] offset:1024 sc1
	s_waitcnt vmcnt(0)
	v_cmp_ne_u32_e32 vcc, 7, v8
	s_cbranch_vccnz .Lgb_7_done
	s_sleep 1
	s_add_u32 s8, s8, 1
	s_cmp_lt_u32 s8, 0x40000
	s_cbranch_scc1 .Lgb_7_spin

.LBB0_1013:
	ds_read_b128 v[130:133], v172
	ds_read_b128 v[134:137], v172 offset:1024
	ds_read_b128 v[138:141], v172 offset:2048
	ds_read_b128 v[142:145], v172 offset:3072
	ds_read_b128 v[164:167], v173
	ds_read_b128 v[176:179], v173 offset:1024
	ds_read_b128 v[180:183], v173 offset:2048
	ds_read_b128 v[184:187], v173 offset:3072
	s_add_u32 s25, s64, 0xfffc0080
	s_addc_u32 s28, s65, -1
	s_cmp_eq_u32 s24, 12
	s_cselect_b32 s69, s6, s28
	s_cselect_b32 s68, s14, s25
	s_cselect_b32 s67, s15, s19
	s_cselect_b32 s66, s17, s18
	v_lshl_add_u64 v[168:169], s[64:65], 0, v[156:157]
	s_add_i32 m0, s73, 0xc000
	ds_read_b128 v[188:191], v174
	ds_read_b128 v[192:195], v174 offset:1024
	ds_read_b128 v[196:199], v174 offset:2048
	ds_read_b128 v[200:203], v174 offset:3072
	ds_read_b128 v[206:209], v174 offset:4096
	ds_read_b128 v[210:213], v174 offset:5120
	ds_read_b128 v[214:217], v174 offset:6144
	ds_read_b128 v[218:221], v174 offset:7168
	global_load_lds_dwordx4 v[168:169], off
	v_lshl_add_u64 v[168:169], s[64:65], 0, v[158:159]
	s_add_i32 m0, s73, 0xe000
	s_nop 0
	global_load_lds_dwordx4 v[168:169], off
	s_waitcnt vmcnt(8)
	s_waitcnt lgkmcnt(0)
	s_barrier
	s_setprio 1
	s_waitcnt lgkmcnt(0)
	v_mfma_f32_16x16x32_bf16 v[126:129], v[130:133], v[188:191], v[126:129]
	v_mfma_f32_16x16x32_bf16 v[122:125], v[138:141], v[188:191], v[122:125]
	v_mfma_f32_16x16x32_bf16 v[110:113], v[130:133], v[196:199], v[110:113]
	v_mfma_f32_16x16x32_bf16 v[106:109], v[138:141], v[196:199], v[106:109]
	v_mfma_f32_16x16x32_bf16 v[94:97], v[130:133], v[206:209], v[94:97]
	v_mfma_f32_16x16x32_bf16 v[90:93], v[138:141], v[206:209], v[90:93]
	v_mfma_f32_16x16x32_bf16 v[78:81], v[130:133], v[214:217], v[78:81]
	v_mfma_f32_16x16x32_bf16 v[74:77], v[138:141], v[214:217], v[74:77]
	v_mfma_f32_16x16x32_bf16 v[126:129], v[134:137], v[192:195], v[126:129]
	v_mfma_f32_16x16x32_bf16 v[122:125], v[142:145], v[192:195], v[122:125]
	v_mfma_f32_16x16x32_bf16 v[110:113], v[134:137], v[200:203], v[110:113]
	v_mfma_f32_16x16x32_bf16 v[106:109], v[142:145], v[200:203], v[106:109]
	v_mfma_f32_16x16x32_bf16 v[94:97], v[134:137], v[210:213], v[94:97]
	v_mfma_f32_16x16x32_bf16 v[90:93], v[142:145], v[210:213], v[90:93]
	v_mfma_f32_16x16x32_bf16 v[78:81], v[134:137], v[218:221], v[78:81]
	v_mfma_f32_16x16x32_bf16 v[74:77], v[142:145], v[218:221], v[74:77]
	s_setprio 0
	s_setprio 1
	v_mfma_f32_16x16x32_bf16 v[118:121], v[164:167], v[188:191], v[118:121]
	v_mfma_f32_16x16x32_bf16 v[114:117], v[180:183], v[188:191], v[114:117]
	v_mfma_f32_16x16x32_bf16 v[102:105], v[164:167], v[196:199], v[102:105]
	v_mfma_f32_16x16x32_bf16 v[98:101], v[180:183], v[196:199], v[98:101]
	v_mfma_f32_16x16x32_bf16 v[86:89], v[164:167], v[206:209], v[86:89]
	v_mfma_f32_16x16x32_bf16 v[82:85], v[180:183], v[206:209], v[82:85]
	v_mfma_f32_16x16x32_bf16 v[70:73], v[164:167], v[214:217], v[70:73]
	v_mfma_f32_16x16x32_bf16 v[66:69], v[180:183], v[214:217], v[66:69]
	v_mfma_f32_16x16x32_bf16 v[118:121], v[176:179], v[192:195], v[118:121]
	v_mfma_f32_16x16x32_bf16 v[114:117], v[184:187], v[192:195], v[114:117]
	v_mfma_f32_16x16x32_bf16 v[102:105], v[176:179], v[200:203], v[102:105]
	v_mfma_f32_16x16x32_bf16 v[98:101], v[184:187], v[200:203], v[98:101]
	v_mfma_f32_16x16x32_bf16 v[86:89], v[176:179], v[210:213], v[86:89]
	v_mfma_f32_16x16x32_bf16 v[82:85], v[184:187], v[210:213], v[82:85]
	v_mfma_f32_16x16x32_bf16 v[70:73], v[176:179], v[218:221], v[70:73]
	v_mfma_f32_16x16x32_bf16 v[66:69], v[184:187], v[218:221], v[66:69]
	s_setprio 0
	s_barrier
	s_add_i32 s25, s82, s70
	v_lshl_add_u64 v[168:169], s[66:67], 0, v[150:151]
	s_mov_b32 m0, s25
	ds_read_b128 v[188:191], v174 offset:16384
	ds_read_b128 v[192:195], v174 offset:17408
	ds_read_b128 v[196:199], v174 offset:18432
	ds_read_b128 v[200:203], v174 offset:19456
	ds_read_b128 v[206:209], v174 offset:20480
	ds_read_b128 v[210:213], v174 offset:21504
	ds_read_b128 v[214:217], v174 offset:22528
	ds_read_b128 v[218:221], v174 offset:23552
	global_load_lds_dwordx4 v[168:169], off
	s_add_i32 m0, s25, 0x2000
	s_add_u32 s28, s66, 0x40000
	v_lshl_add_u64 v[222:223], s[66:67], 0, v[146:147]
	s_addc_u32 s29, s67, 0
	s_add_i32 s25, s83, s70
	global_load_lds_dwordx4 v[222:223], off
	v_lshl_add_u64 v[224:225], s[28:29], 0, v[150:151]
	s_mov_b32 m0, s25
	v_lshl_add_u64 v[226:227], s[68:69], 0, v[148:149]
	global_load_lds_dwordx4 v[224:225], off
	v_lshl_add_u64 v[224:225], s[28:29], 0, v[146:147]
	s_add_i32 m0, s25, 0x2000
	s_nop 0
	global_load_lds_dwordx4 v[224:225], off
	v_lshl_add_u64 v[224:225], s[68:69], 0, v[152:153]
	s_mov_b32 m0, s73
	s_nop 0
	global_load_lds_dwordx4 v[224:225], off
	s_mov_b32 m0, s74
	s_nop 0
	global_load_lds_dwordx4 v[226:227], off
	s_waitcnt vmcnt(8)
	s_waitcnt lgkmcnt(0)
	s_barrier
	s_setprio 1
	s_waitcnt lgkmcnt(0)
	v_mfma_f32_16x16x32_bf16 v[62:65], v[130:133], v[188:191], v[62:65]
	v_mfma_f32_16x16x32_bf16 v[58:61], v[138:141], v[188:191], v[58:61]
	v_mfma_f32_16x16x32_bf16 v[46:49], v[130:133], v[196:199], v[46:49]
	v_mfma_f32_16x16x32_bf16 v[42:45], v[138:141], v[196:199], v[42:45]
	v_mfma_f32_16x16x32_bf16 v[30:33], v[130:133], v[206:209], v[30:33]
	v_mfma_f32_16x16x32_bf16 v[26:29], v[138:141], v[206:209], v[26:29]
	v_mfma_f32_16x16x32_bf16 v[14:17], v[130:133], v[214:217], v[14:17]
	v_mfma_f32_16x16x32_bf16 v[10:13], v[138:141], v[214:217], v[10:13]
	v_mfma_f32_16x16x32_bf16 v[62:65], v[134:137], v[192:195], v[62:65]
	v_mfma_f32_16x16x32_bf16 v[58:61], v[142:145], v[192:195], v[58:61]
	v_mfma_f32_16x16x32_bf16 v[46:49], v[134:137], v[200:203], v[46:49]
	v_mfma_f32_16x16x32_bf16 v[42:45], v[142:145], v[200:203], v[42:45]
	v_mfma_f32_16x16x32_bf16 v[30:33], v[134:137], v[210:213], v[30:33]
	v_mfma_f32_16x16x32_bf16 v[26:29], v[142:145], v[210:213], v[26:29]
	v_mfma_f32_16x16x32_bf16 v[14:17], v[134:137], v[218:221], v[14:17]
	v_mfma_f32_16x16x32_bf16 v[10:13], v[142:145], v[218:221], v[10:13]
	s_setprio 0
	s_setprio 1
	v_mfma_f32_16x16x32_bf16 v[54:57], v[164:167], v[188:191], v[54:57]
	v_mfma_f32_16x16x32_bf16 v[50:53], v[180:183], v[188:191], v[50:53]
	v_mfma_f32_16x16x32_bf16 v[38:41], v[164:167], v[196:199], v[38:41]
	v_mfma_f32_16x16x32_bf16 v[34:37], v[180:183], v[196:199], v[34:37]
	v_mfma_f32_16x16x32_bf16 v[22:25], v[164:167], v[206:209], v[22:25]
	v_mfma_f32_16x16x32_bf16 v[18:21], v[180:183], v[206:209], v[18:21]
	v_mfma_f32_16x16x32_bf16 v[6:9], v[164:167], v[214:217], v[6:9]
	v_mfma_f32_16x16x32_bf16 v[2:5], v[180:183], v[214:217], v[2:5]
	v_mfma_f32_16x16x32_bf16 v[54:57], v[176:179], v[192:195], v[54:57]
	v_mfma_f32_16x16x32_bf16 v[50:53], v[184:187], v[192:195], v[50:53]
	v_mfma_f32_16x16x32_bf16 v[38:41], v[176:179], v[200:203], v[38:41]
	v_mfma_f32_16x16x32_bf16 v[34:37], v[184:187], v[200:203], v[34:37]
	v_mfma_f32_16x16x32_bf16 v[22:25], v[176:179], v[210:213], v[22:25]
	v_mfma_f32_16x16x32_bf16 v[18:21], v[184:187], v[210:213], v[18:21]
	v_mfma_f32_16x16x32_bf16 v[6:9], v[176:179], v[218:221], v[6:9]
	v_mfma_f32_16x16x32_bf16 v[2:5], v[184:187], v[218:221], v[2:5]
	s_setprio 0
	s_barrier
	s_add_i32 s25, 0, 0x18000
	s_add_i32 s30, 0, 0x1c000
	v_add_u32_e32 v142, s25, v171
	v_add_u32_e32 v175, s30, v171
	ds_read_b128 v[130:133], v142
	ds_read_b128 v[134:137], v142 offset:1024
	ds_read_b128 v[138:141], v142 offset:2048
	ds_read_b128 v[142:145], v142 offset:3072
	ds_read_b128 v[164:167], v175
	ds_read_b128 v[176:179], v175 offset:1024
	ds_read_b128 v[180:183], v175 offset:2048
	ds_read_b128 v[184:187], v175 offset:3072
	s_add_u32 s28, s68, 0x40000
	s_addc_u32 s29, s69, 0
	s_mov_b32 m0, s75
	v_lshl_add_u64 v[228:229], s[28:29], 0, v[152:153]
	ds_read_b128 v[188:191], v174 offset:32768
	ds_read_b128 v[192:195], v174 offset:33792
	ds_read_b128 v[196:199], v174 offset:34816
	ds_read_b128 v[200:203], v174 offset:35840
	ds_read_b128 v[206:209], v174 offset:36864
	ds_read_b128 v[210:213], v174 offset:37888
	ds_read_b128 v[214:217], v174 offset:38912
	ds_read_b128 v[218:221], v174 offset:39936
	global_load_lds_dwordx4 v[228:229], off
	v_lshl_add_u64 v[228:229], s[28:29], 0, v[148:149]
	s_mov_b32 m0, s76
	s_nop 0
	global_load_lds_dwordx4 v[228:229], off
	s_waitcnt vmcnt(8)
	s_waitcnt lgkmcnt(0)
	s_barrier
	s_setprio 1
	s_waitcnt lgkmcnt(0)
	v_mfma_f32_16x16x32_bf16 v[126:129], v[130:133], v[188:191], v[126:129]
	v_mfma_f32_16x16x32_bf16 v[122:125], v[138:141], v[188:191], v[122:125]
	v_mfma_f32_16x16x32_bf16 v[110:113], v[130:133], v[196:199], v[110:113]
	v_mfma_f32_16x16x32_bf16 v[106:109], v[138:141], v[196:199], v[106:109]
	v_mfma_f32_16x16x32_bf16 v[94:97], v[130:133], v[206:209], v[94:97]
	v_mfma_f32_16x16x32_bf16 v[90:93], v[138:141], v[206:209], v[90:93]
	v_mfma_f32_16x16x32_bf16 v[78:81], v[130:133], v[214:217], v[78:81]
	v_mfma_f32_16x16x32_bf16 v[74:77], v[138:141], v[214:217], v[74:77]
	v_mfma_f32_16x16x32_bf16 v[126:129], v[134:137], v[192:195], v[126:129]
	v_mfma_f32_16x16x32_bf16 v[122:125], v[142:145], v[192:195], v[122:125]
	v_mfma_f32_16x16x32_bf16 v[110:113], v[134:137], v[200:203], v[110:113]
	v_mfma_f32_16x16x32_bf16 v[106:109], v[142:145], v[200:203], v[106:109]
	v_mfma_f32_16x16x32_bf16 v[94:97], v[134:137], v[210:213], v[94:97]
	v_mfma_f32_16x16x32_bf16 v[90:93], v[142:145], v[210:213], v[90:93]
	v_mfma_f32_16x16x32_bf16 v[78:81], v[134:137], v[218:221], v[78:81]
	v_mfma_f32_16x16x32_bf16 v[74:77], v[142:145], v[218:221], v[74:77]
	s_setprio 0
	s_setprio 1
	v_mfma_f32_16x16x32_bf16 v[118:121], v[164:167], v[188:191], v[118:121]
	v_mfma_f32_16x16x32_bf16 v[114:117], v[180:183], v[188:191], v[114:117]
	v_mfma_f32_16x16x32_bf16 v[102:105], v[164:167], v[196:199], v[102:105]
	v_mfma_f32_16x16x32_bf16 v[98:101], v[180:183], v[196:199], v[98:101]
	v_mfma_f32_16x16x32_bf16 v[86:89], v[164:167], v[206:209], v[86:89]
	v_mfma_f32_16x16x32_bf16 v[82:85], v[180:183], v[206:209], v[82:85]
	v_mfma_f32_16x16x32_bf16 v[70:73], v[164:167], v[214:217], v[70:73]
	v_mfma_f32_16x16x32_bf16 v[66:69], v[180:183], v[214:217], v[66:69]
	v_mfma_f32_16x16x32_bf16 v[118:121], v[176:179], v[192:195], v[118:121]
	v_mfma_f32_16x16x32_bf16 v[114:117], v[184:187], v[192:195], v[114:117]
	v_mfma_f32_16x16x32_bf16 v[102:105], v[176:179], v[200:203], v[102:105]
	v_mfma_f32_16x16x32_bf16 v[98:101], v[184:187], v[200:203], v[98:101]
	v_mfma_f32_16x16x32_bf16 v[86:89], v[176:179], v[210:213], v[86:89]
	v_mfma_f32_16x16x32_bf16 v[82:85], v[184:187], v[210:213], v[82:85]
	v_mfma_f32_16x16x32_bf16 v[70:73], v[176:179], v[218:221], v[70:73]
	v_mfma_f32_16x16x32_bf16 v[66:69], v[184:187], v[218:221], v[66:69]
	s_setprio 0
	s_barrier
	s_add_i32 s25, s25, s70
	v_lshl_add_u64 v[168:169], v[168:169], 0, s[36:37]
	s_mov_b32 m0, s25
	ds_read_b128 v[188:191], v174 offset:49152
	ds_read_b128 v[192:195], v174 offset:50176
	ds_read_b128 v[196:199], v174 offset:51200
	ds_read_b128 v[200:203], v174 offset:52224
	ds_read_b128 v[206:209], v174 offset:53248
	ds_read_b128 v[210:213], v174 offset:54272
	ds_read_b128 v[214:217], v174 offset:55296
	ds_read_b128 v[218:221], v174 offset:56320
	global_load_lds_dwordx4 v[168:169], off
	s_add_i32 m0, s25, 0x2000
	s_add_u32 s28, s66, 0x40080
	v_lshl_add_u64 v[168:169], v[222:223], 0, s[36:37]
	s_addc_u32 s29, s67, 0
	s_add_i32 s25, s30, s70
	global_load_lds_dwordx4 v[168:169], off
	v_lshl_add_u64 v[168:169], s[28:29], 0, v[150:151]
	s_mov_b32 m0, s25
	s_nop 0
	global_load_lds_dwordx4 v[168:169], off
	v_lshl_add_u64 v[168:169], s[28:29], 0, v[146:147]
	s_add_i32 m0, s25, 0x2000
	s_nop 0
	global_load_lds_dwordx4 v[168:169], off
	v_lshl_add_u64 v[168:169], v[224:225], 0, s[36:37]
	s_mov_b32 m0, s79
	s_nop 0
	global_load_lds_dwordx4 v[168:169], off
	v_lshl_add_u64 v[168:169], v[226:227], 0, s[36:37]
	s_mov_b32 m0, s80
	s_nop 0
	global_load_lds_dwordx4 v[168:169], off
	s_waitcnt vmcnt(8)
	s_waitcnt lgkmcnt(0)
	s_barrier
	s_setprio 1
	s_waitcnt lgkmcnt(0)
	v_mfma_f32_16x16x32_bf16 v[62:65], v[130:133], v[188:191], v[62:65]
	v_mfma_f32_16x16x32_bf16 v[58:61], v[138:141], v[188:191], v[58:61]
	v_mfma_f32_16x16x32_bf16 v[46:49], v[130:133], v[196:199], v[46:49]
	v_mfma_f32_16x16x32_bf16 v[42:45], v[138:141], v[196:199], v[42:45]
	v_mfma_f32_16x16x32_bf16 v[30:33], v[130:133], v[206:209], v[30:33]
	v_mfma_f32_16x16x32_bf16 v[26:29], v[138:141], v[206:209], v[26:29]
	v_mfma_f32_16x16x32_bf16 v[14:17], v[130:133], v[214:217], v[14:17]
	v_mfma_f32_16x16x32_bf16 v[10:13], v[138:141], v[214:217], v[10:13]
	v_mfma_f32_16x16x32_bf16 v[62:65], v[134:137], v[192:195], v[62:65]
	v_mfma_f32_16x16x32_bf16 v[58:61], v[142:145], v[192:195], v[58:61]
	v_mfma_f32_16x16x32_bf16 v[46:49], v[134:137], v[200:203], v[46:49]
	v_mfma_f32_16x16x32_bf16 v[42:45], v[142:145], v[200:203], v[42:45]
	v_mfma_f32_16x16x32_bf16 v[30:33], v[134:137], v[210:213], v[30:33]
	v_mfma_f32_16x16x32_bf16 v[26:29], v[142:145], v[210:213], v[26:29]
	v_mfma_f32_16x16x32_bf16 v[14:17], v[134:137], v[218:221], v[14:17]
	v_mfma_f32_16x16x32_bf16 v[10:13], v[142:145], v[218:221], v[10:13]
	s_setprio 0
	s_setprio 1
	v_mfma_f32_16x16x32_bf16 v[54:57], v[164:167], v[188:191], v[54:57]
	v_mfma_f32_16x16x32_bf16 v[50:53], v[180:183], v[188:191], v[50:53]
	v_mfma_f32_16x16x32_bf16 v[38:41], v[164:167], v[196:199], v[38:41]
	v_mfma_f32_16x16x32_bf16 v[34:37], v[180:183], v[196:199], v[34:37]
	v_mfma_f32_16x16x32_bf16 v[22:25], v[164:167], v[206:209], v[22:25]
	v_mfma_f32_16x16x32_bf16 v[18:21], v[180:183], v[206:209], v[18:21]
	v_mfma_f32_16x16x32_bf16 v[6:9], v[164:167], v[214:217], v[6:9]
	v_mfma_f32_16x16x32_bf16 v[2:5], v[180:183], v[214:217], v[2:5]
	v_mfma_f32_16x16x32_bf16 v[54:57], v[176:179], v[192:195], v[54:57]
	v_mfma_f32_16x16x32_bf16 v[50:53], v[184:187], v[192:195], v[50:53]
	v_mfma_f32_16x16x32_bf16 v[38:41], v[176:179], v[200:203], v[38:41]
	v_mfma_f32_16x16x32_bf16 v[34:37], v[184:187], v[200:203], v[34:37]
	v_mfma_f32_16x16x32_bf16 v[22:25], v[176:179], v[210:213], v[22:25]
	v_mfma_f32_16x16x32_bf16 v[18:21], v[184:187], v[210:213], v[18:21]
	v_mfma_f32_16x16x32_bf16 v[6:9], v[176:179], v[218:221], v[6:9]
	v_mfma_f32_16x16x32_bf16 v[2:5], v[184:187], v[218:221], v[2:5]
	s_setprio 0
	s_barrier
	s_add_i32 s24, s24, 2
	s_add_u32 s64, s64, 0x100
	s_addc_u32 s65, s65, 0
	s_add_u32 s18, s18, 0x100
	s_addc_u32 s19, s19, 0
	s_cmp_gt_u32 s24, 13
	s_cbranch_scc0 .LBB0_1013
	s_and_b64 vcc, exec, s[38:39]
	s_cbranch_vccz .LBB0_1016
	s_barrier

.LBB0_1041:
	s_cmp_gt_i32 s59, 11
	s_cselect_b64 s[4:5], -1, 0
	s_and_b64 s[0:1], s[0:1], s[4:5]
	s_andn2_b64 vcc, exec, s[0:1]
	s_cbranch_vccnz .LBB0_1095
	s_waitcnt vmcnt(0) lgkmcnt(0)
	s_barrier
	s_mov_b64 s[0:1], exec
	v_readlane_b32 s2, v249, 5
	v_readlane_b32 s3, v249, 6
	v_readlane_b32 s8, v249, 4
	s_and_b64 s[2:3], s[0:1], s[2:3]
	s_mov_b64 exec, s[2:3]
	s_cbranch_execz .Lgb_8_done
	v_mov_b32_e32 v1, 0x27e00
	ds_read2_b32 v[2:3], v1 offset1:1
	s_lshl_b32 s8, s8, 8
	s_add_u32 s6, s56, s8
	s_addc_u32 s7, s57, 0
	v_mov_b32_e32 v4, 0x1000
	v_mov_b32_e32 v5, 1
	global_atomic_add v6, v4, v5, s[6:7] offset:1024 sc0
	buffer_inv sc1
	s_waitcnt lgkmcnt(0)
	v_mul_lo_u32 v7, v2, 9
	s_waitcnt vmcnt(1)
	v_add_u32_e32 v6, 1, v6
	v_cmp_eq_u32_e32 vcc, v6, v7
	s_cbranch_vccz .Lgb_8_wait
	buffer_wbl2 sc1
	s_waitcnt vmcnt(0)
	v_mov_b32_e32 v4, 0x3000
	global_atomic_add v8, v4, v5, s[56:57] offset:1024 sc0
	v_mul_lo_u32 v7, v3, 9
	s_waitcnt vmcnt(0)
	v_add_u32_e32 v8, 1, v8
	v_cmp_eq_u32_e32 vcc, v8, v7
	s_cbranch_vccz .Lgb_8_wait
	v_mov_b32_e32 v9, 0x2400
	global_atomic_add v9, v5, s[56:57] offset:0
	global_atomic_add v9, v5, s[56:57] offset:256
	global_atomic_add v9, v5, s[56:57] offset:512
	global_atomic_add v9, v5, s[56:57] offset:768
	global_atomic_add v9, v5, s[56:57] offset:1024
	global_atomic_add v9, v5, s[56:57] offset:1280
	global_atomic_add v9, v5, s[56:57] offset:1536
	global_atomic_add v9, v5, s[56:57] offset:1792
	global_atomic_add v9, v5, s[56:57] offset:2048
	global_atomic_add v9, v5, s[56:57] offset:2304
	global_atomic_add v9, v5, s[56:57] offset:2560
	global_atomic_add v9, v5, s[56:57] offset:2816
	global_atomic_add v9, v5, s[56:57] offset:3072
	global_atomic_add v9, v5, s[56:57] offset:3328
	global_atomic_add v9, v5, s[56:57] offset:3584
	global_atomic_add v9, v5, s[56:57] offset:3840
	s_waitcnt vmcnt(0)
	s_branch .Lgb_8_done

.Lgb_8_spin:
	global_load_dword v8, v9, s[6:7] offset:1024 sc1
	s_waitcnt vmcnt(0)
	v_cmp_ne_u32_e32 vcc, 8, v8
	s_cbranch_vccnz .Lgb_8_done
	s_sleep 1
	s_add_u32 s8, s8, 1
	s_cmp_lt_u32 s8, 0x40000
	s_cbranch_scc1 .Lgb_8_spin

.LBB0_1214:
	s_cmp_gt_i32 s59, 12
	s_cselect_b64 s[4:5], -1, 0
	s_and_b64 s[6:7], s[36:37], s[4:5]
	s_andn2_b64 vcc, exec, s[6:7]
	s_cbranch_vccnz .LBB0_1268
	s_waitcnt vmcnt(0) lgkmcnt(0)
	s_barrier
	s_mov_b64 s[6:7], exec
	v_readlane_b32 s8, v249, 5
	v_readlane_b32 s9, v249, 6
	v_readlane_b32 s12, v249, 4
	s_and_b64 s[8:9], s[6:7], s[8:9]
	s_mov_b64 exec, s[8:9]
	s_cbranch_execz .Lgb_9_done
	v_mov_b32_e32 v1, 0x27e00
	ds_read2_b32 v[2:3], v1 offset1:1
	s_lshl_b32 s12, s12, 8
	s_add_u32 s10, s56, s12
	s_addc_u32 s11, s57, 0
	v_mov_b32_e32 v4, 0x1000
	v_mov_b32_e32 v5, 1
	global_atomic_add v6, v4, v5, s[10:11] offset:1024 sc0
	buffer_inv sc1
	s_waitcnt lgkmcnt(0)
	v_mul_lo_u32 v7, v2, 10
	s_waitcnt vmcnt(1)
	v_add_u32_e32 v6, 1, v6
	v_cmp_eq_u32_e32 vcc, v6, v7
	s_cbranch_vccz .Lgb_9_wait
	buffer_wbl2 sc1
	s_waitcnt vmcnt(0)
	v_mov_b32_e32 v4, 0x3000
	global_atomic_add v8, v4, v5, s[56:57] offset:1024 sc0
	v_mul_lo_u32 v7, v3, 10
	s_waitcnt vmcnt(0)
	v_add_u32_e32 v8, 1, v8
	v_cmp_eq_u32_e32 vcc, v8, v7
	s_cbranch_vccz .Lgb_9_wait
	v_mov_b32_e32 v9, 0x2400
	global_atomic_add v9, v5, s[56:57] offset:0
	global_atomic_add v9, v5, s[56:57] offset:256
	global_atomic_add v9, v5, s[56:57] offset:512
	global_atomic_add v9, v5, s[56:57] offset:768
	global_atomic_add v9, v5, s[56:57] offset:1024
	global_atomic_add v9, v5, s[56:57] offset:1280
	global_atomic_add v9, v5, s[56:57] offset:1536
	global_atomic_add v9, v5, s[56:57] offset:1792
	global_atomic_add v9, v5, s[56:57] offset:2048
	global_atomic_add v9, v5, s[56:57] offset:2304
	global_atomic_add v9, v5, s[56:57] offset:2560
	global_atomic_add v9, v5, s[56:57] offset:2816
	global_atomic_add v9, v5, s[56:57] offset:3072
	global_atomic_add v9, v5, s[56:57] offset:3328
	global_atomic_add v9, v5, s[56:57] offset:3584
	global_atomic_add v9, v5, s[56:57] offset:3840
	s_waitcnt vmcnt(0)
	s_branch .Lgb_9_done
.Lgb_9_wait:
	s_mov_b32 s12, 0
	v_mov_b32_e32 v9, 0x2000
.Lgb_9_spin:
	global_load_dword v8, v9, s[10:11] offset:1024 sc1
	s_waitcnt vmcnt(0)
	v_cmp_ne_u32_e32 vcc, 9, v8
	s_cbranch_vccnz .Lgb_9_done
	s_sleep 1
	s_add_u32 s12, s12, 1
	s_cmp_lt_u32 s12, 0x40000
	s_cbranch_scc1 .Lgb_9_spin
.Lgb_9_done:
	s_mov_b64 exec, s[6:7]
	s_waitcnt vmcnt(0) lgkmcnt(0)
	s_barrier

.LBB0_1275:
	s_cmp_gt_i32 s59, 13
	s_cselect_b64 s[4:5], -1, 0
	s_and_b64 s[6:7], s[6:7], s[4:5]
	s_andn2_b64 vcc, exec, s[6:7]
	s_cbranch_vccnz .LBB0_1329
	s_waitcnt vmcnt(0) lgkmcnt(0)
	s_barrier
	s_mov_b64 s[6:7], exec
	v_readlane_b32 s8, v249, 5
	v_readlane_b32 s9, v249, 6
	v_readlane_b32 s12, v249, 4
	s_and_b64 s[8:9], s[6:7], s[8:9]
	s_mov_b64 exec, s[8:9]
	s_cbranch_execz .Lgb_10_done
	v_mov_b32_e32 v1, 0x27e00
	ds_read2_b32 v[2:3], v1 offset1:1
	s_lshl_b32 s12, s12, 8
	s_add_u32 s10, s56, s12
	s_addc_u32 s11, s57, 0
	v_mov_b32_e32 v4, 0x1000
	v_mov_b32_e32 v5, 1
	global_atomic_add v6, v4, v5, s[10:11] offset:1024 sc0
	buffer_inv sc1
	s_waitcnt lgkmcnt(0)
	v_mul_lo_u32 v7, v2, 11
	s_waitcnt vmcnt(1)
	v_add_u32_e32 v6, 1, v6
	v_cmp_eq_u32_e32 vcc, v6, v7
	s_cbranch_vccz .Lgb_10_wait
	buffer_wbl2 sc1
	s_waitcnt vmcnt(0)
	v_mov_b32_e32 v4, 0x3000
	global_atomic_add v8, v4, v5, s[56:57] offset:1024 sc0
	v_mul_lo_u32 v7, v3, 11
	s_waitcnt vmcnt(0)
	v_add_u32_e32 v8, 1, v8
	v_cmp_eq_u32_e32 vcc, v8, v7
	s_cbranch_vccz .Lgb_10_wait
	v_mov_b32_e32 v9, 0x2400
	global_atomic_add v9, v5, s[56:57] offset:0
	global_atomic_add v9, v5, s[56:57] offset:256
	global_atomic_add v9, v5, s[56:57] offset:512
	global_atomic_add v9, v5, s[56:57] offset:768
	global_atomic_add v9, v5, s[56:57] offset:1024
	global_atomic_add v9, v5, s[56:57] offset:1280
	global_atomic_add v9, v5, s[56:57] offset:1536
	global_atomic_add v9, v5, s[56:57] offset:1792
	global_atomic_add v9, v5, s[56:57] offset:2048
	global_atomic_add v9, v5, s[56:57] offset:2304
	global_atomic_add v9, v5, s[56:57] offset:2560
	global_atomic_add v9, v5, s[56:57] offset:2816
	global_atomic_add v9, v5, s[56:57] offset:3072
	global_atomic_add v9, v5, s[56:57] offset:3328
	global_atomic_add v9, v5, s[56:57] offset:3584
	global_atomic_add v9, v5, s[56:57] offset:3840
	s_waitcnt vmcnt(0)
	s_branch .Lgb_10_done

.Lgb_10_spin:
	global_load_dword v8, v9, s[10:11] offset:1024 sc1
	s_waitcnt vmcnt(0)
	v_cmp_ne_u32_e32 vcc, 10, v8
	s_cbranch_vccnz .Lgb_10_done
	s_sleep 1
	s_add_u32 s12, s12, 1
	s_cmp_lt_u32 s12, 0x40000
	s_cbranch_scc1 .Lgb_10_spin

.LBB0_1346:
	s_cmp_lt_i32 s58, 14
	s_cselect_b64 s[2:3], -1, 0
	s_cmp_gt_i32 s59, 14
	s_cselect_b64 s[0:1], -1, 0
	s_and_b64 s[2:3], s[2:3], s[0:1]
	s_andn2_b64 vcc, exec, s[2:3]
	s_cbranch_vccnz .LBB0_1400
	s_waitcnt vmcnt(0) lgkmcnt(0)
	s_barrier
	s_mov_b64 s[2:3], exec
	v_readlane_b32 s4, v249, 5
	v_readlane_b32 s5, v249, 6
	v_readlane_b32 s8, v249, 4
	s_and_b64 s[4:5], s[2:3], s[4:5]
	s_mov_b64 exec, s[4:5]
	s_cbranch_execz .Lgb_11_done
	v_mov_b32_e32 v1, 0x27e00
	ds_read2_b32 v[2:3], v1 offset1:1
	s_lshl_b32 s8, s8, 8
	s_add_u32 s6, s56, s8
	s_addc_u32 s7, s57, 0
	v_mov_b32_e32 v4, 0x1000
	v_mov_b32_e32 v5, 1
	global_atomic_add v6, v4, v5, s[6:7] offset:1024 sc0
	buffer_inv sc1
	s_waitcnt lgkmcnt(0)
	v_mul_lo_u32 v7, v2, 12
	s_waitcnt vmcnt(1)
	v_add_u32_e32 v6, 1, v6
	v_cmp_eq_u32_e32 vcc, v6, v7
	s_cbranch_vccz .Lgb_11_wait
	buffer_wbl2 sc1
	s_waitcnt vmcnt(0)
	v_mov_b32_e32 v4, 0x3000
	global_atomic_add v8, v4, v5, s[56:57] offset:1024 sc0
	v_mul_lo_u32 v7, v3, 12
	s_waitcnt vmcnt(0)
	v_add_u32_e32 v8, 1, v8
	v_cmp_eq_u32_e32 vcc, v8, v7
	s_cbranch_vccz .Lgb_11_wait
	v_mov_b32_e32 v9, 0x2400
	global_atomic_add v9, v5, s[56:57] offset:0
	global_atomic_add v9, v5, s[56:57] offset:256
	global_atomic_add v9, v5, s[56:57] offset:512
	global_atomic_add v9, v5, s[56:57] offset:768
	global_atomic_add v9, v5, s[56:57] offset:1024
	global_atomic_add v9, v5, s[56:57] offset:1280
	global_atomic_add v9, v5, s[56:57] offset:1536
	global_atomic_add v9, v5, s[56:57] offset:1792
	global_atomic_add v9, v5, s[56:57] offset:2048
	global_atomic_add v9, v5, s[56:57] offset:2304
	global_atomic_add v9, v5, s[56:57] offset:2560
	global_atomic_add v9, v5, s[56:57] offset:2816
	global_atomic_add v9, v5, s[56:57] offset:3072
	global_atomic_add v9, v5, s[56:57] offset:3328
	global_atomic_add v9, v5, s[56:57] offset:3584
	global_atomic_add v9, v5, s[56:57] offset:3840
	s_waitcnt vmcnt(0)
	s_branch .Lgb_11_done

.Lgb_11_spin:
	global_load_dword v8, v9, s[6:7] offset:1024 sc1
	s_waitcnt vmcnt(0)
	v_cmp_ne_u32_e32 vcc, 11, v8
	s_cbranch_vccnz .Lgb_11_done
	s_sleep 1
	s_add_u32 s8, s8, 1
	s_cmp_lt_u32 s8, 0x40000
	s_cbranch_scc1 .Lgb_11_spin

.LBB0_1428:
	s_add_i32 s66, s94, 2
	s_add_u32 s67, s10, 0xfffc0080
	s_addc_u32 s72, s11, -1
	s_cmp_eq_u32 s85, s94
	s_cselect_b32 s97, s14, s72
	s_cselect_b32 s96, s15, s67
	s_cselect_b32 s95, s51, vcc_hi
	s_cselect_b32 s94, s84, vcc_lo
	s_add_i32 s67, 0, 0x10000
	s_add_i32 s62, 0, 0x14000
	v_add_u32_e32 v126, s67, v199
	v_add_u32_e32 v158, s62, v199
	ds_read_b128 v[114:117], v126
	ds_read_b128 v[118:121], v126 offset:1024
	ds_read_b128 v[122:125], v126 offset:2048
	ds_read_b128 v[126:129], v126 offset:3072
	ds_read_b128 v[146:149], v158
	ds_read_b128 v[150:153], v158 offset:1024
	ds_read_b128 v[154:157], v158 offset:2048
	ds_read_b128 v[158:161], v158 offset:3072
	v_lshl_add_u64 v[202:203], s[10:11], 0, v[196:197]
	s_add_i32 m0, s28, 0xc000
	ds_read_b128 v[162:165], v214
	ds_read_b128 v[166:169], v214 offset:1024
	ds_read_b128 v[216:219], v214 offset:2048
	ds_read_b128 v[220:223], v214 offset:3072
	ds_read_b128 v[224:227], v214 offset:4096
	ds_read_b128 v[228:231], v214 offset:5120
	ds_read_b128 v[232:235], v214 offset:6144
	ds_read_b128 v[236:239], v214 offset:7168
	global_load_lds_dwordx4 v[202:203], off
	v_lshl_add_u64 v[202:203], s[10:11], 0, v[176:177]
	s_add_i32 m0, s28, 0xe000
	s_nop 0
	global_load_lds_dwordx4 v[202:203], off
	s_waitcnt vmcnt(8)
	s_waitcnt lgkmcnt(0)
	s_barrier
	s_setprio 1
	s_waitcnt lgkmcnt(0)
	v_mfma_f32_16x16x32_bf16 v[142:145], v[114:117], v[162:165], v[142:145]
	v_mfma_f32_16x16x32_bf16 v[138:141], v[122:125], v[162:165], v[138:141]
	v_mfma_f32_16x16x32_bf16 v[110:113], v[114:117], v[216:219], v[110:113]
	v_mfma_f32_16x16x32_bf16 v[106:109], v[122:125], v[216:219], v[106:109]
	v_mfma_f32_16x16x32_bf16 v[98:101], v[114:117], v[224:227], v[98:101]
	v_mfma_f32_16x16x32_bf16 v[90:93], v[122:125], v[224:227], v[90:93]
	v_mfma_f32_16x16x32_bf16 v[82:85], v[114:117], v[232:235], v[82:85]
	v_mfma_f32_16x16x32_bf16 v[74:77], v[122:125], v[232:235], v[74:77]
	v_mfma_f32_16x16x32_bf16 v[142:145], v[118:121], v[166:169], v[142:145]
	v_mfma_f32_16x16x32_bf16 v[138:141], v[126:129], v[166:169], v[138:141]
	v_mfma_f32_16x16x32_bf16 v[110:113], v[118:121], v[220:223], v[110:113]
	v_mfma_f32_16x16x32_bf16 v[106:109], v[126:129], v[220:223], v[106:109]
	v_mfma_f32_16x16x32_bf16 v[98:101], v[118:121], v[228:231], v[98:101]
	v_mfma_f32_16x16x32_bf16 v[90:93], v[126:129], v[228:231], v[90:93]
	v_mfma_f32_16x16x32_bf16 v[82:85], v[118:121], v[236:239], v[82:85]
	v_mfma_f32_16x16x32_bf16 v[74:77], v[126:129], v[236:239], v[74:77]
	s_setprio 0
	s_setprio 1
	v_mfma_f32_16x16x32_bf16 v[134:137], v[146:149], v[162:165], v[134:137]
	v_mfma_f32_16x16x32_bf16 v[130:133], v[154:157], v[162:165], v[130:133]
	v_mfma_f32_16x16x32_bf16 v[102:105], v[146:149], v[216:219], v[102:105]
	v_mfma_f32_16x16x32_bf16 v[94:97], v[154:157], v[216:219], v[94:97]
	v_mfma_f32_16x16x32_bf16 v[86:89], v[146:149], v[224:227], v[86:89]
	v_mfma_f32_16x16x32_bf16 v[78:81], v[154:157], v[224:227], v[78:81]
	v_mfma_f32_16x16x32_bf16 v[70:73], v[146:149], v[232:235], v[70:73]
	v_mfma_f32_16x16x32_bf16 v[66:69], v[154:157], v[232:235], v[66:69]
	v_mfma_f32_16x16x32_bf16 v[134:137], v[150:153], v[166:169], v[134:137]
	v_mfma_f32_16x16x32_bf16 v[130:133], v[158:161], v[166:169], v[130:133]
	v_mfma_f32_16x16x32_bf16 v[102:105], v[150:153], v[220:223], v[102:105]
	v_mfma_f32_16x16x32_bf16 v[94:97], v[158:161], v[220:223], v[94:97]
	v_mfma_f32_16x16x32_bf16 v[86:89], v[150:153], v[228:231], v[86:89]
	v_mfma_f32_16x16x32_bf16 v[78:81], v[158:161], v[228:231], v[78:81]
	v_mfma_f32_16x16x32_bf16 v[70:73], v[150:153], v[236:239], v[70:73]
	v_mfma_f32_16x16x32_bf16 v[66:69], v[158:161], v[236:239], v[66:69]
	s_setprio 0
	s_barrier
	s_add_i32 s63, s67, s17
	v_lshl_add_u64 v[202:203], s[94:95], 0, v[174:175]
	s_mov_b32 m0, s63
	ds_read_b128 v[162:165], v214 offset:16384
	ds_read_b128 v[166:169], v214 offset:17408
	ds_read_b128 v[216:219], v214 offset:18432
	ds_read_b128 v[220:223], v214 offset:19456
	ds_read_b128 v[224:227], v214 offset:20480
	ds_read_b128 v[228:231], v214 offset:21504
	ds_read_b128 v[232:235], v214 offset:22528
	ds_read_b128 v[236:239], v214 offset:23552
	global_load_lds_dwordx4 v[202:203], off
	s_add_i32 m0, s63, 0x2000
	s_add_u32 s72, s94, 0x40000
	v_lshl_add_u64 v[240:241], s[94:95], 0, v[178:179]
	s_addc_u32 s73, s95, 0
	s_add_i32 s62, s62, s17
	global_load_lds_dwordx4 v[240:241], off
	v_lshl_add_u64 v[242:243], s[72:73], 0, v[174:175]
	s_mov_b32 m0, s62
	v_lshl_add_u64 v[244:245], s[96:97], 0, v[176:177]
	global_load_lds_dwordx4 v[242:243], off
	v_lshl_add_u64 v[242:243], s[72:73], 0, v[178:179]
	s_add_i32 m0, s62, 0x2000
	s_nop 0
	global_load_lds_dwordx4 v[242:243], off
	v_lshl_add_u64 v[242:243], s[96:97], 0, v[172:173]
	s_mov_b32 m0, s28
	s_nop 0
	global_load_lds_dwordx4 v[242:243], off
	s_mov_b32 m0, s29
	s_nop 0
	global_load_lds_dwordx4 v[244:245], off
	s_waitcnt vmcnt(8)
	s_waitcnt lgkmcnt(0)
	s_barrier
	s_setprio 1
	s_waitcnt lgkmcnt(0)
	v_mfma_f32_16x16x32_bf16 v[62:65], v[114:117], v[162:165], v[62:65]
	v_mfma_f32_16x16x32_bf16 v[58:61], v[122:125], v[162:165], v[58:61]
	v_mfma_f32_16x16x32_bf16 v[50:53], v[114:117], v[216:219], v[50:53]
	v_mfma_f32_16x16x32_bf16 v[42:45], v[122:125], v[216:219], v[42:45]
	v_mfma_f32_16x16x32_bf16 v[34:37], v[114:117], v[224:227], v[34:37]
	v_mfma_f32_16x16x32_bf16 v[26:29], v[122:125], v[224:227], v[26:29]
	v_mfma_f32_16x16x32_bf16 v[18:21], v[114:117], v[232:235], v[18:21]
	v_mfma_f32_16x16x32_bf16 v[10:13], v[122:125], v[232:235], v[10:13]
	v_mfma_f32_16x16x32_bf16 v[62:65], v[118:121], v[166:169], v[62:65]
	v_mfma_f32_16x16x32_bf16 v[58:61], v[126:129], v[166:169], v[58:61]
	v_mfma_f32_16x16x32_bf16 v[50:53], v[118:121], v[220:223], v[50:53]
	v_mfma_f32_16x16x32_bf16 v[42:45], v[126:129], v[220:223], v[42:45]
	v_mfma_f32_16x16x32_bf16 v[34:37], v[118:121], v[228:231], v[34:37]
	v_mfma_f32_16x16x32_bf16 v[26:29], v[126:129], v[228:231], v[26:29]
	v_mfma_f32_16x16x32_bf16 v[18:21], v[118:121], v[236:239], v[18:21]
	v_mfma_f32_16x16x32_bf16 v[10:13], v[126:129], v[236:239], v[10:13]
	s_setprio 0
	s_setprio 1
	v_mfma_f32_16x16x32_bf16 v[54:57], v[146:149], v[162:165], v[54:57]
	v_mfma_f32_16x16x32_bf16 v[46:49], v[154:157], v[162:165], v[46:49]
	v_mfma_f32_16x16x32_bf16 v[38:41], v[146:149], v[216:219], v[38:41]
	v_mfma_f32_16x16x32_bf16 v[30:33], v[154:157], v[216:219], v[30:33]
	v_mfma_f32_16x16x32_bf16 v[22:25], v[146:149], v[224:227], v[22:25]
	v_mfma_f32_16x16x32_bf16 v[14:17], v[154:157], v[224:227], v[14:17]
	v_mfma_f32_16x16x32_bf16 v[6:9], v[146:149], v[232:235], v[6:9]
	v_mfma_f32_16x16x32_bf16 v[2:5], v[154:157], v[232:235], v[2:5]
	v_mfma_f32_16x16x32_bf16 v[54:57], v[150:153], v[166:169], v[54:57]
	v_mfma_f32_16x16x32_bf16 v[46:49], v[158:161], v[166:169], v[46:49]
	v_mfma_f32_16x16x32_bf16 v[38:41], v[150:153], v[220:223], v[38:41]
	v_mfma_f32_16x16x32_bf16 v[30:33], v[158:161], v[220:223], v[30:33]
	v_mfma_f32_16x16x32_bf16 v[22:25], v[150:153], v[228:231], v[22:25]
	v_mfma_f32_16x16x32_bf16 v[14:17], v[158:161], v[228:231], v[14:17]
	v_mfma_f32_16x16x32_bf16 v[6:9], v[150:153], v[236:239], v[6:9]
	v_mfma_f32_16x16x32_bf16 v[2:5], v[158:161], v[236:239], v[2:5]
	s_setprio 0
	s_barrier
	s_add_i32 s62, 0, 0x18000
	s_add_i32 s63, 0, 0x1c000
	v_add_u32_e32 v126, s62, v199
	v_add_u32_e32 v158, s63, v199
	ds_read_b128 v[114:117], v126
	ds_read_b128 v[118:121], v126 offset:1024
	ds_read_b128 v[122:125], v126 offset:2048
	ds_read_b128 v[126:129], v126 offset:3072
	ds_read_b128 v[146:149], v158
	ds_read_b128 v[150:153], v158 offset:1024
	ds_read_b128 v[154:157], v158 offset:2048
	ds_read_b128 v[158:161], v158 offset:3072
	s_add_u32 s72, s96, 0x40000
	s_addc_u32 s73, s97, 0
	s_mov_b32 m0, s30
	v_lshl_add_u64 v[246:247], s[72:73], 0, v[172:173]
	ds_read_b128 v[162:165], v214 offset:32768
	ds_read_b128 v[166:169], v214 offset:33792
	ds_read_b128 v[216:219], v214 offset:34816
	ds_read_b128 v[220:223], v214 offset:35840
	ds_read_b128 v[224:227], v214 offset:36864
	ds_read_b128 v[228:231], v214 offset:37888
	ds_read_b128 v[232:235], v214 offset:38912
	ds_read_b128 v[236:239], v214 offset:39936
	global_load_lds_dwordx4 v[246:247], off
	v_lshl_add_u64 v[246:247], s[72:73], 0, v[176:177]
	s_mov_b32 m0, s31
	s_nop 0
	global_load_lds_dwordx4 v[246:247], off
	s_waitcnt vmcnt(8)
	s_waitcnt lgkmcnt(0)
	s_barrier
	s_setprio 1
	s_waitcnt lgkmcnt(0)
	v_mfma_f32_16x16x32_bf16 v[142:145], v[114:117], v[162:165], v[142:145]
	v_mfma_f32_16x16x32_bf16 v[138:141], v[122:125], v[162:165], v[138:141]
	v_mfma_f32_16x16x32_bf16 v[110:113], v[114:117], v[216:219], v[110:113]
	v_mfma_f32_16x16x32_bf16 v[106:109], v[122:125], v[216:219], v[106:109]
	v_mfma_f32_16x16x32_bf16 v[98:101], v[114:117], v[224:227], v[98:101]
	v_mfma_f32_16x16x32_bf16 v[90:93], v[122:125], v[224:227], v[90:93]
	v_mfma_f32_16x16x32_bf16 v[82:85], v[114:117], v[232:235], v[82:85]
	v_mfma_f32_16x16x32_bf16 v[74:77], v[122:125], v[232:235], v[74:77]
	v_mfma_f32_16x16x32_bf16 v[142:145], v[118:121], v[166:169], v[142:145]
	v_mfma_f32_16x16x32_bf16 v[138:141], v[126:129], v[166:169], v[138:141]
	v_mfma_f32_16x16x32_bf16 v[110:113], v[118:121], v[220:223], v[110:113]
	v_mfma_f32_16x16x32_bf16 v[106:109], v[126:129], v[220:223], v[106:109]
	v_mfma_f32_16x16x32_bf16 v[98:101], v[118:121], v[228:231], v[98:101]
	v_mfma_f32_16x16x32_bf16 v[90:93], v[126:129], v[228:231], v[90:93]
	v_mfma_f32_16x16x32_bf16 v[82:85], v[118:121], v[236:239], v[82:85]
	v_mfma_f32_16x16x32_bf16 v[74:77], v[126:129], v[236:239], v[74:77]
	s_setprio 0
	s_setprio 1
	v_mfma_f32_16x16x32_bf16 v[134:137], v[146:149], v[162:165], v[134:137]
	v_mfma_f32_16x16x32_bf16 v[130:133], v[154:157], v[162:165], v[130:133]
	v_mfma_f32_16x16x32_bf16 v[102:105], v[146:149], v[216:219], v[102:105]
	v_mfma_f32_16x16x32_bf16 v[94:97], v[154:157], v[216:219], v[94:97]
	v_mfma_f32_16x16x32_bf16 v[86:89], v[146:149], v[224:227], v[86:89]
	v_mfma_f32_16x16x32_bf16 v[78:81], v[154:157], v[224:227], v[78:81]
	v_mfma_f32_16x16x32_bf16 v[70:73], v[146:149], v[232:235], v[70:73]
	v_mfma_f32_16x16x32_bf16 v[66:69], v[154:157], v[232:235], v[66:69]
	v_mfma_f32_16x16x32_bf16 v[134:137], v[150:153], v[166:169], v[134:137]
	v_mfma_f32_16x16x32_bf16 v[130:133], v[158:161], v[166:169], v[130:133]
	v_mfma_f32_16x16x32_bf16 v[102:105], v[150:153], v[220:223], v[102:105]
	v_mfma_f32_16x16x32_bf16 v[94:97], v[158:161], v[220:223], v[94:97]
	v_mfma_f32_16x16x32_bf16 v[86:89], v[150:153], v[228:231], v[86:89]
	v_mfma_f32_16x16x32_bf16 v[78:81], v[158:161], v[228:231], v[78:81]
	v_mfma_f32_16x16x32_bf16 v[70:73], v[150:153], v[236:239], v[70:73]
	v_mfma_f32_16x16x32_bf16 v[66:69], v[158:161], v[236:239], v[66:69]
	s_setprio 0
	s_barrier
	s_add_i32 s62, s62, s17
	v_lshl_add_u64 v[202:203], v[202:203], 0, s[76:77]
	s_mov_b32 m0, s62
	ds_read_b128 v[162:165], v214 offset:49152
	ds_read_b128 v[166:169], v214 offset:50176
	ds_read_b128 v[216:219], v214 offset:51200
	ds_read_b128 v[220:223], v214 offset:52224
	ds_read_b128 v[224:227], v214 offset:53248
	ds_read_b128 v[228:231], v214 offset:54272
	ds_read_b128 v[232:235], v214 offset:55296
	ds_read_b128 v[236:239], v214 offset:56320
	global_load_lds_dwordx4 v[202:203], off
	s_add_i32 m0, s62, 0x2000
	s_add_u32 s72, s94, 0x40080
	v_lshl_add_u64 v[202:203], v[240:241], 0, s[76:77]
	s_addc_u32 s73, s95, 0
	s_add_i32 s62, s63, s17
	global_load_lds_dwordx4 v[202:203], off
	v_lshl_add_u64 v[202:203], s[72:73], 0, v[174:175]
	s_mov_b32 m0, s62
	s_nop 0
	global_load_lds_dwordx4 v[202:203], off
	v_lshl_add_u64 v[202:203], s[72:73], 0, v[178:179]
	s_add_i32 m0, s62, 0x2000
	s_nop 0
	global_load_lds_dwordx4 v[202:203], off
	v_lshl_add_u64 v[202:203], v[242:243], 0, s[76:77]
	s_mov_b32 m0, s44
	s_nop 0
	global_load_lds_dwordx4 v[202:203], off
	v_lshl_add_u64 v[202:203], v[244:245], 0, s[76:77]
	s_mov_b32 m0, s36
	s_nop 0
	global_load_lds_dwordx4 v[202:203], off
	s_waitcnt vmcnt(8)
	s_waitcnt lgkmcnt(0)
	s_barrier
	s_setprio 1
	s_waitcnt lgkmcnt(0)
	v_mfma_f32_16x16x32_bf16 v[62:65], v[114:117], v[162:165], v[62:65]
	v_mfma_f32_16x16x32_bf16 v[58:61], v[122:125], v[162:165], v[58:61]
	v_mfma_f32_16x16x32_bf16 v[50:53], v[114:117], v[216:219], v[50:53]
	v_mfma_f32_16x16x32_bf16 v[42:45], v[122:125], v[216:219], v[42:45]
	v_mfma_f32_16x16x32_bf16 v[34:37], v[114:117], v[224:227], v[34:37]
	v_mfma_f32_16x16x32_bf16 v[26:29], v[122:125], v[224:227], v[26:29]
	v_mfma_f32_16x16x32_bf16 v[18:21], v[114:117], v[232:235], v[18:21]
	v_mfma_f32_16x16x32_bf16 v[10:13], v[122:125], v[232:235], v[10:13]
	v_mfma_f32_16x16x32_bf16 v[62:65], v[118:121], v[166:169], v[62:65]
	v_mfma_f32_16x16x32_bf16 v[58:61], v[126:129], v[166:169], v[58:61]
	v_mfma_f32_16x16x32_bf16 v[50:53], v[118:121], v[220:223], v[50:53]
	v_mfma_f32_16x16x32_bf16 v[42:45], v[126:129], v[220:223], v[42:45]
	v_mfma_f32_16x16x32_bf16 v[34:37], v[118:121], v[228:231], v[34:37]
	v_mfma_f32_16x16x32_bf16 v[26:29], v[126:129], v[228:231], v[26:29]
	v_mfma_f32_16x16x32_bf16 v[18:21], v[118:121], v[236:239], v[18:21]
	v_mfma_f32_16x16x32_bf16 v[10:13], v[126:129], v[236:239], v[10:13]
	s_setprio 0
	s_setprio 1
	v_mfma_f32_16x16x32_bf16 v[54:57], v[146:149], v[162:165], v[54:57]
	v_mfma_f32_16x16x32_bf16 v[46:49], v[154:157], v[162:165], v[46:49]
	v_mfma_f32_16x16x32_bf16 v[38:41], v[146:149], v[216:219], v[38:41]
	v_mfma_f32_16x16x32_bf16 v[30:33], v[154:157], v[216:219], v[30:33]
	v_mfma_f32_16x16x32_bf16 v[22:25], v[146:149], v[224:227], v[22:25]
	v_mfma_f32_16x16x32_bf16 v[14:17], v[154:157], v[224:227], v[14:17]
	v_mfma_f32_16x16x32_bf16 v[6:9], v[146:149], v[232:235], v[6:9]
	v_mfma_f32_16x16x32_bf16 v[2:5], v[154:157], v[232:235], v[2:5]
	v_mfma_f32_16x16x32_bf16 v[54:57], v[150:153], v[166:169], v[54:57]
	v_mfma_f32_16x16x32_bf16 v[46:49], v[158:161], v[166:169], v[46:49]
	v_mfma_f32_16x16x32_bf16 v[38:41], v[150:153], v[220:223], v[38:41]
	v_mfma_f32_16x16x32_bf16 v[30:33], v[158:161], v[220:223], v[30:33]
	v_mfma_f32_16x16x32_bf16 v[22:25], v[150:153], v[228:231], v[22:25]
	v_mfma_f32_16x16x32_bf16 v[14:17], v[158:161], v[228:231], v[14:17]
	v_mfma_f32_16x16x32_bf16 v[6:9], v[150:153], v[236:239], v[6:9]
	v_mfma_f32_16x16x32_bf16 v[2:5], v[158:161], v[236:239], v[2:5]
	s_setprio 0
	s_barrier
	s_add_u32 s10, s10, 0x100
	s_addc_u32 s11, s11, 0
	s_add_u32 vcc_lo, vcc_lo, 0x100
	s_addc_u32 vcc_hi, vcc_hi, 0
	s_cmp_ge_i32 s66, s18
	s_mov_b32 s94, s66
	s_cbranch_scc0 .LBB0_1428
	s_and_b64 vcc, exec, s[82:83]
	s_cbranch_vccz .LBB0_1431
	s_barrier

.LBB0_1555:
	s_cmp_gt_i32 s59, 16
	s_cselect_b64 s[4:5], -1, 0
	s_and_b64 s[0:1], s[10:11], s[4:5]
	s_andn2_b64 vcc, exec, s[0:1]
	s_cbranch_vccnz .LBB0_1609
	s_waitcnt vmcnt(0) lgkmcnt(0)
	s_barrier
	s_mov_b64 s[0:1], exec
	v_readlane_b32 s2, v249, 5
	v_readlane_b32 s3, v249, 6
	v_readlane_b32 s8, v249, 4
	s_and_b64 s[2:3], s[0:1], s[2:3]
	s_mov_b64 exec, s[2:3]
	s_cbranch_execz .Lgb_12_done
	v_mov_b32_e32 v1, 0x27e00
	ds_read2_b32 v[2:3], v1 offset1:1
	s_lshl_b32 s8, s8, 8
	s_add_u32 s6, s56, s8
	s_addc_u32 s7, s57, 0
	v_mov_b32_e32 v4, 0x1000
	v_mov_b32_e32 v5, 1
	global_atomic_add v6, v4, v5, s[6:7] offset:1024 sc0
	buffer_inv sc1
	s_waitcnt lgkmcnt(0)
	v_mul_lo_u32 v7, v2, 13
	s_waitcnt vmcnt(1)
	v_add_u32_e32 v6, 1, v6
	v_cmp_eq_u32_e32 vcc, v6, v7
	s_cbranch_vccz .Lgb_12_wait
	buffer_wbl2 sc1
	s_waitcnt vmcnt(0)
	v_mov_b32_e32 v4, 0x3000
	global_atomic_add v8, v4, v5, s[56:57] offset:1024 sc0
	v_mul_lo_u32 v7, v3, 13
	s_waitcnt vmcnt(0)
	v_add_u32_e32 v8, 1, v8
	v_cmp_eq_u32_e32 vcc, v8, v7
	s_cbranch_vccz .Lgb_12_wait
	v_mov_b32_e32 v9, 0x2400
	global_atomic_add v9, v5, s[56:57] offset:0
	global_atomic_add v9, v5, s[56:57] offset:256
	global_atomic_add v9, v5, s[56:57] offset:512
	global_atomic_add v9, v5, s[56:57] offset:768
	global_atomic_add v9, v5, s[56:57] offset:1024
	global_atomic_add v9, v5, s[56:57] offset:1280
	global_atomic_add v9, v5, s[56:57] offset:1536
	global_atomic_add v9, v5, s[56:57] offset:1792
	global_atomic_add v9, v5, s[56:57] offset:2048
	global_atomic_add v9, v5, s[56:57] offset:2304
	global_atomic_add v9, v5, s[56:57] offset:2560
	global_atomic_add v9, v5, s[56:57] offset:2816
	global_atomic_add v9, v5, s[56:57] offset:3072
	global_atomic_add v9, v5, s[56:57] offset:3328
	global_atomic_add v9, v5, s[56:57] offset:3584
	global_atomic_add v9, v5, s[56:57] offset:3840
	s_waitcnt vmcnt(0)
	s_branch .Lgb_12_done

.Lgb_12_spin:
	global_load_dword v8, v9, s[6:7] offset:1024 sc1
	s_waitcnt vmcnt(0)
	v_cmp_ne_u32_e32 vcc, 12, v8
	s_cbranch_vccnz .Lgb_12_done
	s_sleep 1
	s_add_u32 s8, s8, 1
	s_cmp_lt_u32 s8, 0x40000
	s_cbranch_scc1 .Lgb_12_spin

.LBB0_1619:
	ds_read_b128 v[154:157], v150
	ds_read_b128 v[158:161], v150 offset:1024
	ds_read_b128 v[162:165], v150 offset:2048
	ds_read_b128 v[166:169], v150 offset:3072
	ds_read_b128 v[170:173], v151
	ds_read_b128 v[174:177], v151 offset:1024
	ds_read_b128 v[178:181], v151 offset:2048
	ds_read_b128 v[182:185], v151 offset:3072
	s_add_u32 s30, s28, 0xfffc0080
	s_addc_u32 s31, s29, -1
	s_cmp_eq_u32 s62, 12
	s_cselect_b32 s37, s14, s31
	s_cselect_b32 s36, s15, s30
	s_cselect_b32 s31, s17, s51
	s_cselect_b32 s30, s49, s50
	v_lshl_add_u64 v[146:147], s[28:29], 0, v[138:139]
	s_add_i32 m0, s19, 0xc000
	ds_read_b128 v[186:189], v152
	ds_read_b128 v[190:193], v152 offset:1024
	ds_read_b128 v[194:197], v152 offset:2048
	ds_read_b128 v[198:201], v152 offset:3072
	ds_read_b128 v[206:209], v152 offset:4096
	ds_read_b128 v[210:213], v152 offset:5120
	ds_read_b128 v[214:217], v152 offset:6144
	ds_read_b128 v[218:221], v152 offset:7168
	global_load_lds_dwordx4 v[146:147], off
	v_lshl_add_u64 v[146:147], s[28:29], 0, v[140:141]
	s_add_i32 m0, s19, 0xe000
	s_nop 0
	global_load_lds_dwordx4 v[146:147], off
	s_waitcnt vmcnt(8)
	s_waitcnt lgkmcnt(0)
	s_barrier
	s_setprio 1
	s_waitcnt lgkmcnt(0)
	v_mfma_f32_16x16x32_bf16 v[126:129], v[154:157], v[186:189], v[126:129]
	v_mfma_f32_16x16x32_bf16 v[122:125], v[162:165], v[186:189], v[122:125]
	v_mfma_f32_16x16x32_bf16 v[110:113], v[154:157], v[194:197], v[110:113]
	v_mfma_f32_16x16x32_bf16 v[106:109], v[162:165], v[194:197], v[106:109]
	v_mfma_f32_16x16x32_bf16 v[94:97], v[154:157], v[206:209], v[94:97]
	v_mfma_f32_16x16x32_bf16 v[90:93], v[162:165], v[206:209], v[90:93]
	v_mfma_f32_16x16x32_bf16 v[78:81], v[154:157], v[214:217], v[78:81]
	v_mfma_f32_16x16x32_bf16 v[74:77], v[162:165], v[214:217], v[74:77]
	v_mfma_f32_16x16x32_bf16 v[126:129], v[158:161], v[190:193], v[126:129]
	v_mfma_f32_16x16x32_bf16 v[122:125], v[166:169], v[190:193], v[122:125]
	v_mfma_f32_16x16x32_bf16 v[110:113], v[158:161], v[198:201], v[110:113]
	v_mfma_f32_16x16x32_bf16 v[106:109], v[166:169], v[198:201], v[106:109]
	v_mfma_f32_16x16x32_bf16 v[94:97], v[158:161], v[210:213], v[94:97]
	v_mfma_f32_16x16x32_bf16 v[90:93], v[166:169], v[210:213], v[90:93]
	v_mfma_f32_16x16x32_bf16 v[78:81], v[158:161], v[218:221], v[78:81]
	v_mfma_f32_16x16x32_bf16 v[74:77], v[166:169], v[218:221], v[74:77]
	s_setprio 0
	s_setprio 1
	v_mfma_f32_16x16x32_bf16 v[118:121], v[170:173], v[186:189], v[118:121]
	v_mfma_f32_16x16x32_bf16 v[114:117], v[178:181], v[186:189], v[114:117]
	v_mfma_f32_16x16x32_bf16 v[102:105], v[170:173], v[194:197], v[102:105]
	v_mfma_f32_16x16x32_bf16 v[98:101], v[178:181], v[194:197], v[98:101]
	v_mfma_f32_16x16x32_bf16 v[86:89], v[170:173], v[206:209], v[86:89]
	v_mfma_f32_16x16x32_bf16 v[82:85], v[178:181], v[206:209], v[82:85]
	v_mfma_f32_16x16x32_bf16 v[70:73], v[170:173], v[214:217], v[70:73]
	v_mfma_f32_16x16x32_bf16 v[66:69], v[178:181], v[214:217], v[66:69]
	v_mfma_f32_16x16x32_bf16 v[118:121], v[174:177], v[190:193], v[118:121]
	v_mfma_f32_16x16x32_bf16 v[114:117], v[182:185], v[190:193], v[114:117]
	v_mfma_f32_16x16x32_bf16 v[102:105], v[174:177], v[198:201], v[102:105]
	v_mfma_f32_16x16x32_bf16 v[98:101], v[182:185], v[198:201], v[98:101]
	v_mfma_f32_16x16x32_bf16 v[86:89], v[174:177], v[210:213], v[86:89]
	v_mfma_f32_16x16x32_bf16 v[82:85], v[182:185], v[210:213], v[82:85]
	v_mfma_f32_16x16x32_bf16 v[70:73], v[174:177], v[218:221], v[70:73]
	v_mfma_f32_16x16x32_bf16 v[66:69], v[182:185], v[218:221], v[66:69]
	s_setprio 0
	s_barrier
	s_add_i32 s63, s45, s12
	v_lshl_add_u64 v[146:147], s[30:31], 0, v[134:135]
	s_mov_b32 m0, s63
	ds_read_b128 v[186:189], v152 offset:16384
	ds_read_b128 v[190:193], v152 offset:17408
	ds_read_b128 v[194:197], v152 offset:18432
	ds_read_b128 v[198:201], v152 offset:19456
	ds_read_b128 v[206:209], v152 offset:20480
	ds_read_b128 v[210:213], v152 offset:21504
	ds_read_b128 v[214:217], v152 offset:22528
	ds_read_b128 v[218:221], v152 offset:23552
	global_load_lds_dwordx4 v[146:147], off
	s_add_i32 m0, s63, 0x2000
	s_add_u32 s64, s30, 0x40000
	v_lshl_add_u64 v[202:203], s[30:31], 0, v[130:131]
	s_addc_u32 s65, s31, 0
	s_add_i32 s63, s46, s12
	global_load_lds_dwordx4 v[202:203], off
	v_lshl_add_u64 v[222:223], s[64:65], 0, v[134:135]
	s_mov_b32 m0, s63
	v_lshl_add_u64 v[224:225], s[36:37], 0, v[132:133]
	global_load_lds_dwordx4 v[222:223], off
	v_lshl_add_u64 v[222:223], s[64:65], 0, v[130:131]
	s_add_i32 m0, s63, 0x2000
	s_nop 0
	global_load_lds_dwordx4 v[222:223], off
	v_lshl_add_u64 v[222:223], s[36:37], 0, v[136:137]
	s_mov_b32 m0, s19
	s_nop 0
	global_load_lds_dwordx4 v[222:223], off
	s_mov_b32 m0, s33
	s_nop 0
	global_load_lds_dwordx4 v[224:225], off
	s_waitcnt vmcnt(8)
	s_waitcnt lgkmcnt(0)
	s_barrier
	s_setprio 1
	s_waitcnt lgkmcnt(0)
	v_mfma_f32_16x16x32_bf16 v[62:65], v[154:157], v[186:189], v[62:65]
	v_mfma_f32_16x16x32_bf16 v[58:61], v[162:165], v[186:189], v[58:61]
	v_mfma_f32_16x16x32_bf16 v[46:49], v[154:157], v[194:197], v[46:49]
	v_mfma_f32_16x16x32_bf16 v[42:45], v[162:165], v[194:197], v[42:45]
	v_mfma_f32_16x16x32_bf16 v[30:33], v[154:157], v[206:209], v[30:33]
	v_mfma_f32_16x16x32_bf16 v[26:29], v[162:165], v[206:209], v[26:29]
	v_mfma_f32_16x16x32_bf16 v[14:17], v[154:157], v[214:217], v[14:17]
	v_mfma_f32_16x16x32_bf16 v[10:13], v[162:165], v[214:217], v[10:13]
	v_mfma_f32_16x16x32_bf16 v[62:65], v[158:161], v[190:193], v[62:65]
	v_mfma_f32_16x16x32_bf16 v[58:61], v[166:169], v[190:193], v[58:61]
	v_mfma_f32_16x16x32_bf16 v[46:49], v[158:161], v[198:201], v[46:49]
	v_mfma_f32_16x16x32_bf16 v[42:45], v[166:169], v[198:201], v[42:45]
	v_mfma_f32_16x16x32_bf16 v[30:33], v[158:161], v[210:213], v[30:33]
	v_mfma_f32_16x16x32_bf16 v[26:29], v[166:169], v[210:213], v[26:29]
	v_mfma_f32_16x16x32_bf16 v[14:17], v[158:161], v[218:221], v[14:17]
	v_mfma_f32_16x16x32_bf16 v[10:13], v[166:169], v[218:221], v[10:13]
	s_setprio 0
	s_setprio 1
	v_mfma_f32_16x16x32_bf16 v[54:57], v[170:173], v[186:189], v[54:57]
	v_mfma_f32_16x16x32_bf16 v[50:53], v[178:181], v[186:189], v[50:53]
	v_mfma_f32_16x16x32_bf16 v[38:41], v[170:173], v[194:197], v[38:41]
	v_mfma_f32_16x16x32_bf16 v[34:37], v[178:181], v[194:197], v[34:37]
	v_mfma_f32_16x16x32_bf16 v[22:25], v[170:173], v[206:209], v[22:25]
	v_mfma_f32_16x16x32_bf16 v[18:21], v[178:181], v[206:209], v[18:21]
	v_mfma_f32_16x16x32_bf16 v[6:9], v[170:173], v[214:217], v[6:9]
	v_mfma_f32_16x16x32_bf16 v[2:5], v[178:181], v[214:217], v[2:5]
	v_mfma_f32_16x16x32_bf16 v[54:57], v[174:177], v[190:193], v[54:57]
	v_mfma_f32_16x16x32_bf16 v[50:53], v[182:185], v[190:193], v[50:53]
	v_mfma_f32_16x16x32_bf16 v[38:41], v[174:177], v[198:201], v[38:41]
	v_mfma_f32_16x16x32_bf16 v[34:37], v[182:185], v[198:201], v[34:37]
	v_mfma_f32_16x16x32_bf16 v[22:25], v[174:177], v[210:213], v[22:25]
	v_mfma_f32_16x16x32_bf16 v[18:21], v[182:185], v[210:213], v[18:21]
	v_mfma_f32_16x16x32_bf16 v[6:9], v[174:177], v[218:221], v[6:9]
	v_mfma_f32_16x16x32_bf16 v[2:5], v[182:185], v[218:221], v[2:5]
	s_setprio 0
	s_barrier
	s_add_i32 s63, 0, 0x18000
	v_add_u32_e32 v153, s63, v149
	s_add_i32 s64, 0, 0x1c000
	ds_read_b128 v[154:157], v153
	ds_read_b128 v[158:161], v153 offset:1024
	ds_read_b128 v[162:165], v153 offset:2048
	ds_read_b128 v[166:169], v153 offset:3072
	v_add_u32_e32 v153, s64, v149
	ds_read_b128 v[170:173], v153
	ds_read_b128 v[174:177], v153 offset:1024
	ds_read_b128 v[178:181], v153 offset:2048
	ds_read_b128 v[182:185], v153 offset:3072
	s_add_u32 s36, s36, 0x40000
	s_addc_u32 s37, s37, 0
	s_mov_b32 m0, s35
	v_lshl_add_u64 v[226:227], s[36:37], 0, v[136:137]
	ds_read_b128 v[186:189], v152 offset:32768
	ds_read_b128 v[190:193], v152 offset:33792
	ds_read_b128 v[194:197], v152 offset:34816
	ds_read_b128 v[198:201], v152 offset:35840
	ds_read_b128 v[206:209], v152 offset:36864
	ds_read_b128 v[210:213], v152 offset:37888
	ds_read_b128 v[214:217], v152 offset:38912
	ds_read_b128 v[218:221], v152 offset:39936
	global_load_lds_dwordx4 v[226:227], off
	v_lshl_add_u64 v[226:227], s[36:37], 0, v[132:133]
	s_mov_b32 m0, s38
	s_nop 0
	global_load_lds_dwordx4 v[226:227], off
	s_waitcnt vmcnt(8)
	s_waitcnt lgkmcnt(0)
	s_barrier
	s_setprio 1
	s_waitcnt lgkmcnt(0)
	v_mfma_f32_16x16x32_bf16 v[126:129], v[154:157], v[186:189], v[126:129]
	v_mfma_f32_16x16x32_bf16 v[122:125], v[162:165], v[186:189], v[122:125]
	v_mfma_f32_16x16x32_bf16 v[110:113], v[154:157], v[194:197], v[110:113]
	v_mfma_f32_16x16x32_bf16 v[106:109], v[162:165], v[194:197], v[106:109]
	v_mfma_f32_16x16x32_bf16 v[94:97], v[154:157], v[206:209], v[94:97]
	v_mfma_f32_16x16x32_bf16 v[90:93], v[162:165], v[206:209], v[90:93]
	v_mfma_f32_16x16x32_bf16 v[78:81], v[154:157], v[214:217], v[78:81]
	v_mfma_f32_16x16x32_bf16 v[74:77], v[162:165], v[214:217], v[74:77]
	v_mfma_f32_16x16x32_bf16 v[126:129], v[158:161], v[190:193], v[126:129]
	v_mfma_f32_16x16x32_bf16 v[122:125], v[166:169], v[190:193], v[122:125]
	v_mfma_f32_16x16x32_bf16 v[110:113], v[158:161], v[198:201], v[110:113]
	v_mfma_f32_16x16x32_bf16 v[106:109], v[166:169], v[198:201], v[106:109]
	v_mfma_f32_16x16x32_bf16 v[94:97], v[158:161], v[210:213], v[94:97]
	v_mfma_f32_16x16x32_bf16 v[90:93], v[166:169], v[210:213], v[90:93]
	v_mfma_f32_16x16x32_bf16 v[78:81], v[158:161], v[218:221], v[78:81]
	v_mfma_f32_16x16x32_bf16 v[74:77], v[166:169], v[218:221], v[74:77]
	s_setprio 0
	s_setprio 1
	v_mfma_f32_16x16x32_bf16 v[118:121], v[170:173], v[186:189], v[118:121]
	v_mfma_f32_16x16x32_bf16 v[114:117], v[178:181], v[186:189], v[114:117]
	v_mfma_f32_16x16x32_bf16 v[102:105], v[170:173], v[194:197], v[102:105]
	v_mfma_f32_16x16x32_bf16 v[98:101], v[178:181], v[194:197], v[98:101]
	v_mfma_f32_16x16x32_bf16 v[86:89], v[170:173], v[206:209], v[86:89]
	v_mfma_f32_16x16x32_bf16 v[82:85], v[178:181], v[206:209], v[82:85]
	v_mfma_f32_16x16x32_bf16 v[70:73], v[170:173], v[214:217], v[70:73]
	v_mfma_f32_16x16x32_bf16 v[66:69], v[178:181], v[214:217], v[66:69]
	v_mfma_f32_16x16x32_bf16 v[118:121], v[174:177], v[190:193], v[118:121]
	v_mfma_f32_16x16x32_bf16 v[114:117], v[182:185], v[190:193], v[114:117]
	v_mfma_f32_16x16x32_bf16 v[102:105], v[174:177], v[198:201], v[102:105]
	v_mfma_f32_16x16x32_bf16 v[98:101], v[182:185], v[198:201], v[98:101]
	v_mfma_f32_16x16x32_bf16 v[86:89], v[174:177], v[210:213], v[86:89]
	v_mfma_f32_16x16x32_bf16 v[82:85], v[182:185], v[210:213], v[82:85]
	v_mfma_f32_16x16x32_bf16 v[70:73], v[174:177], v[218:221], v[70:73]
	v_mfma_f32_16x16x32_bf16 v[66:69], v[182:185], v[218:221], v[66:69]
	s_setprio 0
	s_barrier
	s_add_i32 s36, s63, s12
	v_lshl_add_u64 v[146:147], v[146:147], 0, s[8:9]
	s_mov_b32 m0, s36
	ds_read_b128 v[186:189], v152 offset:49152
	ds_read_b128 v[190:193], v152 offset:50176
	ds_read_b128 v[194:197], v152 offset:51200
	ds_read_b128 v[198:201], v152 offset:52224
	ds_read_b128 v[206:209], v152 offset:53248
	ds_read_b128 v[210:213], v152 offset:54272
	ds_read_b128 v[214:217], v152 offset:55296
	ds_read_b128 v[218:221], v152 offset:56320
	global_load_lds_dwordx4 v[146:147], off
	s_add_i32 m0, s36, 0x2000
	s_add_u32 s30, s30, 0x40080
	v_lshl_add_u64 v[146:147], v[202:203], 0, s[8:9]
	s_addc_u32 s31, s31, 0
	s_add_i32 s36, s64, s12
	global_load_lds_dwordx4 v[146:147], off
	v_lshl_add_u64 v[146:147], s[30:31], 0, v[134:135]
	s_mov_b32 m0, s36
	s_nop 0
	global_load_lds_dwordx4 v[146:147], off
	v_lshl_add_u64 v[146:147], s[30:31], 0, v[130:131]
	s_add_i32 m0, s36, 0x2000
	s_nop 0
	global_load_lds_dwordx4 v[146:147], off
	v_lshl_add_u64 v[146:147], v[222:223], 0, s[8:9]
	s_mov_b32 m0, s42
	s_nop 0
	global_load_lds_dwordx4 v[146:147], off
	v_lshl_add_u64 v[146:147], v[224:225], 0, s[8:9]
	s_mov_b32 m0, s43
	s_nop 0
	global_load_lds_dwordx4 v[146:147], off
	s_waitcnt vmcnt(8)
	s_waitcnt lgkmcnt(0)
	s_barrier
	s_setprio 1
	s_waitcnt lgkmcnt(0)
	v_mfma_f32_16x16x32_bf16 v[62:65], v[154:157], v[186:189], v[62:65]
	v_mfma_f32_16x16x32_bf16 v[58:61], v[162:165], v[186:189], v[58:61]
	v_mfma_f32_16x16x32_bf16 v[46:49], v[154:157], v[194:197], v[46:49]
	v_mfma_f32_16x16x32_bf16 v[42:45], v[162:165], v[194:197], v[42:45]
	v_mfma_f32_16x16x32_bf16 v[30:33], v[154:157], v[206:209], v[30:33]
	v_mfma_f32_16x16x32_bf16 v[26:29], v[162:165], v[206:209], v[26:29]
	v_mfma_f32_16x16x32_bf16 v[14:17], v[154:157], v[214:217], v[14:17]
	v_mfma_f32_16x16x32_bf16 v[10:13], v[162:165], v[214:217], v[10:13]
	v_mfma_f32_16x16x32_bf16 v[62:65], v[158:161], v[190:193], v[62:65]
	v_mfma_f32_16x16x32_bf16 v[58:61], v[166:169], v[190:193], v[58:61]
	v_mfma_f32_16x16x32_bf16 v[46:49], v[158:161], v[198:201], v[46:49]
	v_mfma_f32_16x16x32_bf16 v[42:45], v[166:169], v[198:201], v[42:45]
	v_mfma_f32_16x16x32_bf16 v[30:33], v[158:161], v[210:213], v[30:33]
	v_mfma_f32_16x16x32_bf16 v[26:29], v[166:169], v[210:213], v[26:29]
	v_mfma_f32_16x16x32_bf16 v[14:17], v[158:161], v[218:221], v[14:17]
	v_mfma_f32_16x16x32_bf16 v[10:13], v[166:169], v[218:221], v[10:13]
	s_setprio 0
	s_setprio 1
	v_mfma_f32_16x16x32_bf16 v[54:57], v[170:173], v[186:189], v[54:57]
	v_mfma_f32_16x16x32_bf16 v[50:53], v[178:181], v[186:189], v[50:53]
	v_mfma_f32_16x16x32_bf16 v[38:41], v[170:173], v[194:197], v[38:41]
	v_mfma_f32_16x16x32_bf16 v[34:37], v[178:181], v[194:197], v[34:37]
	v_mfma_f32_16x16x32_bf16 v[22:25], v[170:173], v[206:209], v[22:25]
	v_mfma_f32_16x16x32_bf16 v[18:21], v[178:181], v[206:209], v[18:21]
	v_mfma_f32_16x16x32_bf16 v[6:9], v[170:173], v[214:217], v[6:9]
	v_mfma_f32_16x16x32_bf16 v[2:5], v[178:181], v[214:217], v[2:5]
	v_mfma_f32_16x16x32_bf16 v[54:57], v[174:177], v[190:193], v[54:57]
	v_mfma_f32_16x16x32_bf16 v[50:53], v[182:185], v[190:193], v[50:53]
	v_mfma_f32_16x16x32_bf16 v[38:41], v[174:177], v[198:201], v[38:41]
	v_mfma_f32_16x16x32_bf16 v[34:37], v[182:185], v[198:201], v[34:37]
	v_mfma_f32_16x16x32_bf16 v[22:25], v[174:177], v[210:213], v[22:25]
	v_mfma_f32_16x16x32_bf16 v[18:21], v[182:185], v[210:213], v[18:21]
	v_mfma_f32_16x16x32_bf16 v[6:9], v[174:177], v[218:221], v[6:9]
	v_mfma_f32_16x16x32_bf16 v[2:5], v[182:185], v[218:221], v[2:5]
	s_setprio 0
	s_barrier
	s_add_i32 s62, s62, 2
	s_add_u32 s28, s28, 0x100
	s_addc_u32 s29, s29, 0
	s_add_u32 s50, s50, 0x100
	s_addc_u32 s51, s51, 0
	s_cmp_gt_u32 s62, 13
	s_cbranch_scc0 .LBB0_1619
	s_and_b64 vcc, exec, s[10:11]
	s_cbranch_vccz .LBB0_1622
	s_barrier

.LBB0_1626:
	s_cmp_gt_i32 s59, 17
	s_cselect_b64 s[4:5], -1, 0
	s_and_b64 s[0:1], s[0:1], s[4:5]
	s_andn2_b64 vcc, exec, s[0:1]
	s_cbranch_vccnz .LBB0_1680
	s_waitcnt vmcnt(0) lgkmcnt(0)
	s_barrier
	s_mov_b64 s[0:1], exec
	v_readlane_b32 s2, v249, 5
	v_readlane_b32 s3, v249, 6
	v_readlane_b32 s8, v249, 4
	s_and_b64 s[2:3], s[0:1], s[2:3]
	s_mov_b64 exec, s[2:3]
	s_cbranch_execz .Lgb_13_done
	v_mov_b32_e32 v1, 0x27e00
	ds_read2_b32 v[2:3], v1 offset1:1
	s_lshl_b32 s8, s8, 8
	s_add_u32 s6, s56, s8
	s_addc_u32 s7, s57, 0
	v_mov_b32_e32 v4, 0x1000
	v_mov_b32_e32 v5, 1
	global_atomic_add v6, v4, v5, s[6:7] offset:1024 sc0
	buffer_inv sc1
	s_waitcnt lgkmcnt(0)
	v_mul_lo_u32 v7, v2, 14
	s_waitcnt vmcnt(1)
	v_add_u32_e32 v6, 1, v6
	v_cmp_eq_u32_e32 vcc, v6, v7
	s_cbranch_vccz .Lgb_13_wait
	buffer_wbl2 sc1
	s_waitcnt vmcnt(0)
	v_mov_b32_e32 v4, 0x3000
	global_atomic_add v8, v4, v5, s[56:57] offset:1024 sc0
	v_mul_lo_u32 v7, v3, 14
	s_waitcnt vmcnt(0)
	v_add_u32_e32 v8, 1, v8
	v_cmp_eq_u32_e32 vcc, v8, v7
	s_cbranch_vccz .Lgb_13_wait
	v_mov_b32_e32 v9, 0x2400
	global_atomic_add v9, v5, s[56:57] offset:0
	global_atomic_add v9, v5, s[56:57] offset:256
	global_atomic_add v9, v5, s[56:57] offset:512
	global_atomic_add v9, v5, s[56:57] offset:768
	global_atomic_add v9, v5, s[56:57] offset:1024
	global_atomic_add v9, v5, s[56:57] offset:1280
	global_atomic_add v9, v5, s[56:57] offset:1536
	global_atomic_add v9, v5, s[56:57] offset:1792
	global_atomic_add v9, v5, s[56:57] offset:2048
	global_atomic_add v9, v5, s[56:57] offset:2304
	global_atomic_add v9, v5, s[56:57] offset:2560
	global_atomic_add v9, v5, s[56:57] offset:2816
	global_atomic_add v9, v5, s[56:57] offset:3072
	global_atomic_add v9, v5, s[56:57] offset:3328
	global_atomic_add v9, v5, s[56:57] offset:3584
	global_atomic_add v9, v5, s[56:57] offset:3840
	s_waitcnt vmcnt(0)
	s_branch .Lgb_13_done

.Lgb_13_spin:
	global_load_dword v8, v9, s[6:7] offset:1024 sc1
	s_waitcnt vmcnt(0)
	v_cmp_ne_u32_e32 vcc, 13, v8
	s_cbranch_vccnz .Lgb_13_done
	s_sleep 1
	s_add_u32 s8, s8, 1
	s_cmp_lt_u32 s8, 0x40000
	s_cbranch_scc1 .Lgb_13_spin

.LBB0_1708:
	ds_read_b128 v[130:133], v168
	ds_read_b128 v[134:137], v168 offset:1024
	ds_read_b128 v[138:141], v168 offset:2048
	ds_read_b128 v[142:145], v168 offset:3072
	ds_read_b128 v[162:165], v169
	ds_read_b128 v[172:175], v169 offset:1024
	ds_read_b128 v[176:179], v169 offset:2048
	ds_read_b128 v[180:183], v169 offset:3072
	s_add_i32 s93, s62, 2
	s_add_u32 s63, s50, 0xfff00080
	s_addc_u32 s64, s51, -1
	s_cmp_eq_u32 s69, s62
	s_cselect_b32 s62, s68, s91
	s_cselect_b32 s65, s34, s64
	s_cselect_b32 s64, s66, s63
	s_cselect_b32 s63, s67, s92
	v_lshl_add_u64 v[218:219], s[50:51], 0, v[156:157]
	s_add_i32 m0, s12, 0xc000
	ds_read_b128 v[184:187], v170
	ds_read_b128 v[188:191], v170 offset:1024
	ds_read_b128 v[192:195], v170 offset:2048
	ds_read_b128 v[196:199], v170 offset:3072
	ds_read_b128 v[200:203], v170 offset:4096
	ds_read_b128 v[206:209], v170 offset:5120
	ds_read_b128 v[210:213], v170 offset:6144
	ds_read_b128 v[214:217], v170 offset:7168
	global_load_lds_dwordx4 v[218:219], off
	v_lshl_add_u64 v[218:219], s[50:51], 0, v[158:159]
	s_add_i32 m0, s12, 0xe000
	s_nop 0
	global_load_lds_dwordx4 v[218:219], off
	s_waitcnt vmcnt(8)
	s_waitcnt lgkmcnt(0)
	s_barrier
	s_setprio 1
	s_waitcnt lgkmcnt(0)
	v_mfma_f32_16x16x32_bf16 v[126:129], v[130:133], v[184:187], v[126:129]
	v_mfma_f32_16x16x32_bf16 v[122:125], v[138:141], v[184:187], v[122:125]
	v_mfma_f32_16x16x32_bf16 v[110:113], v[130:133], v[192:195], v[110:113]
	v_mfma_f32_16x16x32_bf16 v[106:109], v[138:141], v[192:195], v[106:109]
	v_mfma_f32_16x16x32_bf16 v[98:101], v[130:133], v[200:203], v[98:101]
	v_mfma_f32_16x16x32_bf16 v[90:93], v[138:141], v[200:203], v[90:93]
	v_mfma_f32_16x16x32_bf16 v[82:85], v[130:133], v[210:213], v[82:85]
	v_mfma_f32_16x16x32_bf16 v[74:77], v[138:141], v[210:213], v[74:77]
	v_mfma_f32_16x16x32_bf16 v[126:129], v[134:137], v[188:191], v[126:129]
	v_mfma_f32_16x16x32_bf16 v[122:125], v[142:145], v[188:191], v[122:125]
	v_mfma_f32_16x16x32_bf16 v[110:113], v[134:137], v[196:199], v[110:113]
	v_mfma_f32_16x16x32_bf16 v[106:109], v[142:145], v[196:199], v[106:109]
	v_mfma_f32_16x16x32_bf16 v[98:101], v[134:137], v[206:209], v[98:101]
	v_mfma_f32_16x16x32_bf16 v[90:93], v[142:145], v[206:209], v[90:93]
	v_mfma_f32_16x16x32_bf16 v[82:85], v[134:137], v[214:217], v[82:85]
	v_mfma_f32_16x16x32_bf16 v[74:77], v[142:145], v[214:217], v[74:77]
	s_setprio 0
	s_setprio 1
	v_mfma_f32_16x16x32_bf16 v[118:121], v[162:165], v[184:187], v[118:121]
	v_mfma_f32_16x16x32_bf16 v[114:117], v[176:179], v[184:187], v[114:117]
	v_mfma_f32_16x16x32_bf16 v[102:105], v[162:165], v[192:195], v[102:105]
	v_mfma_f32_16x16x32_bf16 v[94:97], v[176:179], v[192:195], v[94:97]
	v_mfma_f32_16x16x32_bf16 v[86:89], v[162:165], v[200:203], v[86:89]
	v_mfma_f32_16x16x32_bf16 v[78:81], v[176:179], v[200:203], v[78:81]
	v_mfma_f32_16x16x32_bf16 v[70:73], v[162:165], v[210:213], v[70:73]
	v_mfma_f32_16x16x32_bf16 v[66:69], v[176:179], v[210:213], v[66:69]
	v_mfma_f32_16x16x32_bf16 v[118:121], v[172:175], v[188:191], v[118:121]
	v_mfma_f32_16x16x32_bf16 v[114:117], v[180:183], v[188:191], v[114:117]
	v_mfma_f32_16x16x32_bf16 v[102:105], v[172:175], v[196:199], v[102:105]
	v_mfma_f32_16x16x32_bf16 v[94:97], v[180:183], v[196:199], v[94:97]
	v_mfma_f32_16x16x32_bf16 v[86:89], v[172:175], v[206:209], v[86:89]
	v_mfma_f32_16x16x32_bf16 v[78:81], v[180:183], v[206:209], v[78:81]
	v_mfma_f32_16x16x32_bf16 v[70:73], v[172:175], v[214:217], v[70:73]
	v_mfma_f32_16x16x32_bf16 v[66:69], v[180:183], v[214:217], v[66:69]
	s_setprio 0
	s_barrier
	s_add_i32 s94, s31, s2
	v_lshl_add_u64 v[218:219], s[62:63], 0, v[148:149]
	s_mov_b32 m0, s94
	ds_read_b128 v[184:187], v170 offset:16384
	ds_read_b128 v[188:191], v170 offset:17408
	ds_read_b128 v[192:195], v170 offset:18432
	ds_read_b128 v[196:199], v170 offset:19456
	ds_read_b128 v[200:203], v170 offset:20480
	ds_read_b128 v[206:209], v170 offset:21504
	ds_read_b128 v[210:213], v170 offset:22528
	ds_read_b128 v[214:217], v170 offset:23552
	global_load_lds_dwordx4 v[218:219], off
	s_add_i32 m0, s94, 0x2000
	s_add_u32 s94, s62, 0x100000
	v_lshl_add_u64 v[220:221], s[62:63], 0, v[152:153]
	s_addc_u32 s95, s63, 0
	s_add_i32 s96, s82, s2
	global_load_lds_dwordx4 v[220:221], off
	v_lshl_add_u64 v[222:223], s[94:95], 0, v[148:149]
	s_mov_b32 m0, s96
	v_lshl_add_u64 v[224:225], s[64:65], 0, v[150:151]
	global_load_lds_dwordx4 v[222:223], off
	v_lshl_add_u64 v[222:223], s[94:95], 0, v[152:153]
	s_add_i32 m0, s96, 0x2000
	s_nop 0
	global_load_lds_dwordx4 v[222:223], off
	v_lshl_add_u64 v[222:223], s[64:65], 0, v[146:147]
	s_mov_b32 m0, s12
	s_nop 0
	global_load_lds_dwordx4 v[222:223], off
	s_mov_b32 m0, s13
	s_nop 0
	global_load_lds_dwordx4 v[224:225], off
	s_waitcnt vmcnt(8)
	s_waitcnt lgkmcnt(0)
	s_barrier
	s_setprio 1
	s_waitcnt lgkmcnt(0)
	v_mfma_f32_16x16x32_bf16 v[62:65], v[130:133], v[184:187], v[62:65]
	v_mfma_f32_16x16x32_bf16 v[58:61], v[138:141], v[184:187], v[58:61]
	v_mfma_f32_16x16x32_bf16 v[50:53], v[130:133], v[192:195], v[50:53]
	v_mfma_f32_16x16x32_bf16 v[42:45], v[138:141], v[192:195], v[42:45]
	v_mfma_f32_16x16x32_bf16 v[34:37], v[130:133], v[200:203], v[34:37]
	v_mfma_f32_16x16x32_bf16 v[26:29], v[138:141], v[200:203], v[26:29]
	v_mfma_f32_16x16x32_bf16 v[18:21], v[130:133], v[210:213], v[18:21]
	v_mfma_f32_16x16x32_bf16 v[10:13], v[138:141], v[210:213], v[10:13]
	v_mfma_f32_16x16x32_bf16 v[62:65], v[134:137], v[188:191], v[62:65]
	v_mfma_f32_16x16x32_bf16 v[58:61], v[142:145], v[188:191], v[58:61]
	v_mfma_f32_16x16x32_bf16 v[50:53], v[134:137], v[196:199], v[50:53]
	v_mfma_f32_16x16x32_bf16 v[42:45], v[142:145], v[196:199], v[42:45]
	v_mfma_f32_16x16x32_bf16 v[34:37], v[134:137], v[206:209], v[34:37]
	v_mfma_f32_16x16x32_bf16 v[26:29], v[142:145], v[206:209], v[26:29]
	v_mfma_f32_16x16x32_bf16 v[18:21], v[134:137], v[214:217], v[18:21]
	v_mfma_f32_16x16x32_bf16 v[10:13], v[142:145], v[214:217], v[10:13]
	s_setprio 0
	s_setprio 1
	v_mfma_f32_16x16x32_bf16 v[54:57], v[162:165], v[184:187], v[54:57]
	v_mfma_f32_16x16x32_bf16 v[46:49], v[176:179], v[184:187], v[46:49]
	v_mfma_f32_16x16x32_bf16 v[38:41], v[162:165], v[192:195], v[38:41]
	v_mfma_f32_16x16x32_bf16 v[30:33], v[176:179], v[192:195], v[30:33]
	v_mfma_f32_16x16x32_bf16 v[22:25], v[162:165], v[200:203], v[22:25]
	v_mfma_f32_16x16x32_bf16 v[14:17], v[176:179], v[200:203], v[14:17]
	v_mfma_f32_16x16x32_bf16 v[6:9], v[162:165], v[210:213], v[6:9]
	v_mfma_f32_16x16x32_bf16 v[2:5], v[176:179], v[210:213], v[2:5]
	v_mfma_f32_16x16x32_bf16 v[54:57], v[172:175], v[188:191], v[54:57]
	v_mfma_f32_16x16x32_bf16 v[46:49], v[180:183], v[188:191], v[46:49]
	v_mfma_f32_16x16x32_bf16 v[38:41], v[172:175], v[196:199], v[38:41]
	v_mfma_f32_16x16x32_bf16 v[30:33], v[180:183], v[196:199], v[30:33]
	v_mfma_f32_16x16x32_bf16 v[22:25], v[172:175], v[206:209], v[22:25]
	v_mfma_f32_16x16x32_bf16 v[14:17], v[180:183], v[206:209], v[14:17]
	v_mfma_f32_16x16x32_bf16 v[6:9], v[172:175], v[214:217], v[6:9]
	v_mfma_f32_16x16x32_bf16 v[2:5], v[180:183], v[214:217], v[2:5]
	s_setprio 0
	s_barrier
	s_add_i32 s94, 0, 0x18000
	s_add_i32 s95, 0, 0x1c000
	v_add_u32_e32 v142, s94, v167
	v_add_u32_e32 v154, s95, v167
	ds_read_b128 v[130:133], v142
	ds_read_b128 v[134:137], v142 offset:1024
	ds_read_b128 v[138:141], v142 offset:2048
	ds_read_b128 v[142:145], v142 offset:3072
	ds_read_b128 v[162:165], v154
	ds_read_b128 v[172:175], v154 offset:1024
	ds_read_b128 v[176:179], v154 offset:2048
	ds_read_b128 v[180:183], v154 offset:3072
	s_add_u32 s64, s64, 0x100000
	s_addc_u32 s65, s65, 0
	s_mov_b32 m0, s18
	v_lshl_add_u64 v[226:227], s[64:65], 0, v[146:147]
	ds_read_b128 v[184:187], v170 offset:32768
	ds_read_b128 v[188:191], v170 offset:33792
	ds_read_b128 v[192:195], v170 offset:34816
	ds_read_b128 v[196:199], v170 offset:35840
	ds_read_b128 v[200:203], v170 offset:36864
	ds_read_b128 v[206:209], v170 offset:37888
	ds_read_b128 v[210:213], v170 offset:38912
	ds_read_b128 v[214:217], v170 offset:39936
	global_load_lds_dwordx4 v[226:227], off
	v_lshl_add_u64 v[226:227], s[64:65], 0, v[150:151]
	s_mov_b32 m0, s19
	s_nop 0
	global_load_lds_dwordx4 v[226:227], off
	s_waitcnt vmcnt(8)
	s_waitcnt lgkmcnt(0)
	s_barrier
	s_setprio 1
	s_waitcnt lgkmcnt(0)
	v_mfma_f32_16x16x32_bf16 v[126:129], v[130:133], v[184:187], v[126:129]
	v_mfma_f32_16x16x32_bf16 v[122:125], v[138:141], v[184:187], v[122:125]
	v_mfma_f32_16x16x32_bf16 v[110:113], v[130:133], v[192:195], v[110:113]
	v_mfma_f32_16x16x32_bf16 v[106:109], v[138:141], v[192:195], v[106:109]
	v_mfma_f32_16x16x32_bf16 v[98:101], v[130:133], v[200:203], v[98:101]
	v_mfma_f32_16x16x32_bf16 v[90:93], v[138:141], v[200:203], v[90:93]
	v_mfma_f32_16x16x32_bf16 v[82:85], v[130:133], v[210:213], v[82:85]
	v_mfma_f32_16x16x32_bf16 v[74:77], v[138:141], v[210:213], v[74:77]
	v_mfma_f32_16x16x32_bf16 v[126:129], v[134:137], v[188:191], v[126:129]
	v_mfma_f32_16x16x32_bf16 v[122:125], v[142:145], v[188:191], v[122:125]
	v_mfma_f32_16x16x32_bf16 v[110:113], v[134:137], v[196:199], v[110:113]
	v_mfma_f32_16x16x32_bf16 v[106:109], v[142:145], v[196:199], v[106:109]
	v_mfma_f32_16x16x32_bf16 v[98:101], v[134:137], v[206:209], v[98:101]
	v_mfma_f32_16x16x32_bf16 v[90:93], v[142:145], v[206:209], v[90:93]
	v_mfma_f32_16x16x32_bf16 v[82:85], v[134:137], v[214:217], v[82:85]
	v_mfma_f32_16x16x32_bf16 v[74:77], v[142:145], v[214:217], v[74:77]
	s_setprio 0
	s_setprio 1
	v_mfma_f32_16x16x32_bf16 v[118:121], v[162:165], v[184:187], v[118:121]
	v_mfma_f32_16x16x32_bf16 v[114:117], v[176:179], v[184:187], v[114:117]
	v_mfma_f32_16x16x32_bf16 v[102:105], v[162:165], v[192:195], v[102:105]
	v_mfma_f32_16x16x32_bf16 v[94:97], v[176:179], v[192:195], v[94:97]
	v_mfma_f32_16x16x32_bf16 v[86:89], v[162:165], v[200:203], v[86:89]
	v_mfma_f32_16x16x32_bf16 v[78:81], v[176:179], v[200:203], v[78:81]
	v_mfma_f32_16x16x32_bf16 v[70:73], v[162:165], v[210:213], v[70:73]
	v_mfma_f32_16x16x32_bf16 v[66:69], v[176:179], v[210:213], v[66:69]
	v_mfma_f32_16x16x32_bf16 v[118:121], v[172:175], v[188:191], v[118:121]
	v_mfma_f32_16x16x32_bf16 v[114:117], v[180:183], v[188:191], v[114:117]
	v_mfma_f32_16x16x32_bf16 v[102:105], v[172:175], v[196:199], v[102:105]
	v_mfma_f32_16x16x32_bf16 v[94:97], v[180:183], v[196:199], v[94:97]
	v_mfma_f32_16x16x32_bf16 v[86:89], v[172:175], v[206:209], v[86:89]
	v_mfma_f32_16x16x32_bf16 v[78:81], v[180:183], v[206:209], v[78:81]
	v_mfma_f32_16x16x32_bf16 v[70:73], v[172:175], v[214:217], v[70:73]
	v_mfma_f32_16x16x32_bf16 v[66:69], v[180:183], v[214:217], v[66:69]
	s_setprio 0
	s_barrier
	s_add_i32 s64, s94, s2
	v_lshl_add_u64 v[218:219], v[218:219], 0, s[16:17]
	s_mov_b32 m0, s64
	ds_read_b128 v[184:187], v170 offset:49152
	ds_read_b128 v[188:191], v170 offset:50176
	ds_read_b128 v[192:195], v170 offset:51200
	ds_read_b128 v[196:199], v170 offset:52224
	ds_read_b128 v[200:203], v170 offset:53248
	ds_read_b128 v[206:209], v170 offset:54272
	ds_read_b128 v[210:213], v170 offset:55296
	ds_read_b128 v[214:217], v170 offset:56320
	global_load_lds_dwordx4 v[218:219], off
	s_add_i32 m0, s64, 0x2000
	s_add_u32 s62, s62, 0x100080
	v_lshl_add_u64 v[218:219], v[220:221], 0, s[16:17]
	s_addc_u32 s63, s63, 0
	s_add_i32 s64, s95, s2
	global_load_lds_dwordx4 v[218:219], off
	v_lshl_add_u64 v[218:219], s[62:63], 0, v[148:149]
	s_mov_b32 m0, s64
	s_nop 0
	global_load_lds_dwordx4 v[218:219], off
	v_lshl_add_u64 v[218:219], s[62:63], 0, v[152:153]
	s_add_i32 m0, s64, 0x2000
	s_nop 0
	global_load_lds_dwordx4 v[218:219], off
	v_lshl_add_u64 v[218:219], v[222:223], 0, s[16:17]
	s_mov_b32 m0, s74
	s_nop 0
	global_load_lds_dwordx4 v[218:219], off
	v_lshl_add_u64 v[218:219], v[224:225], 0, s[16:17]
	s_mov_b32 m0, s75
	s_nop 0
	global_load_lds_dwordx4 v[218:219], off
	s_waitcnt vmcnt(8)
	s_waitcnt lgkmcnt(0)
	s_barrier
	s_setprio 1
	s_waitcnt lgkmcnt(0)
	v_mfma_f32_16x16x32_bf16 v[62:65], v[130:133], v[184:187], v[62:65]
	v_mfma_f32_16x16x32_bf16 v[58:61], v[138:141], v[184:187], v[58:61]
	v_mfma_f32_16x16x32_bf16 v[50:53], v[130:133], v[192:195], v[50:53]
	v_mfma_f32_16x16x32_bf16 v[42:45], v[138:141], v[192:195], v[42:45]
	v_mfma_f32_16x16x32_bf16 v[34:37], v[130:133], v[200:203], v[34:37]
	v_mfma_f32_16x16x32_bf16 v[26:29], v[138:141], v[200:203], v[26:29]
	v_mfma_f32_16x16x32_bf16 v[18:21], v[130:133], v[210:213], v[18:21]
	v_mfma_f32_16x16x32_bf16 v[10:13], v[138:141], v[210:213], v[10:13]
	v_mfma_f32_16x16x32_bf16 v[62:65], v[134:137], v[188:191], v[62:65]
	v_mfma_f32_16x16x32_bf16 v[58:61], v[142:145], v[188:191], v[58:61]
	v_mfma_f32_16x16x32_bf16 v[50:53], v[134:137], v[196:199], v[50:53]
	v_mfma_f32_16x16x32_bf16 v[42:45], v[142:145], v[196:199], v[42:45]
	v_mfma_f32_16x16x32_bf16 v[34:37], v[134:137], v[206:209], v[34:37]
	v_mfma_f32_16x16x32_bf16 v[26:29], v[142:145], v[206:209], v[26:29]
	v_mfma_f32_16x16x32_bf16 v[18:21], v[134:137], v[214:217], v[18:21]
	v_mfma_f32_16x16x32_bf16 v[10:13], v[142:145], v[214:217], v[10:13]
	s_setprio 0
	s_setprio 1
	v_mfma_f32_16x16x32_bf16 v[54:57], v[162:165], v[184:187], v[54:57]
	v_mfma_f32_16x16x32_bf16 v[46:49], v[176:179], v[184:187], v[46:49]
	v_mfma_f32_16x16x32_bf16 v[38:41], v[162:165], v[192:195], v[38:41]
	v_mfma_f32_16x16x32_bf16 v[30:33], v[176:179], v[192:195], v[30:33]
	v_mfma_f32_16x16x32_bf16 v[22:25], v[162:165], v[200:203], v[22:25]
	v_mfma_f32_16x16x32_bf16 v[14:17], v[176:179], v[200:203], v[14:17]
	v_mfma_f32_16x16x32_bf16 v[6:9], v[162:165], v[210:213], v[6:9]
	v_mfma_f32_16x16x32_bf16 v[2:5], v[176:179], v[210:213], v[2:5]
	v_mfma_f32_16x16x32_bf16 v[54:57], v[172:175], v[188:191], v[54:57]
	v_mfma_f32_16x16x32_bf16 v[46:49], v[180:183], v[188:191], v[46:49]
	v_mfma_f32_16x16x32_bf16 v[38:41], v[172:175], v[196:199], v[38:41]
	v_mfma_f32_16x16x32_bf16 v[30:33], v[180:183], v[196:199], v[30:33]
	v_mfma_f32_16x16x32_bf16 v[22:25], v[172:175], v[206:209], v[22:25]
	v_mfma_f32_16x16x32_bf16 v[14:17], v[180:183], v[206:209], v[14:17]
	v_mfma_f32_16x16x32_bf16 v[6:9], v[172:175], v[214:217], v[6:9]
	v_mfma_f32_16x16x32_bf16 v[2:5], v[180:183], v[214:217], v[2:5]
	s_setprio 0
	s_barrier
	s_add_u32 s50, s50, 0x100
	s_addc_u32 s51, s51, 0
	s_add_u32 s91, s91, 0x100
	s_addc_u32 s92, s92, 0
	s_cmp_ge_i32 s93, s7
	s_mov_b32 s62, s93
	s_cbranch_scc0 .LBB0_1708
	s_and_b64 vcc, exec, s[20:21]
	s_cbranch_vccz .LBB0_1711
	s_barrier
